# v52 with the softmax-phase priority raise moved up into the middle of the V-fragment LDS reads
# speedup vs baseline: 1.0032x; 1.0032x over previous
; DI void expsum(f32x16& p, float& l_reg, bf16x8& pa0, bf16x8& pa1) {
; #pragma unroll
;     for (int r = 0; r < 16; ++r) p[r] = __builtin_amdgcn_exp2f(p[r]);
;     float ps = 0.f;
; #pragma unroll
;     for (int r = 0; r < 16; ++r) ps += p[r];
;     l_reg += ps; asm volatile("" : "+v"(l_reg));
;     ...
;     ATT_PK4(p, 0, pa0); ATT_PK4(p, 8, pa1);
;     ...
; }
.LBB0_1922:
	s_add_i32 s3, s0, -1
	s_add_i32 s2, s22, 0xffffa000
	s_and_b32 s2, s2, 0x6000
	v_add_u32_e32 v121, s2, v114
	v_add_u32_e32 v122, v121, v115
	v_add_u32_e32 v126, v121, v116
	ds_read_b128 v[122:125], v122 offset:4096
	ds_read_b128 v[132:135], v126 offset:4096
	v_add_u32_e32 v126, v121, v117
	v_add_u32_e32 v121, v121, v118
	s_lshl_b32 s2, s1, 14
	ds_read_b128 v[136:139], v126 offset:4096
	ds_read_b128 v[140:143], v121 offset:4096
	v_add_u32_e32 v121, s2, v106
	ds_read_b64_tr_b16 v[144:145], v121 offset:0
	ds_read_b64_tr_b16 v[146:147], v121 offset:0x800
	ds_read_b64_tr_b16 v[148:149], v121 offset:0x1000
	ds_read_b64_tr_b16 v[150:151], v121 offset:0x1800
	ds_read_b64_tr_b16 v[152:153], v121 offset:0x200
	ds_read_b64_tr_b16 v[154:155], v121 offset:0xa00
	ds_read_b64_tr_b16 v[156:157], v121 offset:0x1200
	ds_read_b64_tr_b16 v[158:159], v121 offset:0x1a00
	s_setprio 2
	ds_read_b64_tr_b16 v[162:163], v121 offset:0x400
	ds_read_b64_tr_b16 v[164:165], v121 offset:0xc00
	ds_read_b64_tr_b16 v[166:167], v121 offset:0x1400
	ds_read_b64_tr_b16 v[168:169], v121 offset:0x1c00
	ds_read_b64_tr_b16 v[170:171], v121 offset:0x600
	ds_read_b64_tr_b16 v[172:173], v121 offset:0xe00
	ds_read_b64_tr_b16 v[174:175], v121 offset:0x1600
	ds_read_b64_tr_b16 v[176:177], v121 offset:0x1e00
	v_exp_f32_e32 v64, v64
	v_exp_f32_e32 v65, v65
	v_exp_f32_e32 v66, v66
	v_exp_f32_e32 v67, v67
	v_exp_f32_e32 v68, v68
	v_exp_f32_e32 v69, v69
	v_add_f32_e32 v126, v65, v64
	v_exp_f32_e32 v70, v70
	v_add_f32_e32 v126, v66, v126
	v_exp_f32_e32 v71, v71
	v_add_f32_e32 v126, v67, v126
	v_exp_f32_e32 v72, v72
	v_add_f32_e32 v126, v68, v126
	v_exp_f32_e32 v73, v73
	v_add_f32_e32 v126, v69, v126
	v_exp_f32_e32 v74, v74
	v_add_f32_e32 v126, v70, v126
	v_exp_f32_e32 v75, v75
	v_add_f32_e32 v126, v71, v126
	v_exp_f32_e32 v76, v76
	v_add_f32_e32 v126, v72, v126
	v_exp_f32_e32 v77, v77
	v_add_f32_e32 v126, v73, v126
	v_exp_f32_e32 v78, v78
	v_add_f32_e32 v126, v74, v126
	v_exp_f32_e32 v79, v79
	v_add_f32_e32 v126, v75, v126
	v_add_f32_e32 v126, v76, v126
	v_add_f32_e32 v126, v77, v126
	v_add_f32_e32 v126, v78, v126
	v_add_f32_e32 v126, v79, v126
	v_add_f32_e32 v120, v126, v120
	v_cvt_pk_bf16_f32 v64, v64, v65
	v_cvt_pk_bf16_f32 v65, v66, v67
	v_cvt_pk_bf16_f32 v66, v68, v69
	v_cvt_pk_bf16_f32 v67, v70, v71
	v_cvt_pk_bf16_f32 v68, v72, v73
	v_cvt_pk_bf16_f32 v69, v74, v75
	v_cvt_pk_bf16_f32 v70, v76, v77
	v_cvt_pk_bf16_f32 v71, v78, v79
	s_nop 0
	v_permlane32_swap_b32_e32 v64, v66
	v_permlane32_swap_b32_e32 v65, v67
	v_permlane32_swap_b32_e32 v68, v70
	v_permlane32_swap_b32_e32 v69, v71
	s_waitcnt lgkmcnt(0)
	s_setprio 1
	v_mfma_f32_32x32x16_bf16 v[0:15], v[64:67], v[144:147], v[0:15]
	s_cmp_lt_i32 s3, s55
	s_cselect_b64 vcc, -1, 0
	s_cmp_ge_i32 s3, s97
	s_cselect_b64 s[74:75], -1, 0
	s_or_b64 s[74:75], vcc, s[74:75]
	s_and_b64 vcc, exec, s[74:75]
	v_mfma_f32_32x32x16_bf16 v[48:63], v[64:67], v[152:155], v[48:63]
	v_mfma_f32_32x32x16_bf16 v[32:47], v[64:67], v[162:165], v[32:47]
	v_mfma_f32_32x32x16_bf16 v[16:31], v[64:67], v[170:173], v[16:31]
	v_mfma_f32_32x32x16_bf16 v[0:15], v[68:71], v[148:151], v[0:15]
	v_mfma_f32_32x32x16_bf16 v[48:63], v[68:71], v[156:159], v[48:63]
	v_mfma_f32_32x32x16_bf16 v[32:47], v[68:71], v[166:169], v[32:47]
	v_mfma_f32_32x32x16_bf16 v[16:31], v[68:71], v[174:177], v[16:31]
	v_mfma_f32_32x32x16_bf16 v[64:79], v[122:125], v[92:95], 0
	v_mfma_f32_32x32x16_bf16 v[64:79], v[132:135], v[88:91], v[64:79]
	v_mfma_f32_32x32x16_bf16 v[64:79], v[136:139], v[84:87], v[64:79]
	v_mfma_f32_32x32x16_bf16 v[64:79], v[140:143], v[80:83], v[64:79]
	s_setprio 0
	v_add_u32_e32 v122, s7, v119
	s_cbranch_vccnz .LBB0_1924
	v_add_u32_e32 v138, 0x28908, v122
	v_add_u32_e32 v140, 0x28920, v122
	v_add_u32_e32 v142, 0x28928, v122
	v_add_u32_e32 v124, 0x28940, v122
	v_add_u32_e32 v126, 0x28948, v122
	v_add_u32_e32 v132, 0x28960, v122
	v_add_u32_e32 v134, 0x28968, v122
	v_add_u32_e32 v123, 0x28900, v122
	ds_read2_b32 v[124:125], v124 offset1:1
	ds_read2_b32 v[126:127], v126 offset1:1
	ds_read2_b32 v[132:133], v132 offset1:1
	ds_read2_b32 v[134:135], v134 offset1:1
	ds_read2_b32 v[136:137], v123 offset1:1
	ds_read2_b32 v[138:139], v138 offset1:1
	ds_read2_b32 v[140:141], v140 offset1:1
	ds_read2_b32 v[142:143], v142 offset1:1
	s_waitcnt lgkmcnt(0)
	v_pk_add_f32 v[78:79], v[78:79], v[134:135]
	v_pk_add_f32 v[76:77], v[76:77], v[132:133]
	v_pk_add_f32 v[74:75], v[74:75], v[126:127]
	v_pk_add_f32 v[72:73], v[72:73], v[124:125]
	v_pk_add_f32 v[70:71], v[70:71], v[142:143]
	v_pk_add_f32 v[68:69], v[68:69], v[140:141]
	v_pk_add_f32 v[66:67], v[66:67], v[138:139]
	v_pk_add_f32 v[64:65], v[64:65], v[136:137]
; DI void expsum(f32x16& p, float& l_reg, bf16x8& pa0, bf16x8& pa1) {
; #pragma unroll
;     for (int r = 0; r < 16; ++r) p[r] = __builtin_amdgcn_exp2f(p[r]);
;     float ps = 0.f;
; #pragma unroll
;     for (int r = 0; r < 16; ++r) ps += p[r];
;     l_reg += ps; asm volatile("" : "+v"(l_reg));
;     ...
;     ATT_PK4(p, 0, pa0); ATT_PK4(p, 8, pa1);
;     ...
; }
.LBB0_1924:
	s_add_i32 s3, s22, 0xffffc000
	s_and_b32 s3, s3, 0x6000
	v_add_u32_e32 v123, s3, v114
	v_add_u32_e32 v140, v123, v118
	v_add_u32_e32 v136, v123, v117
	v_add_u32_e32 v132, v123, v116
	v_add_u32_e32 v123, v123, v115
	ds_read_b128 v[124:127], v123
	ds_read_b128 v[132:135], v132
	ds_read_b128 v[136:139], v136
	ds_read_b128 v[140:143], v140
	ds_read_b64_tr_b16 v[144:145], v121 offset:0x2000
	ds_read_b64_tr_b16 v[146:147], v121 offset:0x2800
	ds_read_b64_tr_b16 v[148:149], v121 offset:0x3000
	ds_read_b64_tr_b16 v[150:151], v121 offset:0x3800
	ds_read_b64_tr_b16 v[152:153], v121 offset:0x2200
	ds_read_b64_tr_b16 v[154:155], v121 offset:0x2a00
	ds_read_b64_tr_b16 v[156:157], v121 offset:0x3200
	ds_read_b64_tr_b16 v[158:159], v121 offset:0x3a00
	s_setprio 2
	ds_read_b64_tr_b16 v[162:163], v121 offset:0x2400
	ds_read_b64_tr_b16 v[164:165], v121 offset:0x2c00
	ds_read_b64_tr_b16 v[166:167], v121 offset:0x3400
	ds_read_b64_tr_b16 v[168:169], v121 offset:0x3c00
	ds_read_b64_tr_b16 v[170:171], v121 offset:0x2600
	ds_read_b64_tr_b16 v[172:173], v121 offset:0x2e00
	ds_read_b64_tr_b16 v[174:175], v121 offset:0x3600
	ds_read_b64_tr_b16 v[176:177], v121 offset:0x3e00
	v_exp_f32_e32 v64, v64
	v_exp_f32_e32 v65, v65
	v_exp_f32_e32 v66, v66
	v_exp_f32_e32 v67, v67
	v_exp_f32_e32 v68, v68
	v_exp_f32_e32 v69, v69
	v_add_f32_e32 v121, v65, v64
	v_exp_f32_e32 v70, v70
	v_add_f32_e32 v121, v66, v121
	v_exp_f32_e32 v71, v71
	v_add_f32_e32 v121, v67, v121
	v_exp_f32_e32 v72, v72
	v_add_f32_e32 v121, v68, v121
	v_exp_f32_e32 v73, v73
	v_add_f32_e32 v121, v69, v121
	v_exp_f32_e32 v74, v74
	v_add_f32_e32 v121, v70, v121
	v_exp_f32_e32 v75, v75
	v_add_f32_e32 v121, v71, v121
	v_exp_f32_e32 v76, v76
	v_add_f32_e32 v121, v72, v121
	v_exp_f32_e32 v77, v77
	v_add_f32_e32 v121, v73, v121
	v_exp_f32_e32 v78, v78
	v_add_f32_e32 v121, v74, v121
	v_exp_f32_e32 v79, v79
	v_add_f32_e32 v121, v75, v121
	v_add_f32_e32 v121, v76, v121
	v_add_f32_e32 v121, v77, v121
	v_add_f32_e32 v121, v78, v121
	v_add_f32_e32 v121, v79, v121
	v_add_f32_e32 v120, v120, v121
	v_cvt_pk_bf16_f32 v64, v64, v65
	v_cvt_pk_bf16_f32 v65, v66, v67
	v_cvt_pk_bf16_f32 v66, v68, v69
	v_cvt_pk_bf16_f32 v67, v70, v71
	v_cvt_pk_bf16_f32 v68, v72, v73
	v_cvt_pk_bf16_f32 v69, v74, v75
	v_cvt_pk_bf16_f32 v70, v76, v77
	v_cvt_pk_bf16_f32 v71, v78, v79
	s_nop 0
	v_permlane32_swap_b32_e32 v64, v66
	v_permlane32_swap_b32_e32 v65, v67
	v_permlane32_swap_b32_e32 v68, v70
	v_permlane32_swap_b32_e32 v69, v71
	s_waitcnt lgkmcnt(0)
	s_setprio 1
	s_cmp_lt_u32 s33, 0x100
	s_cbranch_scc1 .Lstg_d0_mid_11
	s_waitcnt vmcnt(3)
	s_barrier

; #define SBAR() __builtin_amdgcn_sched_barrier(0)
; DI int v_rd_base(int lane) { return ((lane & 3) << 3) | (((lane >> 2) & 3) << 6) | (((lane >> 4) & 1) << 5) | (((lane >> 5) & 1) << 8); }
; #define ATT_DMA_K(t) do { const bf16_t* kg_ = Kh + (size_t)(t) * 64 * LDK; LAS unsigned char* sb_ = lds + ((t) & 3) * KBUF; \
;     _Pragma("unroll") for (int i_ = 0; i_ < NKP; ++i_) __builtin_amdgcn_global_load_lds((const unsigned*)(kg_ + kgo[i_]), (LAS unsigned*)(sb_ + (wid + 8 * i_) * 1024), 16, 0, 0); } while (0)
; #define ATT_DMA_V(t, vs) do { const bf16_t* vg_ = Vh + (size_t)(t) * 64 * LDV; LAS unsigned char* sb_ = lds + V_OFF + (vs) * SHM_V; \
;     _Pragma("unroll") for (int i_ = 0; i_ < 2; ++i_) __builtin_amdgcn_global_load_lds((const unsigned*)(vg_ + vgo[i_]), (LAS unsigned*)(sb_ + (2 * wid + i_) * 1024), 16, 0, 0); } while (0)
; #define ATT_SEG(t) do { if constexpr (MODE != 0) { if (((t) == tL && tL > 0) || (t) == tR) { const float f_ = (t) == tR ? fR : fL; l_reg *= f_; \
;     _Pragma("unroll") for (int d = 0; d < 4; ++d) _Pragma("unroll") for (int r = 0; r < 16; ++r) o[d][r] *= f_; } } } while (0)
; #define ATT_BIAS(P, t, half) do { if constexpr (MODE != 0) { if ((t) >= tL && (t) < tR) { const LAS float* bp_ = bt + ((t) * 64 + (half) * 32 - qpos + 224 + 4 * hi);     \
;     _Pragma("unroll") for (int r = 0; r < 16; ++r) P[r] += bp_[(r & 3) + 8 * (r >> 2)]; } } } while (0)
; template <int DQK, int MODE, int LDQ, int LDK, int LDV> ...
;     ...
;     const int vbase = (int)(unsigned)(size_t)lds + V_OFF + v_rd_base(lane);
;     ...
;     constexpr int NDA = ND0 > 6 ? 6 : ND0;
;     ...
;     f32x16 pA, pB; bf16x8 pa0, pa1;
;     int v0 = 0, v1 = 1, v2 = 2;
;     ATT_TOP(NKP + 2);
;     { bf16x8 kf[NDA]; k_reads<DQK, 0, NDA>(kf, lds, 0, r32, hi); ATT_LGKM0(); qk_mma<0, NDA>(pA, kf, qr);
;       if constexpr (ND0 > NDA) { bf16x8 kg[ND0 - NDA]; k_reads<DQK, NDA, ND0>(kg, lds, 0, r32, hi); ATT_LGKM0(); qk_mma<NDA, ND0>(pA, kg, qr); }
;       ATT_BIAS(pA, 0, 0); }
;     if (wid >= 4) __builtin_amdgcn_s_setprio(1);
;     for (int j = 0; j < NT; ++j) {
;         if (j + 2 < NT) ATT_TOP(NKP + 2); else ATT_TOP(0);
;         if (j + 3 < NT) ATT_DMA_K(j + 3);
;         if (j + 2 < NT) ATT_DMA_V(j + 2, v2);
;         ATT_SEG(j); SBAR();
;         ATT_STEP(pA, pB, 0, v0, true, 1, j);
;         ATT_STEP(pB, pA, 1, v0, (j + 1 < NT), 0, j + 1);
.LBB0_1930:
	s_mov_b64 s[96:97], 0xc00
	ds_read_b128 v[98:101], v107 offset:12288
	ds_read_b128 v[102:105], v108 offset:12288
	ds_read_b128 v[114:117], v109 offset:12288
	ds_read_b128 v[122:125], v110 offset:12288
	v_lshl_add_u32 v96, s64, 14, v106
	ds_read_b64_tr_b16 v[132:133], v96 offset:0
	ds_read_b64_tr_b16 v[134:135], v96 offset:0x800
	ds_read_b64_tr_b16 v[136:137], v96 offset:0x1000
	ds_read_b64_tr_b16 v[138:139], v96 offset:0x1800
	ds_read_b64_tr_b16 v[140:141], v96 offset:0x200
	ds_read_b64_tr_b16 v[142:143], v96 offset:0xa00
	ds_read_b64_tr_b16 v[144:145], v96 offset:0x1200
	ds_read_b64_tr_b16 v[146:147], v96 offset:0x1a00
	s_setprio 2
	ds_read_b64_tr_b16 v[148:149], v96 offset:0x400
	ds_read_b64_tr_b16 v[150:151], v96 offset:0xc00
	ds_read_b64_tr_b16 v[152:153], v96 offset:0x1400
	ds_read_b64_tr_b16 v[154:155], v96 offset:0x1c00
	ds_read_b64_tr_b16 v[156:157], v96 offset:0x600
	ds_read_b64_tr_b16 v[158:159], v96 offset:0xe00
	ds_read_b64_tr_b16 v[162:163], v96 offset:0x1600
	ds_read_b64_tr_b16 v[164:165], v96 offset:0x1e00
	v_exp_f32_e32 v64, v64
	v_exp_f32_e32 v65, v65
	v_exp_f32_e32 v66, v66
	v_exp_f32_e32 v67, v67
	v_exp_f32_e32 v68, v68
	v_exp_f32_e32 v69, v69
	v_add_f32_e32 v97, v65, v64
	v_exp_f32_e32 v70, v70
	v_add_f32_e32 v97, v66, v97
	v_exp_f32_e32 v71, v71
	v_add_f32_e32 v97, v67, v97
	v_exp_f32_e32 v72, v72
	v_add_f32_e32 v97, v68, v97
	v_exp_f32_e32 v73, v73
	v_add_f32_e32 v97, v69, v97
	v_exp_f32_e32 v74, v74
	v_add_f32_e32 v97, v70, v97
	v_exp_f32_e32 v75, v75
	v_add_f32_e32 v97, v71, v97
	v_exp_f32_e32 v76, v76
	v_add_f32_e32 v97, v72, v97
	v_exp_f32_e32 v77, v77
	v_add_f32_e32 v97, v73, v97
	v_exp_f32_e32 v78, v78
	v_add_f32_e32 v97, v74, v97
	v_exp_f32_e32 v79, v79
	v_add_f32_e32 v97, v75, v97
	v_add_f32_e32 v97, v76, v97
	v_add_f32_e32 v97, v77, v97
	v_add_f32_e32 v97, v78, v97
	v_add_f32_e32 v97, v79, v97
	v_add_f32_e32 v97, v97, v120
	v_cvt_pk_bf16_f32 v64, v64, v65
	v_cvt_pk_bf16_f32 v65, v66, v67
	v_cvt_pk_bf16_f32 v66, v68, v69
	v_cvt_pk_bf16_f32 v67, v70, v71
	v_cvt_pk_bf16_f32 v68, v72, v73
	v_cvt_pk_bf16_f32 v69, v74, v75
	v_cvt_pk_bf16_f32 v70, v76, v77
	v_cvt_pk_bf16_f32 v71, v78, v79
	s_nop 0
	v_permlane32_swap_b32_e32 v64, v66
	v_permlane32_swap_b32_e32 v65, v67
	v_permlane32_swap_b32_e32 v68, v70
	v_permlane32_swap_b32_e32 v69, v71
	s_waitcnt lgkmcnt(0)
	s_setprio 1
	v_mfma_f32_32x32x16_bf16 v[0:15], v[64:67], v[132:135], v[0:15]
	s_cmp_gt_i32 s55, 61
	s_cselect_b64 s[0:1], -1, 0
	s_cmp_lt_i32 s58, 62
	s_cselect_b64 s[2:3], -1, 0
	s_or_b64 s[0:1], s[0:1], s[2:3]
	s_and_b64 vcc, exec, s[0:1]
	v_mfma_f32_32x32x16_bf16 v[48:63], v[64:67], v[140:143], v[48:63]
	v_mfma_f32_32x32x16_bf16 v[32:47], v[64:67], v[148:151], v[32:47]
	v_mfma_f32_32x32x16_bf16 v[16:31], v[64:67], v[156:159], v[16:31]
	v_mfma_f32_32x32x16_bf16 v[0:15], v[68:71], v[136:139], v[0:15]
	v_mfma_f32_32x32x16_bf16 v[48:63], v[68:71], v[144:147], v[48:63]
	v_mfma_f32_32x32x16_bf16 v[32:47], v[68:71], v[152:155], v[32:47]
	v_mfma_f32_32x32x16_bf16 v[16:31], v[68:71], v[162:165], v[16:31]
	s_waitcnt lgkmcnt(0)
	v_mfma_f32_32x32x16_bf16 v[64:79], v[98:101], v[92:95], 0
	v_mfma_f32_32x32x16_bf16 v[64:79], v[102:105], v[88:91], v[64:79]
	v_mfma_f32_32x32x16_bf16 v[64:79], v[114:117], v[84:87], v[64:79]
	v_mfma_f32_32x32x16_bf16 v[64:79], v[122:125], v[80:83], v[64:79]
	s_setprio 0
	s_cbranch_vccnz .LBB0_1932
	v_sub_u32_e32 v98, 0xf40, v111
	v_lshlrev_b32_e32 v98, 2, v98
	v_add3_u32 v98, s88, v98, v130
	v_add_u32_e32 v114, 0x400, v98
	v_add_u32_e32 v116, 0x408, v98
	v_add_u32_e32 v118, 0x420, v98
	v_add_u32_e32 v120, 0x428, v98
	v_add_u32_e32 v99, 0x440, v98
	v_add_u32_e32 v100, 0x448, v98
	v_add_u32_e32 v102, 0x460, v98
	v_add_u32_e32 v104, 0x468, v98
	ds_read2_b32 v[98:99], v99 offset1:1
	ds_read2_b32 v[100:101], v100 offset1:1
	ds_read2_b32 v[102:103], v102 offset1:1
	ds_read2_b32 v[104:105], v104 offset1:1
	ds_read2_b32 v[114:115], v114 offset1:1
	ds_read2_b32 v[116:117], v116 offset1:1
	ds_read2_b32 v[118:119], v118 offset1:1
	ds_read2_b32 v[120:121], v120 offset1:1
	s_waitcnt lgkmcnt(0)
	v_pk_add_f32 v[78:79], v[78:79], v[104:105]
	v_pk_add_f32 v[76:77], v[76:77], v[102:103]
	v_pk_add_f32 v[74:75], v[74:75], v[100:101]
	v_pk_add_f32 v[72:73], v[72:73], v[98:99]
	v_pk_add_f32 v[70:71], v[70:71], v[120:121]
	v_pk_add_f32 v[68:69], v[68:69], v[118:119]
	v_pk_add_f32 v[66:67], v[66:67], v[116:117]
	v_pk_add_f32 v[64:65], v[64:65], v[114:115]
.LBB0_1932:
	s_movk_i32 s64, 0x70
	ds_read_b128 v[98:101], v107 offset:16384
	ds_read_b128 v[102:105], v108 offset:16384
	ds_read_b128 v[114:117], v109 offset:16384
	ds_read_b128 v[118:121], v110 offset:16384
	ds_read_b64_tr_b16 v[122:123], v96 offset:0x2000
	ds_read_b64_tr_b16 v[124:125], v96 offset:0x2800
	ds_read_b64_tr_b16 v[132:133], v96 offset:0x3000
	ds_read_b64_tr_b16 v[134:135], v96 offset:0x3800
	ds_read_b64_tr_b16 v[136:137], v96 offset:0x2200
	ds_read_b64_tr_b16 v[138:139], v96 offset:0x2a00
	ds_read_b64_tr_b16 v[140:141], v96 offset:0x3200
	ds_read_b64_tr_b16 v[142:143], v96 offset:0x3a00
	s_setprio 2
	ds_read_b64_tr_b16 v[144:145], v96 offset:0x2400
	ds_read_b64_tr_b16 v[146:147], v96 offset:0x2c00
	ds_read_b64_tr_b16 v[148:149], v96 offset:0x3400
	ds_read_b64_tr_b16 v[150:151], v96 offset:0x3c00
	ds_read_b64_tr_b16 v[152:153], v96 offset:0x2600
	ds_read_b64_tr_b16 v[154:155], v96 offset:0x2e00
	ds_read_b64_tr_b16 v[156:157], v96 offset:0x3600
	ds_read_b64_tr_b16 v[158:159], v96 offset:0x3e00
	s_nop 5
	v_exp_f32_e32 v64, v64
	v_exp_f32_e32 v65, v65
	v_exp_f32_e32 v66, v66
	v_exp_f32_e32 v67, v67
	v_exp_f32_e32 v68, v68
	v_exp_f32_e32 v69, v69
	v_add_f32_e32 v96, v65, v64
	v_exp_f32_e32 v70, v70
	v_add_f32_e32 v96, v66, v96
	v_exp_f32_e32 v71, v71
	v_add_f32_e32 v96, v67, v96
	v_exp_f32_e32 v72, v72
	v_add_f32_e32 v96, v68, v96
	v_exp_f32_e32 v73, v73
	v_add_f32_e32 v96, v69, v96
	v_exp_f32_e32 v74, v74
	v_add_f32_e32 v96, v70, v96
	v_exp_f32_e32 v75, v75
	v_add_f32_e32 v96, v71, v96
	v_exp_f32_e32 v76, v76
	v_add_f32_e32 v96, v72, v96
	v_exp_f32_e32 v77, v77
	v_add_f32_e32 v96, v73, v96
	v_exp_f32_e32 v78, v78
	v_add_f32_e32 v96, v74, v96
	v_exp_f32_e32 v79, v79
	v_add_f32_e32 v96, v75, v96
	v_add_f32_e32 v96, v76, v96
	v_add_f32_e32 v96, v77, v96
	v_add_f32_e32 v96, v78, v96
	v_add_f32_e32 v96, v79, v96
	v_add_f32_e32 v96, v97, v96
	v_cvt_pk_bf16_f32 v64, v64, v65
	v_cvt_pk_bf16_f32 v65, v66, v67
	v_cvt_pk_bf16_f32 v66, v68, v69
	v_cvt_pk_bf16_f32 v67, v70, v71
	v_cvt_pk_bf16_f32 v68, v72, v73
	v_cvt_pk_bf16_f32 v69, v74, v75
	v_cvt_pk_bf16_f32 v70, v76, v77
	v_cvt_pk_bf16_f32 v71, v78, v79
	s_nop 0
	v_permlane32_swap_b32_e32 v64, v66
	v_permlane32_swap_b32_e32 v65, v67
	v_permlane32_swap_b32_e32 v68, v70
	v_permlane32_swap_b32_e32 v69, v71
	s_waitcnt lgkmcnt(0)
	s_setprio 1
	s_cmp_lt_u32 s33, 0x100
	s_cbranch_scc1 .Lstg_d0_m61_13
	s_waitcnt vmcnt(0)
	s_barrier

; #define SBAR() __builtin_amdgcn_sched_barrier(0)
; DI int v_rd_base(int lane) { return ((lane & 3) << 3) | (((lane >> 2) & 3) << 6) | (((lane >> 4) & 1) << 5) | (((lane >> 5) & 1) << 8); }
; #define ATT_DMA_K(t) do { const bf16_t* kg_ = Kh + (size_t)(t) * 64 * LDK; LAS unsigned char* sb_ = lds + ((t) & 3) * KBUF; \
;     _Pragma("unroll") for (int i_ = 0; i_ < NKP; ++i_) __builtin_amdgcn_global_load_lds((const unsigned*)(kg_ + kgo[i_]), (LAS unsigned*)(sb_ + (wid + 8 * i_) * 1024), 16, 0, 0); } while (0)
; #define ATT_DMA_V(t, vs) do { const bf16_t* vg_ = Vh + (size_t)(t) * 64 * LDV; LAS unsigned char* sb_ = lds + V_OFF + (vs) * SHM_V; \
;     _Pragma("unroll") for (int i_ = 0; i_ < 2; ++i_) __builtin_amdgcn_global_load_lds((const unsigned*)(vg_ + vgo[i_]), (LAS unsigned*)(sb_ + (2 * wid + i_) * 1024), 16, 0, 0); } while (0)
; #define ATT_SEG(t) do { if constexpr (MODE != 0) { if (((t) == tL && tL > 0) || (t) == tR) { const float f_ = (t) == tR ? fR : fL; l_reg *= f_; \
;     _Pragma("unroll") for (int d = 0; d < 4; ++d) _Pragma("unroll") for (int r = 0; r < 16; ++r) o[d][r] *= f_; } } } while (0)
; #define ATT_BIAS(P, t, half) do { if constexpr (MODE != 0) { if ((t) >= tL && (t) < tR) { const LAS float* bp_ = bt + ((t) * 64 + (half) * 32 - qpos + 224 + 4 * hi);     \
;     _Pragma("unroll") for (int r = 0; r < 16; ++r) P[r] += bp_[(r & 3) + 8 * (r >> 2)]; } } } while (0)
; template <int DQK, int MODE, int LDQ, int LDK, int LDV> ...
;     ...
;     const int vbase = (int)(unsigned)(size_t)lds + V_OFF + v_rd_base(lane);
;     ...
;     constexpr int NDA = ND0 > 6 ? 6 : ND0;
;     ...
;     f32x16 pA, pB; bf16x8 pa0, pa1;
;     int v0 = 0, v1 = 1, v2 = 2;
;     ATT_TOP(NKP + 2);
;     { bf16x8 kf[NDA]; k_reads<DQK, 0, NDA>(kf, lds, 0, r32, hi); ATT_LGKM0(); qk_mma<0, NDA>(pA, kf, qr);
;       if constexpr (ND0 > NDA) { bf16x8 kg[ND0 - NDA]; k_reads<DQK, NDA, ND0>(kg, lds, 0, r32, hi); ATT_LGKM0(); qk_mma<NDA, ND0>(pA, kg, qr); }
;       ATT_BIAS(pA, 0, 0); }
;     if (wid >= 4) __builtin_amdgcn_s_setprio(1);
;     for (int j = 0; j < NT; ++j) {
;         if (j + 2 < NT) ATT_TOP(NKP + 2); else ATT_TOP(0);
;         if (j + 3 < NT) ATT_DMA_K(j + 3);
;         if (j + 2 < NT) ATT_DMA_V(j + 2, v2);
;         ATT_SEG(j); SBAR();
;         ATT_STEP(pA, pB, 0, v0, true, 1, j);
;         ATT_STEP(pB, pA, 1, v0, (j + 1 < NT), 0, j + 1);
.LBB0_1936:
	ds_read_b128 v[100:103], v107 offset:20480
	ds_read_b128 v[114:117], v108 offset:20480
	ds_read_b128 v[118:121], v109 offset:20480
	ds_read_b128 v[122:125], v110 offset:20480
	v_add_u32_e32 v98, 0x8000, v106
	ds_read_b64_tr_b16 v[132:133], v98 offset:0
	ds_read_b64_tr_b16 v[134:135], v98 offset:0x800
	ds_read_b64_tr_b16 v[136:137], v98 offset:0x1000
	ds_read_b64_tr_b16 v[138:139], v98 offset:0x1800
	ds_read_b64_tr_b16 v[140:141], v98 offset:0x200
	ds_read_b64_tr_b16 v[142:143], v98 offset:0xa00
	ds_read_b64_tr_b16 v[144:145], v98 offset:0x1200
	ds_read_b64_tr_b16 v[146:147], v98 offset:0x1a00
	s_setprio 2
	ds_read_b64_tr_b16 v[148:149], v98 offset:0x400
	ds_read_b64_tr_b16 v[150:151], v98 offset:0xc00
	ds_read_b64_tr_b16 v[152:153], v98 offset:0x1400
	ds_read_b64_tr_b16 v[154:155], v98 offset:0x1c00
	ds_read_b64_tr_b16 v[156:157], v98 offset:0x600
	ds_read_b64_tr_b16 v[158:159], v98 offset:0xe00
	ds_read_b64_tr_b16 v[162:163], v98 offset:0x1600
	ds_read_b64_tr_b16 v[164:165], v98 offset:0x1e00
	v_exp_f32_e32 v64, v64
	v_exp_f32_e32 v65, v65
	v_exp_f32_e32 v66, v66
	v_exp_f32_e32 v67, v67
	v_exp_f32_e32 v68, v68
	v_exp_f32_e32 v69, v69
	v_add_f32_e32 v99, v65, v64
	v_exp_f32_e32 v70, v70
	v_add_f32_e32 v99, v66, v99
	v_exp_f32_e32 v71, v71
	v_add_f32_e32 v99, v67, v99
	v_exp_f32_e32 v72, v72
	v_add_f32_e32 v99, v68, v99
	v_exp_f32_e32 v73, v73
	v_add_f32_e32 v99, v69, v99
	v_exp_f32_e32 v74, v74
	v_add_f32_e32 v99, v70, v99
	v_exp_f32_e32 v75, v75
	v_add_f32_e32 v99, v71, v99
	v_exp_f32_e32 v76, v76
	v_add_f32_e32 v99, v72, v99
	v_exp_f32_e32 v77, v77
	v_add_f32_e32 v99, v73, v99
	v_exp_f32_e32 v78, v78
	v_add_f32_e32 v99, v74, v99
	v_exp_f32_e32 v79, v79
	v_add_f32_e32 v99, v75, v99
	v_add_f32_e32 v99, v76, v99
	v_add_f32_e32 v99, v77, v99
	v_add_f32_e32 v99, v78, v99
	v_add_f32_e32 v99, v79, v99
	v_add_f32_e32 v96, v99, v96
	v_cvt_pk_bf16_f32 v64, v64, v65
	v_cvt_pk_bf16_f32 v65, v66, v67
	v_cvt_pk_bf16_f32 v66, v68, v69
	v_cvt_pk_bf16_f32 v67, v70, v71
	v_cvt_pk_bf16_f32 v68, v72, v73
	v_cvt_pk_bf16_f32 v69, v74, v75
	v_cvt_pk_bf16_f32 v70, v76, v77
	v_cvt_pk_bf16_f32 v71, v78, v79
	s_nop 0
	v_permlane32_swap_b32_e32 v64, v66
	v_permlane32_swap_b32_e32 v65, v67
	v_permlane32_swap_b32_e32 v68, v70
	v_permlane32_swap_b32_e32 v69, v71
	s_waitcnt lgkmcnt(0)
	s_setprio 1
	v_mfma_f32_32x32x16_bf16 v[0:15], v[64:67], v[132:135], v[0:15]
	s_and_b64 vcc, exec, s[2:3]
	v_mfma_f32_32x32x16_bf16 v[48:63], v[64:67], v[140:143], v[48:63]
	v_mfma_f32_32x32x16_bf16 v[32:47], v[64:67], v[148:151], v[32:47]
	v_mfma_f32_32x32x16_bf16 v[16:31], v[64:67], v[156:159], v[16:31]
	v_mfma_f32_32x32x16_bf16 v[0:15], v[68:71], v[136:139], v[0:15]
	v_mfma_f32_32x32x16_bf16 v[48:63], v[68:71], v[144:147], v[48:63]
	v_mfma_f32_32x32x16_bf16 v[32:47], v[68:71], v[152:155], v[32:47]
	v_mfma_f32_32x32x16_bf16 v[16:31], v[68:71], v[162:165], v[16:31]
	s_waitcnt lgkmcnt(0)
	v_mfma_f32_32x32x16_bf16 v[64:79], v[100:103], v[92:95], 0
	v_mfma_f32_32x32x16_bf16 v[64:79], v[114:117], v[88:91], v[64:79]
	v_mfma_f32_32x32x16_bf16 v[64:79], v[118:121], v[84:87], v[64:79]
	v_mfma_f32_32x32x16_bf16 v[64:79], v[122:125], v[80:83], v[64:79]
	s_setprio 0
	s_cbranch_vccnz .LBB0_1938
	v_add3_u32 v97, s88, v97, v130
	v_add_u32_e32 v118, 0x408, v97
	v_add_u32_e32 v120, 0x420, v97
	v_add_u32_e32 v122, 0x428, v97
	v_add_u32_e32 v100, 0x440, v97
	v_add_u32_e32 v102, 0x448, v97
	v_add_u32_e32 v104, 0x460, v97
	v_add_u32_e32 v99, 0x400, v97
	v_add_u32_e32 v97, 0x468, v97
	ds_read2_b32 v[100:101], v100 offset1:1
	ds_read2_b32 v[102:103], v102 offset1:1
	ds_read2_b32 v[104:105], v104 offset1:1
	ds_read2_b32 v[114:115], v97 offset1:1
	ds_read2_b32 v[116:117], v99 offset1:1
	ds_read2_b32 v[118:119], v118 offset1:1
	ds_read2_b32 v[120:121], v120 offset1:1
	ds_read2_b32 v[122:123], v122 offset1:1
	s_waitcnt lgkmcnt(0)
	v_pk_add_f32 v[78:79], v[78:79], v[114:115]
	v_pk_add_f32 v[76:77], v[76:77], v[104:105]
	v_pk_add_f32 v[74:75], v[74:75], v[102:103]
	v_pk_add_f32 v[72:73], v[72:73], v[100:101]
	v_pk_add_f32 v[70:71], v[70:71], v[122:123]
	v_pk_add_f32 v[68:69], v[68:69], v[120:121]
	v_pk_add_f32 v[66:67], v[66:67], v[118:119]
	v_pk_add_f32 v[64:65], v[64:65], v[116:117]
.LBB0_1938:
	ds_read_b128 v[100:103], v107 offset:24576
	ds_read_b128 v[114:117], v108 offset:24576
	ds_read_b128 v[118:121], v109 offset:24576
	ds_read_b128 v[122:125], v110 offset:24576
	ds_read_b64_tr_b16 v[132:133], v98 offset:0x2000
	ds_read_b64_tr_b16 v[134:135], v98 offset:0x2800
	ds_read_b64_tr_b16 v[136:137], v98 offset:0x3000
	ds_read_b64_tr_b16 v[138:139], v98 offset:0x3800
	ds_read_b64_tr_b16 v[140:141], v98 offset:0x2200
	ds_read_b64_tr_b16 v[142:143], v98 offset:0x2a00
	ds_read_b64_tr_b16 v[144:145], v98 offset:0x3200
	ds_read_b64_tr_b16 v[146:147], v98 offset:0x3a00
	s_setprio 2
	ds_read_b64_tr_b16 v[148:149], v98 offset:0x2400
	ds_read_b64_tr_b16 v[150:151], v98 offset:0x2c00
	ds_read_b64_tr_b16 v[152:153], v98 offset:0x3400
	ds_read_b64_tr_b16 v[154:155], v98 offset:0x3c00
	ds_read_b64_tr_b16 v[156:157], v98 offset:0x2600
	ds_read_b64_tr_b16 v[158:159], v98 offset:0x2e00
	ds_read_b64_tr_b16 v[162:163], v98 offset:0x3600
	ds_read_b64_tr_b16 v[164:165], v98 offset:0x3e00
	s_nop 6
	v_exp_f32_e32 v64, v64
	v_exp_f32_e32 v65, v65
	v_exp_f32_e32 v66, v66
	v_exp_f32_e32 v67, v67
	v_exp_f32_e32 v68, v68
	v_exp_f32_e32 v69, v69
	v_add_f32_e32 v97, v65, v64
	v_exp_f32_e32 v70, v70
	v_add_f32_e32 v97, v66, v97
	v_exp_f32_e32 v71, v71
	v_add_f32_e32 v97, v67, v97
	v_exp_f32_e32 v72, v72
	v_add_f32_e32 v97, v68, v97
	v_exp_f32_e32 v73, v73
	v_add_f32_e32 v97, v69, v97
	v_exp_f32_e32 v74, v74
	v_add_f32_e32 v97, v70, v97
	v_exp_f32_e32 v75, v75
	v_add_f32_e32 v97, v71, v97
	v_exp_f32_e32 v76, v76
	v_add_f32_e32 v97, v72, v97
	v_exp_f32_e32 v77, v77
	v_add_f32_e32 v97, v73, v97
	v_exp_f32_e32 v78, v78
	v_add_f32_e32 v97, v74, v97
	v_exp_f32_e32 v79, v79
	v_add_f32_e32 v97, v75, v97
	v_add_f32_e32 v97, v76, v97
	v_add_f32_e32 v97, v77, v97
	v_add_f32_e32 v97, v78, v97
	v_add_f32_e32 v97, v79, v97
	v_add_f32_e32 v96, v96, v97
	v_cvt_pk_bf16_f32 v64, v64, v65
	v_cvt_pk_bf16_f32 v65, v66, v67
	v_cvt_pk_bf16_f32 v66, v68, v69
	v_cvt_pk_bf16_f32 v67, v70, v71
	v_cvt_pk_bf16_f32 v68, v72, v73
	v_cvt_pk_bf16_f32 v69, v74, v75
	v_cvt_pk_bf16_f32 v70, v76, v77
	v_cvt_pk_bf16_f32 v71, v78, v79
	s_nop 0
	v_permlane32_swap_b32_e32 v64, v66
	v_permlane32_swap_b32_e32 v65, v67
	v_permlane32_swap_b32_e32 v68, v70
	v_permlane32_swap_b32_e32 v69, v71
	s_waitcnt lgkmcnt(0)
	s_setprio 1
	s_cmp_lt_u32 s33, 0x100
	s_cbranch_scc1 .Lstg_d0_m62_15
	s_waitcnt vmcnt(0)
	s_barrier

; #define LAS __attribute__((address_space(3)))
; DI void pv_mma(f32x16* o, const s16x4* vf, bf16x8 pa0, bf16x8 pa1) {
;     ...
; #pragma unroll
;     for (int d0 = 0; d0 < 4; ++d0) {
;         o[d0] = __builtin_amdgcn_mfma_f32_32x32x16_bf16(pa0, ATT_PK(vf[4 * d0], vf[4 * d0 + 1]), o[d0], 0, 0, 0);
;         o[d0] = __builtin_amdgcn_mfma_f32_32x32x16_bf16(pa1, ATT_PK(vf[4 * d0 + 2], vf[4 * d0 + 3]), o[d0], 0, 0, 0); }
;     ...
; }
; template <int DQK, int D0A, int D0B> DI void k_reads(bf16x8* kf, const LAS unsigned char* Ks, int half, int r32, int hi) {
; #pragma unroll
;     for (int d0 = D0A; d0 < D0B; ++d0) kf[d0 - D0A] = *(const LAS bf16x8*)(Ks + half * (32 * DQK * 2) + kswz<DQK>(r32, (d0 * 16 + hi * 8) * 2));
; }
; template <int D0A, int D0B> DI void qk_mma(f32x16& p, const bf16x8* kf, const bf16x8* qr) {
; #pragma unroll
;     for (int d0 = D0A; d0 < D0B; ++d0) {
;         if (d0 == 0) { f32x16 z; _Pragma("unroll") for (int r = 0; r < 16; ++r) z[r] = 0.f; p = __builtin_amdgcn_mfma_f32_32x32x16_bf16(kf[0], qr[0], z, 0, 0, 0); }
;         else p = __builtin_amdgcn_mfma_f32_32x32x16_bf16(kf[d0 - D0A], qr[d0], p, 0, 0, 0); }
; }
.LBB0_1942:
	ds_read_b128 v[98:101], v107 offset:28672
	ds_read_b128 v[102:105], v108 offset:28672
	ds_read_b128 v[112:115], v109 offset:28672
	ds_read_b128 v[108:111], v110 offset:28672
	ds_read_b64_tr_b16 v[116:117], v106 offset:0
	ds_read_b64_tr_b16 v[118:119], v106 offset:0x800
	ds_read_b64_tr_b16 v[120:121], v106 offset:0x1000
	ds_read_b64_tr_b16 v[122:123], v106 offset:0x1800
	ds_read_b64_tr_b16 v[124:125], v106 offset:0x200
	ds_read_b64_tr_b16 v[126:127], v106 offset:0xa00
	ds_read_b64_tr_b16 v[132:133], v106 offset:0x1200
	ds_read_b64_tr_b16 v[134:135], v106 offset:0x1a00
	s_setprio 2
	ds_read_b64_tr_b16 v[136:137], v106 offset:0x400
	ds_read_b64_tr_b16 v[138:139], v106 offset:0xc00
	ds_read_b64_tr_b16 v[140:141], v106 offset:0x1400
	ds_read_b64_tr_b16 v[142:143], v106 offset:0x1c00
	ds_read_b64_tr_b16 v[144:145], v106 offset:0x600
	ds_read_b64_tr_b16 v[146:147], v106 offset:0xe00
	ds_read_b64_tr_b16 v[148:149], v106 offset:0x1600
	ds_read_b64_tr_b16 v[150:151], v106 offset:0x1e00
	v_exp_f32_e32 v64, v64
	v_exp_f32_e32 v65, v65
	v_exp_f32_e32 v66, v66
	v_exp_f32_e32 v67, v67
	v_exp_f32_e32 v68, v68
	v_exp_f32_e32 v69, v69
	v_add_f32_e32 v107, v65, v64
	v_exp_f32_e32 v70, v70
	v_add_f32_e32 v107, v66, v107
	v_exp_f32_e32 v71, v71
	v_add_f32_e32 v107, v67, v107
	v_exp_f32_e32 v72, v72
	v_add_f32_e32 v107, v68, v107
	v_exp_f32_e32 v73, v73
	v_add_f32_e32 v107, v69, v107
	v_exp_f32_e32 v74, v74
	v_add_f32_e32 v107, v70, v107
	v_exp_f32_e32 v75, v75
	v_add_f32_e32 v107, v71, v107
	v_exp_f32_e32 v76, v76
	v_add_f32_e32 v107, v72, v107
	v_exp_f32_e32 v77, v77
	v_add_f32_e32 v107, v73, v107
	v_exp_f32_e32 v78, v78
	v_add_f32_e32 v107, v74, v107
	v_exp_f32_e32 v79, v79
	v_add_f32_e32 v107, v75, v107
	v_add_f32_e32 v107, v76, v107
	v_add_f32_e32 v107, v77, v107
	v_add_f32_e32 v107, v78, v107
	v_add_f32_e32 v107, v79, v107
	v_add_f32_e32 v96, v107, v96
	v_cvt_pk_bf16_f32 v64, v64, v65
	v_cvt_pk_bf16_f32 v65, v66, v67
	v_cvt_pk_bf16_f32 v66, v68, v69
	v_cvt_pk_bf16_f32 v67, v70, v71
	v_cvt_pk_bf16_f32 v68, v72, v73
	v_cvt_pk_bf16_f32 v69, v74, v75
	v_cvt_pk_bf16_f32 v70, v76, v77
	v_cvt_pk_bf16_f32 v71, v78, v79
	s_nop 0
	v_permlane32_swap_b32_e32 v64, v66
	v_permlane32_swap_b32_e32 v65, v67
	v_permlane32_swap_b32_e32 v68, v70
	v_permlane32_swap_b32_e32 v69, v71
	s_waitcnt lgkmcnt(0)
	s_setprio 1
	v_mfma_f32_32x32x16_bf16 v[0:15], v[64:67], v[116:119], v[0:15]
	s_and_b64 vcc, exec, s[2:3]
	v_mfma_f32_32x32x16_bf16 v[48:63], v[64:67], v[124:127], v[48:63]
	v_mfma_f32_32x32x16_bf16 v[32:47], v[64:67], v[136:139], v[32:47]
	v_mfma_f32_32x32x16_bf16 v[16:31], v[64:67], v[144:147], v[16:31]
	v_mfma_f32_32x32x16_bf16 v[0:15], v[68:71], v[120:123], v[0:15]
	v_mfma_f32_32x32x16_bf16 v[48:63], v[68:71], v[132:135], v[48:63]
	v_mfma_f32_32x32x16_bf16 v[32:47], v[68:71], v[140:143], v[32:47]
	v_mfma_f32_32x32x16_bf16 v[16:31], v[68:71], v[148:151], v[16:31]
	s_waitcnt lgkmcnt(0)
	v_mfma_f32_32x32x16_bf16 v[64:79], v[98:101], v[92:95], 0
	v_mfma_f32_32x32x16_bf16 v[64:79], v[102:105], v[88:91], v[64:79]
	v_mfma_f32_32x32x16_bf16 v[64:79], v[112:115], v[84:87], v[64:79]
	v_mfma_f32_32x32x16_bf16 v[64:79], v[108:111], v[80:83], v[64:79]
	s_setprio 0
	s_cbranch_vccnz .LBB0_1944
	v_add3_u32 v80, s88, v97, v130
	v_add_u32_e32 v88, 0x400, v80
	v_add_u32_e32 v90, 0x408, v80
	v_add_u32_e32 v92, 0x420, v80
	v_add_u32_e32 v94, 0x428, v80
	v_add_u32_e32 v81, 0x440, v80
	v_add_u32_e32 v82, 0x448, v80
	v_add_u32_e32 v84, 0x460, v80
	v_add_u32_e32 v86, 0x468, v80
	ds_read2_b32 v[80:81], v81 offset1:1
	ds_read2_b32 v[82:83], v82 offset1:1
	ds_read2_b32 v[84:85], v84 offset1:1
	ds_read2_b32 v[86:87], v86 offset1:1
	ds_read2_b32 v[88:89], v88 offset1:1
	ds_read2_b32 v[90:91], v90 offset1:1
	ds_read2_b32 v[92:93], v92 offset1:1
	ds_read2_b32 v[94:95], v94 offset1:1
	s_waitcnt lgkmcnt(0)
	v_pk_add_f32 v[78:79], v[78:79], v[86:87]
	v_pk_add_f32 v[76:77], v[76:77], v[84:85]
	v_pk_add_f32 v[74:75], v[74:75], v[82:83]
	v_pk_add_f32 v[72:73], v[72:73], v[80:81]
	v_pk_add_f32 v[70:71], v[70:71], v[94:95]
	v_pk_add_f32 v[68:69], v[68:69], v[92:93]
	v_pk_add_f32 v[66:67], v[66:67], v[90:91]
	v_pk_add_f32 v[64:65], v[64:65], v[88:89]
.LBB0_1944:
	s_lshl_b32 s0, s54, 2
	s_add_i32 s0, s0, 0
	s_add_i32 s0, s0, 0x24000
	ds_read_b64_tr_b16 v[80:81], v106 offset:0x2000
	ds_read_b64_tr_b16 v[82:83], v106 offset:0x2800
	ds_read_b64_tr_b16 v[84:85], v106 offset:0x3000
	ds_read_b64_tr_b16 v[86:87], v106 offset:0x3800
	ds_read_b64_tr_b16 v[88:89], v106 offset:0x2200
	ds_read_b64_tr_b16 v[90:91], v106 offset:0x2a00
	ds_read_b64_tr_b16 v[92:93], v106 offset:0x3200
	ds_read_b64_tr_b16 v[94:95], v106 offset:0x3a00
	s_setprio 2
	ds_read_b64_tr_b16 v[98:99], v106 offset:0x2400
	ds_read_b64_tr_b16 v[100:101], v106 offset:0x2c00
	ds_read_b64_tr_b16 v[102:103], v106 offset:0x3400
	ds_read_b64_tr_b16 v[104:105], v106 offset:0x3c00
	ds_read_b64_tr_b16 v[108:109], v106 offset:0x2600
	ds_read_b64_tr_b16 v[110:111], v106 offset:0x2e00
	ds_read_b64_tr_b16 v[112:113], v106 offset:0x3600
	ds_read_b64_tr_b16 v[114:115], v106 offset:0x3e00
	s_nop 7
	v_exp_f32_e32 v97, v64
	v_exp_f32_e32 v65, v65
	v_exp_f32_e32 v106, v66
	v_exp_f32_e32 v67, v67
	v_exp_f32_e32 v68, v68
	v_exp_f32_e32 v69, v69
	v_add_f32_e32 v64, v65, v97
	v_exp_f32_e32 v70, v70
	v_add_f32_e32 v64, v106, v64
	v_exp_f32_e32 v71, v71
	v_add_f32_e32 v64, v67, v64
	v_exp_f32_e32 v72, v72
	v_add_f32_e32 v64, v68, v64
	v_exp_f32_e32 v73, v73
	v_add_f32_e32 v64, v69, v64
	v_exp_f32_e32 v74, v74
	v_add_f32_e32 v64, v70, v64
	v_exp_f32_e32 v75, v75
	v_add_f32_e32 v64, v71, v64
	v_exp_f32_e32 v76, v76
	v_add_f32_e32 v64, v72, v64
	v_exp_f32_e32 v77, v77
	v_add_f32_e32 v64, v73, v64
	v_exp_f32_e32 v78, v78
	v_add_f32_e32 v64, v74, v64
	v_exp_f32_e32 v79, v79
	v_add_f32_e32 v64, v75, v64
	v_add_f32_e32 v64, v76, v64
	v_add_f32_e32 v64, v77, v64
	v_add_f32_e32 v64, v78, v64
	v_add_f32_e32 v64, v79, v64
	v_add_f32_e32 v64, v96, v64
	v_cvt_pk_bf16_f32 v66, v97, v65
	v_cvt_pk_bf16_f32 v67, v106, v67
	v_cvt_pk_bf16_f32 v68, v68, v69
	v_cvt_pk_bf16_f32 v69, v70, v71
	v_cvt_pk_bf16_f32 v70, v72, v73
	v_cvt_pk_bf16_f32 v71, v74, v75
	v_cvt_pk_bf16_f32 v72, v76, v77
	v_cvt_pk_bf16_f32 v73, v78, v79
	s_nop 0
	v_permlane32_swap_b32_e32 v66, v68
	v_permlane32_swap_b32_e32 v67, v69
	v_permlane32_swap_b32_e32 v70, v72
	v_permlane32_swap_b32_e32 v71, v73
	s_waitcnt lgkmcnt(0)
; template <int TAG = 0> DI int fresh_tid(int wv) { int l; asm volatile("v_mbcnt_lo_u32_b32 %0, -1, 0\n\tv_mbcnt_hi_u32_b32 %0, -1, %0 ; site %1" : "=v"(l) : "n"(TAG)); return wv * 64 + l; }
; DI unsigned short f2bf(float x) { unsigned u = __float_as_uint(x); u += 0x7fffu + ((u >> 16) & 1u); return (unsigned short)(u >> 16); }
; DI int crow(int r, int hi) { return (r & 3) + 8 * (r >> 2) + 4 * hi; }
; DI float swap_sum(float v) { auto rr = __builtin_amdgcn_permlane32_swap(__float_as_uint(v), __float_as_uint(v), false, false); return __uint_as_float(rr[0]) + __uint_as_float(rr[1]); }
; template <int DQK, int MODE, int LDQ, int LDK, int LDV> ...
;     ...
;     __builtin_amdgcn_s_setprio(0);
;     ...
;     l_reg = swap_sum(l_reg);
;     { const int lane2 = fresh_tid<110 + MODE>(wv) & 63, r32 = lane2 & 31, hi = lane2 >> 5;
;     if (hi == 0) li_l[r32] = l_reg;
;     asm volatile("s_waitcnt lgkmcnt(0)" ::: "memory");
;     float s0v[MODE == 2 ? 16 : 1][4];
;     if constexpr (MODE == 2) {
; #pragma unroll
;         for (int r = 0; r < 16; ++r)
; #pragma unroll
;             for (int d0 = 0; d0 < 4; ++d0) s0v[r][d0] = S0[(size_t)(wid * 32 + crow(r, hi)) * 512 + d0 * 32 + r32];
;     }
; #pragma unroll
;     for (int r = 0; r < 16; ++r) { const int orow = wid * 32 + crow(r, hi); const float rl = __builtin_amdgcn_rcpf(li_l[crow(r, hi)]);
;         if constexpr (MODE == 0) {
; #pragma unroll
;             for (int d0 = 0; d0 < 4; ++d0) AOb[(size_t)orow * 1024 + d0 * 32 + r32] = f2bf(o[d0][r] * rl);
;         } else if constexpr (MODE == 1) {
; #pragma unroll
;             for (int d0 = 0; d0 < 4; ++d0) S0[(size_t)orow * 512 + d0 * 32 + r32] = o[d0][r] * rl;
	s_setprio 1
	v_mfma_f32_32x32x16_bf16 v[0:15], v[66:69], v[80:83], v[0:15]
	v_mfma_f32_32x32x16_bf16 v[48:63], v[66:69], v[88:91], v[48:63]
	v_mfma_f32_32x32x16_bf16 v[32:47], v[66:69], v[98:101], v[32:47]
	v_mfma_f32_32x32x16_bf16 v[16:31], v[66:69], v[108:111], v[16:31]
	v_mfma_f32_32x32x16_bf16 v[0:15], v[70:73], v[84:87], v[0:15]
	v_mfma_f32_32x32x16_bf16 v[48:63], v[70:73], v[92:95], v[48:63]
	v_mfma_f32_32x32x16_bf16 v[32:47], v[70:73], v[102:105], v[32:47]
	v_mfma_f32_32x32x16_bf16 v[16:31], v[70:73], v[112:115], v[16:31]
	s_setprio 0
	v_mbcnt_lo_u32_b32 v66, -1, 0
	v_mbcnt_hi_u32_b32 v66, -1, v66
	v_mov_b32_e32 v67, v64
	v_and_b32_e32 v65, 31, v66
	v_bfe_u32 v66, v66, 5, 1
	v_permlane32_swap_b32_e32 v64, v67
	v_cmp_eq_u32_e32 vcc, 0, v66
	s_and_saveexec_b64 s[2:3], vcc
	v_lshl_add_u32 v68, v65, 2, s0
	v_add_f32_e32 v64, v64, v67
	ds_write_b32 v68, v64
	s_or_b64 exec, exec, s[2:3]
	s_waitcnt lgkmcnt(0)
	v_lshl_add_u32 v68, v66, 4, s0
	ds_read_b128 v[70:73], v68
	ds_read_b128 v[74:77], v68 offset:32
	s_lshl_b64 s[58:59], s[40:41], 11
	v_readlane_b32 s1, v255, 2
	s_add_u32 s1, s1, s58
	v_readlane_b32 s2, v255, 0
	s_addc_u32 s2, s2, s59
	s_lshl_b32 s3, s87, 2
	s_waitcnt lgkmcnt(0)
	v_rcp_f32_e32 v69, v70
	s_add_u32 s54, s1, s3
	v_lshl_or_b32 v66, v66, 2, s94
	s_addc_u32 s55, s2, 0
	v_lshlrev_b32_e32 v130, 2, v65
	v_ashrrev_i32_e32 v67, 31, v66
	v_lshl_add_u64 v[64:65], s[54:55], 0, v[130:131]
	v_lshlrev_b64 v[78:79], 11, v[66:67]
	v_lshl_add_u64 v[78:79], v[64:65], 0, v[78:79]
	v_mul_f32_e32 v0, v0, v69
	global_store_dword v[78:79], v0, off
	v_mul_f32_e32 v0, v48, v69
	global_store_dword v[78:79], v0, off offset:128
	v_mul_f32_e32 v0, v32, v69
	global_store_dword v[78:79], v0, off offset:256
	v_mul_f32_e32 v0, v16, v69
	global_store_dword v[78:79], v0, off offset:384
	v_rcp_f32_e32 v0, v71
	v_or_b32_e32 v70, 1, v66
	v_ashrrev_i32_e32 v71, 31, v70
	v_lshlrev_b64 v[70:71], 11, v[70:71]
	v_lshl_add_u64 v[70:71], v[64:65], 0, v[70:71]
	v_mul_f32_e32 v1, v1, v0
	global_store_dword v[70:71], v1, off
	v_mul_f32_e32 v1, v49, v0
	global_store_dword v[70:71], v1, off offset:128
	v_mul_f32_e32 v1, v33, v0
	v_mul_f32_e32 v0, v17, v0
	v_rcp_f32_e32 v16, v72
	global_store_dword v[70:71], v0, off offset:384
	v_or_b32_e32 v0, 2, v66
	global_store_dword v[70:71], v1, off offset:256
	v_ashrrev_i32_e32 v1, 31, v0
	v_lshlrev_b64 v[0:1], 11, v[0:1]
	v_lshl_add_u64 v[0:1], v[64:65], 0, v[0:1]
	v_mul_f32_e32 v2, v2, v16
	global_store_dword v[0:1], v2, off
	v_mul_f32_e32 v2, v50, v16
	global_store_dword v[0:1], v2, off offset:128
	v_mul_f32_e32 v2, v34, v16
	global_store_dword v[0:1], v2, off offset:256
	v_mul_f32_e32 v2, v18, v16
	global_store_dword v[0:1], v2, off offset:384
	v_rcp_f32_e32 v2, v73
	v_or_b32_e32 v0, 3, v66
	v_ashrrev_i32_e32 v1, 31, v0
	v_lshlrev_b64 v[0:1], 11, v[0:1]
	v_lshl_add_u64 v[0:1], v[64:65], 0, v[0:1]
	v_mul_f32_e32 v3, v3, v2
	global_store_dword v[0:1], v3, off
	v_mul_f32_e32 v3, v51, v2
	global_store_dword v[0:1], v3, off offset:128
	v_mul_f32_e32 v3, v35, v2
	v_mul_f32_e32 v2, v19, v2
	global_store_dword v[0:1], v2, off offset:384
	v_rcp_f32_e32 v2, v74
	global_store_dword v[0:1], v3, off offset:256
	v_or_b32_e32 v0, 8, v66
	v_ashrrev_i32_e32 v1, 31, v0
	v_lshlrev_b64 v[0:1], 11, v[0:1]
	v_lshl_add_u64 v[0:1], v[64:65], 0, v[0:1]
	v_mul_f32_e32 v3, v4, v2
	global_store_dword v[0:1], v3, off
	v_mul_f32_e32 v3, v52, v2
	global_store_dword v[0:1], v3, off offset:128
	v_mul_f32_e32 v3, v36, v2
	v_mul_f32_e32 v2, v20, v2
	global_store_dword v[0:1], v2, off offset:384
	v_rcp_f32_e32 v2, v75
	global_store_dword v[0:1], v3, off offset:256
	v_or_b32_e32 v0, 9, v66
	v_ashrrev_i32_e32 v1, 31, v0
	v_lshlrev_b64 v[0:1], 11, v[0:1]
	v_lshl_add_u64 v[0:1], v[64:65], 0, v[0:1]
	v_mul_f32_e32 v3, v5, v2
	global_store_dword v[0:1], v3, off
	v_mul_f32_e32 v3, v53, v2
	global_store_dword v[0:1], v3, off offset:128
	v_mul_f32_e32 v3, v37, v2
	v_mul_f32_e32 v2, v21, v2
	global_store_dword v[0:1], v2, off offset:384
	v_rcp_f32_e32 v2, v76
	global_store_dword v[0:1], v3, off offset:256
	v_or_b32_e32 v0, 10, v66
	v_ashrrev_i32_e32 v1, 31, v0
	v_lshlrev_b64 v[0:1], 11, v[0:1]
	v_lshl_add_u64 v[0:1], v[64:65], 0, v[0:1]
	v_mul_f32_e32 v3, v6, v2
	global_store_dword v[0:1], v3, off
	v_mul_f32_e32 v3, v54, v2
	global_store_dword v[0:1], v3, off offset:128
	v_mul_f32_e32 v3, v38, v2
	v_mul_f32_e32 v2, v22, v2
	v_rcp_f32_e32 v6, v77
	global_store_dword v[0:1], v3, off offset:256
	global_store_dword v[0:1], v2, off offset:384
	v_or_b32_e32 v0, 11, v66
	v_ashrrev_i32_e32 v1, 31, v0
	v_lshlrev_b64 v[0:1], 11, v[0:1]
	v_lshl_add_u64 v[4:5], v[64:65], 0, v[0:1]
	v_mul_f32_e32 v0, v7, v6
	global_store_dword v[4:5], v0, off
	v_mul_f32_e32 v0, v55, v6
	global_store_dword v[4:5], v0, off offset:128
	v_mul_f32_e32 v0, v39, v6
	global_store_dword v[4:5], v0, off offset:256
	ds_read_b128 v[0:3], v68 offset:64
	v_mul_f32_e32 v6, v23, v6
	global_store_dword v[4:5], v6, off offset:384
	ds_read_b128 v[4:7], v68 offset:96
	v_or_b32_e32 v16, 16, v66
	s_waitcnt lgkmcnt(0)
; DI unsigned short f2bf(float x) { unsigned u = __float_as_uint(x); u += 0x7fffu + ((u >> 16) & 1u); return (unsigned short)(u >> 16); }
; DI int crow(int r, int hi) { return (r & 3) + 8 * (r >> 2) + 4 * hi; }
; template <int DQK, int MODE, int LDQ, int LDK, int LDV> ...
;     ...
;     for (int r = 0; r < 16; ++r) { const int orow = wid * 32 + crow(r, hi); const float rl = __builtin_amdgcn_rcpf(li_l[crow(r, hi)]);
;         if constexpr (MODE == 0) {
; #pragma unroll
;             for (int d0 = 0; d0 < 4; ++d0) AOb[(size_t)orow * 1024 + d0 * 32 + r32] = f2bf(o[d0][r] * rl);
;         } else if constexpr (MODE == 1) {
; #pragma unroll
;             for (int d0 = 0; d0 < 4; ++d0) S0[(size_t)orow * 512 + d0 * 32 + r32] = o[d0][r] * rl;
; DI void phase4(const Params& p, LAS unsigned char* lds, int wv) {
;     ...
;             __syncthreads();
	v_rcp_f32_e32 v0, v0
	v_ashrrev_i32_e32 v17, 31, v16
	v_lshlrev_b64 v[16:17], 11, v[16:17]
	v_lshl_add_u64 v[16:17], v[64:65], 0, v[16:17]
	v_mul_f32_e32 v8, v8, v0
	global_store_dword v[16:17], v8, off
	v_mul_f32_e32 v8, v56, v0
	global_store_dword v[16:17], v8, off offset:128
	v_mul_f32_e32 v8, v40, v0
	global_store_dword v[16:17], v8, off offset:256
	v_mul_f32_e32 v0, v24, v0
	v_rcp_f32_e32 v8, v1
	global_store_dword v[16:17], v0, off offset:384
	v_or_b32_e32 v0, 17, v66
	v_ashrrev_i32_e32 v1, 31, v0
	v_lshlrev_b64 v[0:1], 11, v[0:1]
	v_lshl_add_u64 v[0:1], v[64:65], 0, v[0:1]
	v_mul_f32_e32 v9, v9, v8
	global_store_dword v[0:1], v9, off
	v_mul_f32_e32 v9, v57, v8
	global_store_dword v[0:1], v9, off offset:128
	v_mul_f32_e32 v9, v41, v8
	v_mul_f32_e32 v8, v25, v8
	v_rcp_f32_e32 v2, v2
	global_store_dword v[0:1], v9, off offset:256
	global_store_dword v[0:1], v8, off offset:384
	v_or_b32_e32 v0, 18, v66
	v_ashrrev_i32_e32 v1, 31, v0
	v_lshlrev_b64 v[0:1], 11, v[0:1]
	v_lshl_add_u64 v[0:1], v[64:65], 0, v[0:1]
	v_mul_f32_e32 v8, v10, v2
	global_store_dword v[0:1], v8, off
	v_mul_f32_e32 v8, v58, v2
	global_store_dword v[0:1], v8, off offset:128
	v_mul_f32_e32 v8, v42, v2
	v_mul_f32_e32 v2, v26, v2
	global_store_dword v[0:1], v2, off offset:384
	v_rcp_f32_e32 v2, v3
	global_store_dword v[0:1], v8, off offset:256
	v_or_b32_e32 v0, 19, v66
	v_ashrrev_i32_e32 v1, 31, v0
	v_lshlrev_b64 v[0:1], 11, v[0:1]
	v_lshl_add_u64 v[0:1], v[64:65], 0, v[0:1]
	v_mul_f32_e32 v3, v11, v2
	global_store_dword v[0:1], v3, off
	v_mul_f32_e32 v3, v59, v2
	global_store_dword v[0:1], v3, off offset:128
	v_mul_f32_e32 v3, v43, v2
	v_mul_f32_e32 v2, v27, v2
	global_store_dword v[0:1], v2, off offset:384
	v_rcp_f32_e32 v2, v4
	global_store_dword v[0:1], v3, off offset:256
	v_or_b32_e32 v0, 24, v66
	v_ashrrev_i32_e32 v1, 31, v0
	v_lshlrev_b64 v[0:1], 11, v[0:1]
	v_lshl_add_u64 v[0:1], v[64:65], 0, v[0:1]
	v_mul_f32_e32 v3, v12, v2
	global_store_dword v[0:1], v3, off
	v_mul_f32_e32 v3, v60, v2
	global_store_dword v[0:1], v3, off offset:128
	v_mul_f32_e32 v3, v44, v2
	v_mul_f32_e32 v2, v28, v2
	global_store_dword v[0:1], v2, off offset:384
	v_rcp_f32_e32 v2, v5
	global_store_dword v[0:1], v3, off offset:256
	v_or_b32_e32 v0, 25, v66
	v_ashrrev_i32_e32 v1, 31, v0
	v_lshlrev_b64 v[0:1], 11, v[0:1]
	v_lshl_add_u64 v[0:1], v[64:65], 0, v[0:1]
	v_mul_f32_e32 v3, v13, v2
	global_store_dword v[0:1], v3, off
	v_mul_f32_e32 v3, v61, v2
	global_store_dword v[0:1], v3, off offset:128
	v_mul_f32_e32 v3, v45, v2
	v_mul_f32_e32 v2, v29, v2
	global_store_dword v[0:1], v2, off offset:384
	v_rcp_f32_e32 v2, v6
	global_store_dword v[0:1], v3, off offset:256
	v_or_b32_e32 v0, 26, v66
	v_ashrrev_i32_e32 v1, 31, v0
	v_lshlrev_b64 v[0:1], 11, v[0:1]
	v_lshl_add_u64 v[0:1], v[64:65], 0, v[0:1]
	v_mul_f32_e32 v3, v14, v2
	global_store_dword v[0:1], v3, off
	v_mul_f32_e32 v3, v62, v2
	global_store_dword v[0:1], v3, off offset:128
	v_mul_f32_e32 v3, v46, v2
	v_mul_f32_e32 v2, v30, v2
	global_store_dword v[0:1], v2, off offset:384
	v_rcp_f32_e32 v2, v7
	global_store_dword v[0:1], v3, off offset:256
	v_or_b32_e32 v0, 27, v66
	v_ashrrev_i32_e32 v1, 31, v0
	v_lshlrev_b64 v[0:1], 11, v[0:1]
	v_lshl_add_u64 v[0:1], v[64:65], 0, v[0:1]
	v_mul_f32_e32 v3, v15, v2
	global_store_dword v[0:1], v3, off
	v_mul_f32_e32 v3, v63, v2
	global_store_dword v[0:1], v3, off offset:128
	v_mul_f32_e32 v3, v47, v2
	v_mul_f32_e32 v2, v31, v2
	global_store_dword v[0:1], v3, off offset:256
	global_store_dword v[0:1], v2, off offset:384
	s_waitcnt vmcnt(0)
	s_barrier
; DI float bf2f(unsigned short h) { return __uint_as_float((unsigned)h << 16); }
; template <int DQK, int MODE, int LDQ, int LDK, int LDV> ...
;     ...
;     int kgo[NKP], vgo[2];
; #pragma unroll
;     for (int i = 0; i < NKP; ++i) { const int L = (wid + 8 * i) * 64 + lane, row = L / CPR, slot = L % CPR, cc = (slot & ~7) | ((slot & 7) ^ ((row >> 1) & 7)); kgo[i] = row * LDK + cc * 8; }
; #pragma unroll
;     for (int i = 0; i < 2; ++i) { const int L = (2 * wid + i) * 64 + lane, st = L >> 5, w5 = L & 31, kk = (st >> 2) * 8 + (w5 >> 2), c = (st & 3) * 32 + (w5 & 3) * 8;
;         const int k = (kk & ~0xC) | ((kk & 4) << 1) | ((kk & 8) >> 1); vgo[i] = k * LDV + c; }
;     ...
;     ATT_DMA_K(0); ATT_DMA_K(1); ATT_DMA_V(0, 0); ATT_DMA_K(2); ATT_DMA_V(1, 1);
;     bf16x8 qr[ND0];
;     { const bf16_t* Qw = Qb + (size_t)(wid * 32 + r32) * LDQ + hi * 8;
; #pragma unroll
;       for (int d0 = 0; d0 < ND0; ++d0) qr[d0] = *(const bf16x8*)(Qw + d0 * 16);
;       if constexpr (MODE == 0) {
;           float ss = 0.f;
; #pragma unroll
;           for (int d0 = 0; d0 < ND0; ++d0)
; #pragma unroll
;               for (int j = 0; j < 8; ++j) { const float f = bf2f((unsigned short)qr[d0][j]); ss += f * f; }
;           ss = swap_sum(ss);
;           const float rstd = rsqrtf(ss * (1.f / DQK) + EPS) * C;
; #pragma unroll
;           for (int d0 = 0; d0 < ND0; ++d0) { const float* g = gq + d0 * 16 + hi * 8;
;               { float f[8]; _Pragma("unroll") for (int j = 0; j < 8; ++j) f[j] = bf2f((unsigned short)qr[d0][j]) * rstd * g[j];
;                 u32x4 w = {cvtpk(f[0], f[1]), cvtpk(f[2], f[3]), cvtpk(f[4], f[5]), cvtpk(f[6], f[7])}; qr[d0] = __builtin_bit_cast(bf16x8, w); asm volatile("" ::: "memory"); } }
;       } }
;     const int qlo = q0 + wid * 32, qpos = qlo + r32;
;     const int tL = MODE == 0 ? 0 : (qlo >= 191 ? (qlo - 127) >> 6 : 0), tR = MODE == 0 ? NT : min(NT, (qlo + 222) >> 6);
;     float fL = 1.f, fR = 1.f; if constexpr (MODE != 0) { fL = __builtin_amdgcn_exp2f(bt[0]); fR = __builtin_amdgcn_exp2f(-bt[448]); }
;     ...
;     const int vbase = (int)(unsigned)(size_t)lds + V_OFF + v_rd_base(lane);
;     ...
;     constexpr int NDA = ND0 > 6 ? 6 : ND0;
;     ...
;     f32x16 pA, pB; bf16x8 pa0, pa1;
;     int v0 = 0, v1 = 1, v2 = 2;
;     ATT_TOP(NKP + 2);
;     { bf16x8 kf[NDA]; k_reads<DQK, 0, NDA>(kf, lds, 0, r32, hi); ATT_LGKM0(); qk_mma<0, NDA>(pA, kf, qr);
	v_mbcnt_lo_u32_b32 v7, -1, 0
	v_mbcnt_hi_u32_b32 v7, -1, v7
	s_mov_b64 s[4:5], 0x880
	v_add_u32_e32 v0, s33, v7
	v_bfe_u32 v4, v0, 2, 2
	v_readfirstlane_b32 s0, v0
	s_ashr_i32 s2, s0, 31
	s_ashr_i32 s1, s0, 6
	v_mov_b32_e32 v1, s0
	v_bfi_b32 v1, s63, v1, v7
	s_lshr_b32 s2, s2, 29
	v_add_u32_e32 v3, s2, v1
	s_lshl_b32 s2, s1, 7
	v_ashrrev_i32_e32 v9, 3, v3
	v_and_b32_e32 v3, 0x1ffffff8, v3
	s_ashr_i32 s3, s2, 4
	v_lshrrev_b32_e32 v0, 1, v0
	v_sub_u32_e32 v1, v1, v3
	v_lshrrev_b32_e32 v3, 1, v9
	v_lshlrev_b32_e32 v18, 3, v7
	s_and_b32 s2, s3, -16
	v_and_b32_e32 v6, 8, v0
	s_lshr_b32 s3, s3, 1
	v_bitop3_b32 v1, v3, v1, 7 bitop3:0x6c
	v_and_b32_e32 v3, 32, v7
	v_and_b32_e32 v5, 24, v18
	s_and_b32 s3, s3, 4
	v_or3_b32 v0, v6, v4, s2
	v_or_b32_e32 v10, v3, v5
	v_or_b32_e32 v0, s3, v0
	v_lshl_or_b32 v96, v0, 11, v10
	v_lshlrev_b32_e32 v0, 11, v9
	v_lshl_add_u32 v0, v1, 3, v0
	v_ashrrev_i32_e32 v1, 31, v0
	v_lshlrev_b64 v[10:11], 1, v[0:1]
	v_lshl_add_u64 v[12:13], s[46:47], 0, v[10:11]
	v_lshl_add_u64 v[12:13], v[12:13], 0, s[4:5]
	s_lshl_b32 s4, s1, 10
	s_add_i32 s94, s4, 0
	s_mov_b32 m0, s94
	v_lshl_add_u64 v[10:11], s[48:49], 0, v[10:11]
	s_mov_b64 s[4:5], 0x40080
	global_load_lds_dwordx4 v[12:13], off
	v_lshl_add_u64 v[12:13], v[10:11], 0, s[4:5]
	s_add_i32 m0, s94, 0x2000
	s_lshl_b32 s4, s1, 11
	v_ashrrev_i32_e32 v97, 31, v96
	global_load_lds_dwordx4 v[12:13], off
	s_add_i32 s6, s4, 0
	v_lshlrev_b64 v[12:13], 1, v[96:97]
	s_add_i32 s48, s6, 0x18000
	v_lshl_add_u64 v[14:15], s[46:47], 0, v[12:13]
	v_lshl_add_u64 v[16:17], v[14:15], 0, s[96:97]
	s_mov_b32 m0, s48
	s_mov_b64 s[4:5], 0xc80
	global_load_lds_dwordx4 v[16:17], off
	v_lshl_add_u64 v[14:15], v[14:15], 0, s[4:5]
	s_add_i32 m0, s6, 0x18400
	s_mov_b64 s[4:5], 0x80080
	v_or_b32_e32 v98, 64, v96
	global_load_lds_dwordx4 v[14:15], off
	v_lshl_add_u64 v[10:11], v[10:11], 0, s[4:5]
	s_add_i32 m0, s94, 0x4000
	v_ashrrev_i32_e32 v99, 31, v98
	global_load_lds_dwordx4 v[10:11], off
	s_add_i32 m0, s6, 0x1c000
	v_lshl_add_u64 v[10:11], s[52:53], 0, v[12:13]
	v_and_b32_e32 v2, 31, v7
	global_load_lds_dwordx4 v[10:11], off
	v_lshl_add_u64 v[10:11], v[98:99], 1, s[52:53]
	s_add_i32 m0, s6, 0x1c400
	s_lshl_b32 s46, s1, 5
	global_load_lds_dwordx4 v[10:11], off
	v_or_b32_e32 v10, s46, v2
	v_ashrrev_i32_e32 v11, 31, v10
	v_bfe_u32 v8, v7, 5, 1
	v_lshlrev_b64 v[10:11], 12, v[10:11]
	v_lshl_add_u64 v[10:11], s[44:45], 0, v[10:11]
	v_lshlrev_b32_e32 v130, 4, v8
	v_lshl_add_u64 v[10:11], v[10:11], 0, v[130:131]
	global_load_dwordx4 v[92:95], v[10:11], off offset:1152
	global_load_dwordx4 v[88:91], v[10:11], off offset:1184
	global_load_dwordx4 v[84:87], v[10:11], off offset:1216
	global_load_dwordx4 v[80:83], v[10:11], off offset:1248
	v_and_b32_e32 v11, 0x70, v18
	v_mov_b32_e32 v9, s88
	v_mov_b32_e32 v10, s81
	v_lshl_add_u32 v114, v2, 7, 0
	v_bitop3_b32 v115, v130, v18, s64 bitop3:0x78
	v_bitop3_b32 v117, v130, v11, 64 bitop3:0x36
	s_add_i32 s4, s46, s89
	ds_read_b32 v9, v9
	ds_read_b32 v10, v10
	s_waitcnt vmcnt(3)
	s_barrier
	v_add_u32_e32 v107, v114, v115
	v_bitop3_b32 v116, v130, v11, 32 bitop3:0x36
	v_add_u32_e32 v109, v114, v117
	v_bitop3_b32 v118, v130, v11, s65 bitop3:0x36
	s_add_i32 s5, s4, 0xffffff81
	v_add_u32_e32 v108, v114, v116
	ds_read_b128 v[12:15], v107
	ds_read_b128 v[16:19], v108
	v_add_u32_e32 v110, v114, v118
	ds_read_b128 v[20:23], v109
	ds_read_b128 v[24:27], v110
	s_ashr_i32 s5, s5, 6
	s_cmpk_gt_i32 s4, 0xbe
	v_or_b32_e32 v111, s4, v2
	s_cselect_b32 s47, s5, 0
	s_addk_i32 s4, 0xde
	s_ashr_i32 s45, s4, 6
	s_waitcnt lgkmcnt(0)
	s_waitcnt vmcnt(0) lgkmcnt(0)
	v_mfma_f32_32x32x16_bf16 v[64:79], v[12:15], v[92:95], 0
	s_cmp_gt_i32 s47, 0
	s_cselect_b64 s[4:5], -1, 0
	s_cmp_lt_i32 s45, 1
	s_cselect_b64 s[6:7], -1, 0
	s_or_b64 s[4:5], s[6:7], s[4:5]
	s_and_b64 vcc, exec, s[4:5]
	v_mfma_f32_32x32x16_bf16 v[64:79], v[16:19], v[88:91], v[64:79]
	v_mfma_f32_32x32x16_bf16 v[64:79], v[20:23], v[84:87], v[64:79]
	v_mfma_f32_32x32x16_bf16 v[64:79], v[24:27], v[80:83], v[64:79]
	s_cbranch_vccnz .LBB0_1948
	v_lshlrev_b32_e32 v8, 2, v8
	v_sub_u32_e32 v8, v8, v111
	v_lshl_add_u32 v8, v8, 2, s88
	ds_read2_b32 v[12:13], v8 offset0:240 offset1:241
	ds_read2_b32 v[14:15], v8 offset0:242 offset1:243
	ds_read2_b32 v[16:17], v8 offset0:248 offset1:249
	ds_read2_b32 v[18:19], v8 offset0:250 offset1:251
	ds_read2_b32 v[20:21], v8 offset0:224 offset1:225
	ds_read2_b32 v[22:23], v8 offset0:226 offset1:227
	ds_read2_b32 v[24:25], v8 offset0:232 offset1:233
	ds_read2_b32 v[26:27], v8 offset0:234 offset1:235
	s_waitcnt lgkmcnt(4)
	v_pk_add_f32 v[78:79], v[78:79], v[18:19]
	v_pk_add_f32 v[76:77], v[76:77], v[16:17]
	v_pk_add_f32 v[74:75], v[74:75], v[14:15]
	v_pk_add_f32 v[72:73], v[72:73], v[12:13]
	s_waitcnt lgkmcnt(0)
	v_pk_add_f32 v[70:71], v[70:71], v[26:27]
	v_pk_add_f32 v[68:69], v[68:69], v[24:25]
	v_pk_add_f32 v[66:67], v[66:67], v[22:23]
	v_pk_add_f32 v[64:65], v[64:65], v[20:21]

; DI void expsum(f32x16& p, float& l_reg, bf16x8& pa0, bf16x8& pa1) {
; #pragma unroll
;     for (int r = 0; r < 16; ++r) p[r] = __builtin_amdgcn_exp2f(p[r]);
;     float ps = 0.f;
; #pragma unroll
;     for (int r = 0; r < 16; ++r) ps += p[r];
;     l_reg += ps; asm volatile("" : "+v"(l_reg));
;     ...
;     ATT_PK4(p, 0, pa0); ATT_PK4(p, 8, pa1);
;     ...
; }
.LBB0_1953:
	s_add_i32 s3, s0, -1
	s_add_i32 s2, s22, 0xffffa000
	s_and_b32 s2, s2, 0x6000
	v_add_u32_e32 v121, s2, v114
	v_add_u32_e32 v122, v121, v115
	v_add_u32_e32 v126, v121, v116
	ds_read_b128 v[122:125], v122 offset:4096
	ds_read_b128 v[132:135], v126 offset:4096
	v_add_u32_e32 v126, v121, v117
	v_add_u32_e32 v121, v121, v118
	s_lshl_b32 s2, s23, 14
	ds_read_b128 v[136:139], v126 offset:4096
	ds_read_b128 v[140:143], v121 offset:4096
	v_add_u32_e32 v121, s2, v106
	ds_read_b64_tr_b16 v[144:145], v121 offset:0
	ds_read_b64_tr_b16 v[146:147], v121 offset:0x800
	ds_read_b64_tr_b16 v[148:149], v121 offset:0x1000
	ds_read_b64_tr_b16 v[150:151], v121 offset:0x1800
	ds_read_b64_tr_b16 v[152:153], v121 offset:0x200
	ds_read_b64_tr_b16 v[154:155], v121 offset:0xa00
	ds_read_b64_tr_b16 v[156:157], v121 offset:0x1200
	ds_read_b64_tr_b16 v[158:159], v121 offset:0x1a00
	s_setprio 2
	ds_read_b64_tr_b16 v[162:163], v121 offset:0x400
	ds_read_b64_tr_b16 v[164:165], v121 offset:0xc00
	ds_read_b64_tr_b16 v[166:167], v121 offset:0x1400
	ds_read_b64_tr_b16 v[168:169], v121 offset:0x1c00
	ds_read_b64_tr_b16 v[170:171], v121 offset:0x600
	ds_read_b64_tr_b16 v[172:173], v121 offset:0xe00
	ds_read_b64_tr_b16 v[174:175], v121 offset:0x1600
	ds_read_b64_tr_b16 v[176:177], v121 offset:0x1e00
	v_exp_f32_e32 v64, v64
	v_exp_f32_e32 v65, v65
	v_exp_f32_e32 v66, v66
	v_exp_f32_e32 v67, v67
	v_exp_f32_e32 v68, v68
	v_exp_f32_e32 v69, v69
	v_add_f32_e32 v126, v65, v64
	v_exp_f32_e32 v70, v70
	v_add_f32_e32 v126, v66, v126
	v_exp_f32_e32 v71, v71
	v_add_f32_e32 v126, v67, v126
	v_exp_f32_e32 v72, v72
	v_add_f32_e32 v126, v68, v126
	v_exp_f32_e32 v73, v73
	v_add_f32_e32 v126, v69, v126
	v_exp_f32_e32 v74, v74
	v_add_f32_e32 v126, v70, v126
	v_exp_f32_e32 v75, v75
	v_add_f32_e32 v126, v71, v126
	v_exp_f32_e32 v76, v76
	v_add_f32_e32 v126, v72, v126
	v_exp_f32_e32 v77, v77
	v_add_f32_e32 v126, v73, v126
	v_exp_f32_e32 v78, v78
	v_add_f32_e32 v126, v74, v126
	v_exp_f32_e32 v79, v79
	v_add_f32_e32 v126, v75, v126
	v_add_f32_e32 v126, v76, v126
	v_add_f32_e32 v126, v77, v126
	v_add_f32_e32 v126, v78, v126
	v_add_f32_e32 v126, v79, v126
	v_add_f32_e32 v120, v126, v120
	v_cvt_pk_bf16_f32 v64, v64, v65
	v_cvt_pk_bf16_f32 v65, v66, v67
	v_cvt_pk_bf16_f32 v66, v68, v69
	v_cvt_pk_bf16_f32 v67, v70, v71
	v_cvt_pk_bf16_f32 v68, v72, v73
	v_cvt_pk_bf16_f32 v69, v74, v75
	v_cvt_pk_bf16_f32 v70, v76, v77
	v_cvt_pk_bf16_f32 v71, v78, v79
	s_nop 0
	v_permlane32_swap_b32_e32 v64, v66
	v_permlane32_swap_b32_e32 v65, v67
	v_permlane32_swap_b32_e32 v68, v70
	v_permlane32_swap_b32_e32 v69, v71
	s_waitcnt lgkmcnt(0)
	s_setprio 1
	v_mfma_f32_32x32x16_bf16 v[0:15], v[64:67], v[144:147], v[0:15]
	s_cmp_lt_i32 s3, s47
	s_cselect_b64 s[74:75], -1, 0
	s_cmp_ge_i32 s3, s52
	s_cselect_b64 s[90:91], -1, 0
	s_or_b64 s[74:75], s[74:75], s[90:91]
	s_and_b64 vcc, exec, s[74:75]
	v_mfma_f32_32x32x16_bf16 v[48:63], v[64:67], v[152:155], v[48:63]
	v_mfma_f32_32x32x16_bf16 v[16:31], v[64:67], v[162:165], v[16:31]
	v_mfma_f32_32x32x16_bf16 v[32:47], v[64:67], v[170:173], v[32:47]
	v_mfma_f32_32x32x16_bf16 v[0:15], v[68:71], v[148:151], v[0:15]
	v_mfma_f32_32x32x16_bf16 v[48:63], v[68:71], v[156:159], v[48:63]
	v_mfma_f32_32x32x16_bf16 v[16:31], v[68:71], v[166:169], v[16:31]
	v_mfma_f32_32x32x16_bf16 v[32:47], v[68:71], v[174:177], v[32:47]
	v_mfma_f32_32x32x16_bf16 v[64:79], v[122:125], v[92:95], 0
	v_mfma_f32_32x32x16_bf16 v[64:79], v[132:135], v[88:91], v[64:79]
	v_mfma_f32_32x32x16_bf16 v[64:79], v[136:139], v[84:87], v[64:79]
	v_mfma_f32_32x32x16_bf16 v[64:79], v[140:143], v[80:83], v[64:79]
	s_setprio 0
	v_add_u32_e32 v122, s7, v119
	s_cbranch_vccnz .LBB0_1955
	v_add_u32_e32 v138, 0x28908, v122
	v_add_u32_e32 v140, 0x28920, v122
	v_add_u32_e32 v142, 0x28928, v122
	v_add_u32_e32 v124, 0x28940, v122
	v_add_u32_e32 v126, 0x28948, v122
	v_add_u32_e32 v132, 0x28960, v122
	v_add_u32_e32 v134, 0x28968, v122
	v_add_u32_e32 v123, 0x28900, v122
	ds_read2_b32 v[124:125], v124 offset1:1
	ds_read2_b32 v[126:127], v126 offset1:1
	ds_read2_b32 v[132:133], v132 offset1:1
	ds_read2_b32 v[134:135], v134 offset1:1
	ds_read2_b32 v[136:137], v123 offset1:1
	ds_read2_b32 v[138:139], v138 offset1:1
	ds_read2_b32 v[140:141], v140 offset1:1
	ds_read2_b32 v[142:143], v142 offset1:1
	s_waitcnt lgkmcnt(0)
	v_pk_add_f32 v[78:79], v[78:79], v[134:135]
	v_pk_add_f32 v[76:77], v[76:77], v[132:133]
	v_pk_add_f32 v[74:75], v[74:75], v[126:127]
	v_pk_add_f32 v[72:73], v[72:73], v[124:125]
	v_pk_add_f32 v[70:71], v[70:71], v[142:143]
	v_pk_add_f32 v[68:69], v[68:69], v[140:141]
	v_pk_add_f32 v[66:67], v[66:67], v[138:139]
	v_pk_add_f32 v[64:65], v[64:65], v[136:137]

; #define SBAR() __builtin_amdgcn_sched_barrier(0)
; DI int v_rd_base(int lane) { return ((lane & 3) << 3) | (((lane >> 2) & 3) << 6) | (((lane >> 4) & 1) << 5) | (((lane >> 5) & 1) << 8); }
; #define ATT_DMA_K(t) do { const bf16_t* kg_ = Kh + (size_t)(t) * 64 * LDK; LAS unsigned char* sb_ = lds + ((t) & 3) * KBUF; \
;     _Pragma("unroll") for (int i_ = 0; i_ < NKP; ++i_) __builtin_amdgcn_global_load_lds((const unsigned*)(kg_ + kgo[i_]), (LAS unsigned*)(sb_ + (wid + 8 * i_) * 1024), 16, 0, 0); } while (0)
; #define ATT_DMA_V(t, vs) do { const bf16_t* vg_ = Vh + (size_t)(t) * 64 * LDV; LAS unsigned char* sb_ = lds + V_OFF + (vs) * SHM_V; \
;     _Pragma("unroll") for (int i_ = 0; i_ < 2; ++i_) __builtin_amdgcn_global_load_lds((const unsigned*)(vg_ + vgo[i_]), (LAS unsigned*)(sb_ + (2 * wid + i_) * 1024), 16, 0, 0); } while (0)
; #define ATT_SEG(t) do { if constexpr (MODE != 0) { if (((t) == tL && tL > 0) || (t) == tR) { const float f_ = (t) == tR ? fR : fL; l_reg *= f_; \
;     _Pragma("unroll") for (int d = 0; d < 4; ++d) _Pragma("unroll") for (int r = 0; r < 16; ++r) o[d][r] *= f_; } } } while (0)
; #define ATT_BIAS(P, t, half) do { if constexpr (MODE != 0) { if ((t) >= tL && (t) < tR) { const LAS float* bp_ = bt + ((t) * 64 + (half) * 32 - qpos + 224 + 4 * hi);     \
;     _Pragma("unroll") for (int r = 0; r < 16; ++r) P[r] += bp_[(r & 3) + 8 * (r >> 2)]; } } } while (0)
; template <int DQK, int MODE, int LDQ, int LDK, int LDV> ...
;     ...
;     const int vbase = (int)(unsigned)(size_t)lds + V_OFF + v_rd_base(lane);
;     ...
;     constexpr int NDA = ND0 > 6 ? 6 : ND0;
;     ...
;     f32x16 pA, pB; bf16x8 pa0, pa1;
;     int v0 = 0, v1 = 1, v2 = 2;
;     ATT_TOP(NKP + 2);
;     { bf16x8 kf[NDA]; k_reads<DQK, 0, NDA>(kf, lds, 0, r32, hi); ATT_LGKM0(); qk_mma<0, NDA>(pA, kf, qr);
;       if constexpr (ND0 > NDA) { bf16x8 kg[ND0 - NDA]; k_reads<DQK, NDA, ND0>(kg, lds, 0, r32, hi); ATT_LGKM0(); qk_mma<NDA, ND0>(pA, kg, qr); }
;       ATT_BIAS(pA, 0, 0); }
;     if (wid >= 4) __builtin_amdgcn_s_setprio(1);
;     for (int j = 0; j < NT; ++j) {
;         if (j + 2 < NT) ATT_TOP(NKP + 2); else ATT_TOP(0);
;         if (j + 3 < NT) ATT_DMA_K(j + 3);
;         if (j + 2 < NT) ATT_DMA_V(j + 2, v2);
;         ATT_SEG(j); SBAR();
;         ATT_STEP(pA, pB, 0, v0, true, 1, j);
;         ATT_STEP(pB, pA, 1, v0, (j + 1 < NT), 0, j + 1);
.LBB0_1961:
	ds_read_b128 v[98:101], v107 offset:12288
	ds_read_b128 v[102:105], v108 offset:12288
	ds_read_b128 v[114:117], v109 offset:12288
	ds_read_b128 v[122:125], v110 offset:12288
	v_lshl_add_u32 v96, s49, 14, v106
	ds_read_b64_tr_b16 v[132:133], v96 offset:0
	ds_read_b64_tr_b16 v[134:135], v96 offset:0x800
	ds_read_b64_tr_b16 v[136:137], v96 offset:0x1000
	ds_read_b64_tr_b16 v[138:139], v96 offset:0x1800
	ds_read_b64_tr_b16 v[140:141], v96 offset:0x200
	ds_read_b64_tr_b16 v[142:143], v96 offset:0xa00
	ds_read_b64_tr_b16 v[144:145], v96 offset:0x1200
	ds_read_b64_tr_b16 v[146:147], v96 offset:0x1a00
	s_setprio 2
	ds_read_b64_tr_b16 v[148:149], v96 offset:0x400
	ds_read_b64_tr_b16 v[150:151], v96 offset:0xc00
	ds_read_b64_tr_b16 v[152:153], v96 offset:0x1400
	ds_read_b64_tr_b16 v[154:155], v96 offset:0x1c00
	ds_read_b64_tr_b16 v[156:157], v96 offset:0x600
	ds_read_b64_tr_b16 v[158:159], v96 offset:0xe00
	ds_read_b64_tr_b16 v[162:163], v96 offset:0x1600
	ds_read_b64_tr_b16 v[164:165], v96 offset:0x1e00
	v_exp_f32_e32 v64, v64
	v_exp_f32_e32 v65, v65
	v_exp_f32_e32 v66, v66
	v_exp_f32_e32 v67, v67
	v_exp_f32_e32 v68, v68
	v_exp_f32_e32 v69, v69
	v_add_f32_e32 v97, v65, v64
	v_exp_f32_e32 v70, v70
	v_add_f32_e32 v97, v66, v97
	v_exp_f32_e32 v71, v71
	v_add_f32_e32 v97, v67, v97
	v_exp_f32_e32 v72, v72
	v_add_f32_e32 v97, v68, v97
	v_exp_f32_e32 v73, v73
	v_add_f32_e32 v97, v69, v97
	v_exp_f32_e32 v74, v74
	v_add_f32_e32 v97, v70, v97
	v_exp_f32_e32 v75, v75
	v_add_f32_e32 v97, v71, v97
	v_exp_f32_e32 v76, v76
	v_add_f32_e32 v97, v72, v97
	v_exp_f32_e32 v77, v77
	v_add_f32_e32 v97, v73, v97
	v_exp_f32_e32 v78, v78
	v_add_f32_e32 v97, v74, v97
	v_exp_f32_e32 v79, v79
	v_add_f32_e32 v97, v75, v97
	v_add_f32_e32 v97, v76, v97
	v_add_f32_e32 v97, v77, v97
	v_add_f32_e32 v97, v78, v97
	v_add_f32_e32 v97, v79, v97
	v_add_f32_e32 v97, v97, v120
	v_cvt_pk_bf16_f32 v64, v64, v65
	v_cvt_pk_bf16_f32 v65, v66, v67
	v_cvt_pk_bf16_f32 v66, v68, v69
	v_cvt_pk_bf16_f32 v67, v70, v71
	v_cvt_pk_bf16_f32 v68, v72, v73
	v_cvt_pk_bf16_f32 v69, v74, v75
	v_cvt_pk_bf16_f32 v70, v76, v77
	v_cvt_pk_bf16_f32 v71, v78, v79
	s_nop 0
	v_permlane32_swap_b32_e32 v64, v66
	v_permlane32_swap_b32_e32 v65, v67
	v_permlane32_swap_b32_e32 v68, v70
	v_permlane32_swap_b32_e32 v69, v71
	s_waitcnt lgkmcnt(0)
	s_setprio 1
	v_mfma_f32_32x32x16_bf16 v[0:15], v[64:67], v[132:135], v[0:15]
	s_cmp_gt_i32 s47, 61
	s_cselect_b64 s[0:1], -1, 0
	s_cmp_lt_i32 s45, 62
	s_cselect_b64 s[2:3], -1, 0
	s_or_b64 s[0:1], s[0:1], s[2:3]
	s_and_b64 vcc, exec, s[0:1]
	v_mfma_f32_32x32x16_bf16 v[48:63], v[64:67], v[140:143], v[48:63]
	v_mfma_f32_32x32x16_bf16 v[16:31], v[64:67], v[148:151], v[16:31]
	v_mfma_f32_32x32x16_bf16 v[32:47], v[64:67], v[156:159], v[32:47]
	v_mfma_f32_32x32x16_bf16 v[0:15], v[68:71], v[136:139], v[0:15]
	v_mfma_f32_32x32x16_bf16 v[48:63], v[68:71], v[144:147], v[48:63]
	v_mfma_f32_32x32x16_bf16 v[16:31], v[68:71], v[152:155], v[16:31]
	v_mfma_f32_32x32x16_bf16 v[32:47], v[68:71], v[162:165], v[32:47]
	s_waitcnt lgkmcnt(0)
	v_mfma_f32_32x32x16_bf16 v[64:79], v[98:101], v[92:95], 0
	v_mfma_f32_32x32x16_bf16 v[64:79], v[102:105], v[88:91], v[64:79]
	v_mfma_f32_32x32x16_bf16 v[64:79], v[114:117], v[84:87], v[64:79]
	v_mfma_f32_32x32x16_bf16 v[64:79], v[122:125], v[80:83], v[64:79]
	s_setprio 0
	s_cbranch_vccnz .LBB0_1963
	v_sub_u32_e32 v98, 0xf40, v111
	v_lshlrev_b32_e32 v98, 2, v98
	v_add3_u32 v98, s88, v98, v130
	v_add_u32_e32 v114, 0x400, v98
	v_add_u32_e32 v116, 0x408, v98
	v_add_u32_e32 v118, 0x420, v98
	v_add_u32_e32 v120, 0x428, v98
	v_add_u32_e32 v99, 0x440, v98
	v_add_u32_e32 v100, 0x448, v98
	v_add_u32_e32 v102, 0x460, v98
	v_add_u32_e32 v104, 0x468, v98
	ds_read2_b32 v[98:99], v99 offset1:1
	ds_read2_b32 v[100:101], v100 offset1:1
	ds_read2_b32 v[102:103], v102 offset1:1
	ds_read2_b32 v[104:105], v104 offset1:1
	ds_read2_b32 v[114:115], v114 offset1:1
	ds_read2_b32 v[116:117], v116 offset1:1
	ds_read2_b32 v[118:119], v118 offset1:1
	ds_read2_b32 v[120:121], v120 offset1:1
	s_waitcnt lgkmcnt(0)
	v_pk_add_f32 v[78:79], v[78:79], v[104:105]
	v_pk_add_f32 v[76:77], v[76:77], v[102:103]
	v_pk_add_f32 v[74:75], v[74:75], v[100:101]
	v_pk_add_f32 v[72:73], v[72:73], v[98:99]
	v_pk_add_f32 v[70:71], v[70:71], v[120:121]
	v_pk_add_f32 v[68:69], v[68:69], v[118:119]
	v_pk_add_f32 v[66:67], v[66:67], v[116:117]
	v_pk_add_f32 v[64:65], v[64:65], v[114:115]
.LBB0_1963:
	ds_read_b128 v[98:101], v107 offset:16384
	ds_read_b128 v[102:105], v108 offset:16384
	ds_read_b128 v[114:117], v109 offset:16384
	ds_read_b128 v[118:121], v110 offset:16384
	ds_read_b64_tr_b16 v[122:123], v96 offset:0x2000
	ds_read_b64_tr_b16 v[124:125], v96 offset:0x2800
	ds_read_b64_tr_b16 v[132:133], v96 offset:0x3000
	ds_read_b64_tr_b16 v[134:135], v96 offset:0x3800
	ds_read_b64_tr_b16 v[136:137], v96 offset:0x2200
	ds_read_b64_tr_b16 v[138:139], v96 offset:0x2a00
	ds_read_b64_tr_b16 v[140:141], v96 offset:0x3200
	ds_read_b64_tr_b16 v[142:143], v96 offset:0x3a00
	s_setprio 2
	ds_read_b64_tr_b16 v[144:145], v96 offset:0x2400
	ds_read_b64_tr_b16 v[146:147], v96 offset:0x2c00
	ds_read_b64_tr_b16 v[148:149], v96 offset:0x3400
	ds_read_b64_tr_b16 v[150:151], v96 offset:0x3c00
	ds_read_b64_tr_b16 v[152:153], v96 offset:0x2600
	ds_read_b64_tr_b16 v[154:155], v96 offset:0x2e00
	ds_read_b64_tr_b16 v[156:157], v96 offset:0x3600
	ds_read_b64_tr_b16 v[158:159], v96 offset:0x3e00
	s_nop 6
	v_exp_f32_e32 v64, v64
	v_exp_f32_e32 v65, v65
	v_exp_f32_e32 v66, v66
	v_exp_f32_e32 v67, v67
	v_exp_f32_e32 v68, v68
	v_exp_f32_e32 v69, v69
	v_add_f32_e32 v96, v65, v64
	v_exp_f32_e32 v70, v70
	v_add_f32_e32 v96, v66, v96
	v_exp_f32_e32 v71, v71
	v_add_f32_e32 v96, v67, v96
	v_exp_f32_e32 v72, v72
	v_add_f32_e32 v96, v68, v96
	v_exp_f32_e32 v73, v73
	v_add_f32_e32 v96, v69, v96
	v_exp_f32_e32 v74, v74
	v_add_f32_e32 v96, v70, v96
	v_exp_f32_e32 v75, v75
	v_add_f32_e32 v96, v71, v96
	v_exp_f32_e32 v76, v76
	v_add_f32_e32 v96, v72, v96
	v_exp_f32_e32 v77, v77
	v_add_f32_e32 v96, v73, v96
	v_exp_f32_e32 v78, v78
	v_add_f32_e32 v96, v74, v96
	v_exp_f32_e32 v79, v79
	v_add_f32_e32 v96, v75, v96
	v_add_f32_e32 v96, v76, v96
	v_add_f32_e32 v96, v77, v96
	v_add_f32_e32 v96, v78, v96
	v_add_f32_e32 v96, v79, v96
	v_add_f32_e32 v96, v97, v96
	v_cvt_pk_bf16_f32 v64, v64, v65
	v_cvt_pk_bf16_f32 v65, v66, v67
	v_cvt_pk_bf16_f32 v66, v68, v69
	v_cvt_pk_bf16_f32 v67, v70, v71
	v_cvt_pk_bf16_f32 v68, v72, v73
	v_cvt_pk_bf16_f32 v69, v74, v75
	v_cvt_pk_bf16_f32 v70, v76, v77
	v_cvt_pk_bf16_f32 v71, v78, v79
	s_nop 0
	v_permlane32_swap_b32_e32 v64, v66
	v_permlane32_swap_b32_e32 v65, v67
	v_permlane32_swap_b32_e32 v68, v70
	v_permlane32_swap_b32_e32 v69, v71
	s_waitcnt lgkmcnt(0)
	s_setprio 1
	s_cmp_lt_u32 s33, 0x100
	s_cbranch_scc1 .Lstg_d1_m61_21
	s_waitcnt vmcnt(0)
	s_barrier

; DI int v_rd_base(int lane) { return ((lane & 3) << 3) | (((lane >> 2) & 3) << 6) | (((lane >> 4) & 1) << 5) | (((lane >> 5) & 1) << 8); }
; template <int DQK, int MODE, int LDQ, int LDK, int LDV> ...
;     ...
;     const int vbase = (int)(unsigned)(size_t)lds + V_OFF + v_rd_base(lane);
;     ...
;     constexpr int NDA = ND0 > 6 ? 6 : ND0;
.LBB0_1967:
	ds_read_b128 v[100:103], v107 offset:20480
	ds_read_b128 v[114:117], v108 offset:20480
	ds_read_b128 v[118:121], v109 offset:20480
	ds_read_b128 v[122:125], v110 offset:20480
	v_add_u32_e32 v98, 0x8000, v106
	ds_read_b64_tr_b16 v[132:133], v98 offset:0
	ds_read_b64_tr_b16 v[134:135], v98 offset:0x800
	ds_read_b64_tr_b16 v[136:137], v98 offset:0x1000
	ds_read_b64_tr_b16 v[138:139], v98 offset:0x1800
	ds_read_b64_tr_b16 v[140:141], v98 offset:0x200
	ds_read_b64_tr_b16 v[142:143], v98 offset:0xa00
	ds_read_b64_tr_b16 v[144:145], v98 offset:0x1200
	ds_read_b64_tr_b16 v[146:147], v98 offset:0x1a00
	s_setprio 2
	ds_read_b64_tr_b16 v[148:149], v98 offset:0x400
	ds_read_b64_tr_b16 v[150:151], v98 offset:0xc00
	ds_read_b64_tr_b16 v[152:153], v98 offset:0x1400
	ds_read_b64_tr_b16 v[154:155], v98 offset:0x1c00
	ds_read_b64_tr_b16 v[156:157], v98 offset:0x600
	ds_read_b64_tr_b16 v[158:159], v98 offset:0xe00
	ds_read_b64_tr_b16 v[162:163], v98 offset:0x1600
	ds_read_b64_tr_b16 v[164:165], v98 offset:0x1e00
	v_exp_f32_e32 v64, v64
	v_exp_f32_e32 v65, v65
	v_exp_f32_e32 v66, v66
	v_exp_f32_e32 v67, v67
	v_exp_f32_e32 v68, v68
	v_exp_f32_e32 v69, v69
	v_add_f32_e32 v99, v65, v64
	v_exp_f32_e32 v70, v70
	v_add_f32_e32 v99, v66, v99
	v_exp_f32_e32 v71, v71
	v_add_f32_e32 v99, v67, v99
	v_exp_f32_e32 v72, v72
	v_add_f32_e32 v99, v68, v99
	v_exp_f32_e32 v73, v73
	v_add_f32_e32 v99, v69, v99
	v_exp_f32_e32 v74, v74
	v_add_f32_e32 v99, v70, v99
	v_exp_f32_e32 v75, v75
	v_add_f32_e32 v99, v71, v99
	v_exp_f32_e32 v76, v76
	v_add_f32_e32 v99, v72, v99
	v_exp_f32_e32 v77, v77
	v_add_f32_e32 v99, v73, v99
	v_exp_f32_e32 v78, v78
	v_add_f32_e32 v99, v74, v99
	v_exp_f32_e32 v79, v79
	v_add_f32_e32 v99, v75, v99
	v_add_f32_e32 v99, v76, v99
	v_add_f32_e32 v99, v77, v99
	v_add_f32_e32 v99, v78, v99
	v_add_f32_e32 v99, v79, v99
	v_add_f32_e32 v96, v99, v96
	v_cvt_pk_bf16_f32 v64, v64, v65
	v_cvt_pk_bf16_f32 v65, v66, v67
	v_cvt_pk_bf16_f32 v66, v68, v69
	v_cvt_pk_bf16_f32 v67, v70, v71
	v_cvt_pk_bf16_f32 v68, v72, v73
	v_cvt_pk_bf16_f32 v69, v74, v75
	v_cvt_pk_bf16_f32 v70, v76, v77
	v_cvt_pk_bf16_f32 v71, v78, v79
	s_nop 0
	v_permlane32_swap_b32_e32 v64, v66
	v_permlane32_swap_b32_e32 v65, v67
	v_permlane32_swap_b32_e32 v68, v70
	v_permlane32_swap_b32_e32 v69, v71
	s_waitcnt lgkmcnt(0)
	s_setprio 1
	v_mfma_f32_32x32x16_bf16 v[0:15], v[64:67], v[132:135], v[0:15]
	s_and_b64 vcc, exec, s[2:3]
	v_mfma_f32_32x32x16_bf16 v[48:63], v[64:67], v[140:143], v[48:63]
	v_mfma_f32_32x32x16_bf16 v[16:31], v[64:67], v[148:151], v[16:31]
	v_mfma_f32_32x32x16_bf16 v[32:47], v[64:67], v[156:159], v[32:47]
	v_mfma_f32_32x32x16_bf16 v[0:15], v[68:71], v[136:139], v[0:15]
	v_mfma_f32_32x32x16_bf16 v[48:63], v[68:71], v[144:147], v[48:63]
	v_mfma_f32_32x32x16_bf16 v[16:31], v[68:71], v[152:155], v[16:31]
	v_mfma_f32_32x32x16_bf16 v[32:47], v[68:71], v[162:165], v[32:47]
	s_waitcnt lgkmcnt(0)
	v_mfma_f32_32x32x16_bf16 v[64:79], v[100:103], v[92:95], 0
	v_mfma_f32_32x32x16_bf16 v[64:79], v[114:117], v[88:91], v[64:79]
	v_mfma_f32_32x32x16_bf16 v[64:79], v[118:121], v[84:87], v[64:79]
	v_mfma_f32_32x32x16_bf16 v[64:79], v[122:125], v[80:83], v[64:79]
	s_setprio 0
	s_cbranch_vccnz .LBB0_1969
	v_add3_u32 v97, s88, v97, v130
	v_add_u32_e32 v118, 0x408, v97
	v_add_u32_e32 v120, 0x420, v97
	v_add_u32_e32 v122, 0x428, v97
	v_add_u32_e32 v100, 0x440, v97
	v_add_u32_e32 v102, 0x448, v97
	v_add_u32_e32 v104, 0x460, v97
	v_add_u32_e32 v99, 0x400, v97
	v_add_u32_e32 v97, 0x468, v97
	ds_read2_b32 v[100:101], v100 offset1:1
	ds_read2_b32 v[102:103], v102 offset1:1
	ds_read2_b32 v[104:105], v104 offset1:1
	ds_read2_b32 v[114:115], v97 offset1:1
	ds_read2_b32 v[116:117], v99 offset1:1
	ds_read2_b32 v[118:119], v118 offset1:1
	ds_read2_b32 v[120:121], v120 offset1:1
	ds_read2_b32 v[122:123], v122 offset1:1
	s_waitcnt lgkmcnt(0)
	v_pk_add_f32 v[78:79], v[78:79], v[114:115]
	v_pk_add_f32 v[76:77], v[76:77], v[104:105]
	v_pk_add_f32 v[74:75], v[74:75], v[102:103]
	v_pk_add_f32 v[72:73], v[72:73], v[100:101]
	v_pk_add_f32 v[70:71], v[70:71], v[122:123]
	v_pk_add_f32 v[68:69], v[68:69], v[120:121]
	v_pk_add_f32 v[66:67], v[66:67], v[118:119]
	v_pk_add_f32 v[64:65], v[64:65], v[116:117]

; #define LAS __attribute__((address_space(3)))
; DI void pv_mma(f32x16* o, const s16x4* vf, bf16x8 pa0, bf16x8 pa1) {
;     ...
; #pragma unroll
;     for (int d0 = 0; d0 < 4; ++d0) {
;         o[d0] = __builtin_amdgcn_mfma_f32_32x32x16_bf16(pa0, ATT_PK(vf[4 * d0], vf[4 * d0 + 1]), o[d0], 0, 0, 0);
;         o[d0] = __builtin_amdgcn_mfma_f32_32x32x16_bf16(pa1, ATT_PK(vf[4 * d0 + 2], vf[4 * d0 + 3]), o[d0], 0, 0, 0); }
;     ...
; }
; template <int DQK, int D0A, int D0B> DI void k_reads(bf16x8* kf, const LAS unsigned char* Ks, int half, int r32, int hi) {
; #pragma unroll
;     for (int d0 = D0A; d0 < D0B; ++d0) kf[d0 - D0A] = *(const LAS bf16x8*)(Ks + half * (32 * DQK * 2) + kswz<DQK>(r32, (d0 * 16 + hi * 8) * 2));
; }
; template <int D0A, int D0B> DI void qk_mma(f32x16& p, const bf16x8* kf, const bf16x8* qr) {
; #pragma unroll
;     for (int d0 = D0A; d0 < D0B; ++d0) {
;         if (d0 == 0) { f32x16 z; _Pragma("unroll") for (int r = 0; r < 16; ++r) z[r] = 0.f; p = __builtin_amdgcn_mfma_f32_32x32x16_bf16(kf[0], qr[0], z, 0, 0, 0); }
;         else p = __builtin_amdgcn_mfma_f32_32x32x16_bf16(kf[d0 - D0A], qr[d0], p, 0, 0, 0); }
; }
.LBB0_1973:
	ds_read_b128 v[98:101], v107 offset:28672
	ds_read_b128 v[102:105], v108 offset:28672
	ds_read_b128 v[112:115], v109 offset:28672
	ds_read_b128 v[108:111], v110 offset:28672
	ds_read_b64_tr_b16 v[116:117], v106 offset:0
	ds_read_b64_tr_b16 v[118:119], v106 offset:0x800
	ds_read_b64_tr_b16 v[120:121], v106 offset:0x1000
	ds_read_b64_tr_b16 v[122:123], v106 offset:0x1800
	ds_read_b64_tr_b16 v[124:125], v106 offset:0x200
	ds_read_b64_tr_b16 v[126:127], v106 offset:0xa00
	ds_read_b64_tr_b16 v[132:133], v106 offset:0x1200
	ds_read_b64_tr_b16 v[134:135], v106 offset:0x1a00
	s_setprio 2
	ds_read_b64_tr_b16 v[136:137], v106 offset:0x400
	ds_read_b64_tr_b16 v[138:139], v106 offset:0xc00
	ds_read_b64_tr_b16 v[140:141], v106 offset:0x1400
	ds_read_b64_tr_b16 v[142:143], v106 offset:0x1c00
	ds_read_b64_tr_b16 v[144:145], v106 offset:0x600
	ds_read_b64_tr_b16 v[146:147], v106 offset:0xe00
	ds_read_b64_tr_b16 v[148:149], v106 offset:0x1600
	ds_read_b64_tr_b16 v[150:151], v106 offset:0x1e00
	v_exp_f32_e32 v64, v64
	v_exp_f32_e32 v65, v65
	v_exp_f32_e32 v66, v66
	v_exp_f32_e32 v67, v67
	v_exp_f32_e32 v68, v68
	v_exp_f32_e32 v69, v69
	v_add_f32_e32 v107, v65, v64
	v_exp_f32_e32 v70, v70
	v_add_f32_e32 v107, v66, v107
	v_exp_f32_e32 v71, v71
	v_add_f32_e32 v107, v67, v107
	v_exp_f32_e32 v72, v72
	v_add_f32_e32 v107, v68, v107
	v_exp_f32_e32 v73, v73
	v_add_f32_e32 v107, v69, v107
	v_exp_f32_e32 v74, v74
	v_add_f32_e32 v107, v70, v107
	v_exp_f32_e32 v75, v75
	v_add_f32_e32 v107, v71, v107
	v_exp_f32_e32 v76, v76
	v_add_f32_e32 v107, v72, v107
	v_exp_f32_e32 v77, v77
	v_add_f32_e32 v107, v73, v107
	v_exp_f32_e32 v78, v78
	v_add_f32_e32 v107, v74, v107
	v_exp_f32_e32 v79, v79
	v_add_f32_e32 v107, v75, v107
	v_add_f32_e32 v107, v76, v107
	v_add_f32_e32 v107, v77, v107
	v_add_f32_e32 v107, v78, v107
	v_add_f32_e32 v107, v79, v107
	v_add_f32_e32 v96, v107, v96
	v_cvt_pk_bf16_f32 v64, v64, v65
	v_cvt_pk_bf16_f32 v65, v66, v67
	v_cvt_pk_bf16_f32 v66, v68, v69
	v_cvt_pk_bf16_f32 v67, v70, v71
	v_cvt_pk_bf16_f32 v68, v72, v73
	v_cvt_pk_bf16_f32 v69, v74, v75
	v_cvt_pk_bf16_f32 v70, v76, v77
	v_cvt_pk_bf16_f32 v71, v78, v79
	s_nop 0
	v_permlane32_swap_b32_e32 v64, v66
	v_permlane32_swap_b32_e32 v65, v67
	v_permlane32_swap_b32_e32 v68, v70
	v_permlane32_swap_b32_e32 v69, v71
	s_waitcnt lgkmcnt(0)
	s_setprio 1
	v_mfma_f32_32x32x16_bf16 v[0:15], v[64:67], v[116:119], v[0:15]
	s_and_b64 vcc, exec, s[2:3]
	v_mfma_f32_32x32x16_bf16 v[48:63], v[64:67], v[124:127], v[48:63]
	v_mfma_f32_32x32x16_bf16 v[16:31], v[64:67], v[136:139], v[16:31]
	v_mfma_f32_32x32x16_bf16 v[32:47], v[64:67], v[144:147], v[32:47]
	v_mfma_f32_32x32x16_bf16 v[0:15], v[68:71], v[120:123], v[0:15]
	v_mfma_f32_32x32x16_bf16 v[48:63], v[68:71], v[132:135], v[48:63]
	v_mfma_f32_32x32x16_bf16 v[16:31], v[68:71], v[140:143], v[16:31]
	v_mfma_f32_32x32x16_bf16 v[32:47], v[68:71], v[148:151], v[32:47]
	s_waitcnt lgkmcnt(0)
	v_mfma_f32_32x32x16_bf16 v[64:79], v[98:101], v[92:95], 0
	v_mfma_f32_32x32x16_bf16 v[64:79], v[102:105], v[88:91], v[64:79]
	v_mfma_f32_32x32x16_bf16 v[64:79], v[112:115], v[84:87], v[64:79]
	v_mfma_f32_32x32x16_bf16 v[64:79], v[108:111], v[80:83], v[64:79]
	s_setprio 0
	s_cbranch_vccnz .LBB0_1975
	v_add3_u32 v80, s88, v97, v130
	v_add_u32_e32 v88, 0x400, v80
	v_add_u32_e32 v90, 0x408, v80
	v_add_u32_e32 v92, 0x420, v80
	v_add_u32_e32 v94, 0x428, v80
	v_add_u32_e32 v81, 0x440, v80
	v_add_u32_e32 v82, 0x448, v80
	v_add_u32_e32 v84, 0x460, v80
	v_add_u32_e32 v86, 0x468, v80
	ds_read2_b32 v[80:81], v81 offset1:1
	ds_read2_b32 v[82:83], v82 offset1:1
	ds_read2_b32 v[84:85], v84 offset1:1
	ds_read2_b32 v[86:87], v86 offset1:1
	ds_read2_b32 v[88:89], v88 offset1:1
	ds_read2_b32 v[90:91], v90 offset1:1
	ds_read2_b32 v[92:93], v92 offset1:1
	ds_read2_b32 v[94:95], v94 offset1:1
	s_waitcnt lgkmcnt(0)
	v_pk_add_f32 v[78:79], v[78:79], v[86:87]
	v_pk_add_f32 v[76:77], v[76:77], v[84:85]
	v_pk_add_f32 v[74:75], v[74:75], v[82:83]
	v_pk_add_f32 v[72:73], v[72:73], v[80:81]
	v_pk_add_f32 v[70:71], v[70:71], v[94:95]
	v_pk_add_f32 v[68:69], v[68:69], v[92:93]
	v_pk_add_f32 v[66:67], v[66:67], v[90:91]
	v_pk_add_f32 v[64:65], v[64:65], v[88:89]
.LBB0_1975:
	s_lshl_b32 s0, s44, 2
	s_add_i32 s0, s0, 0
	s_add_i32 s0, s0, 0x24000
	ds_read_b64_tr_b16 v[80:81], v106 offset:0x2000
	ds_read_b64_tr_b16 v[82:83], v106 offset:0x2800
	ds_read_b64_tr_b16 v[84:85], v106 offset:0x3000
	ds_read_b64_tr_b16 v[86:87], v106 offset:0x3800
	ds_read_b64_tr_b16 v[88:89], v106 offset:0x2200
	ds_read_b64_tr_b16 v[90:91], v106 offset:0x2a00
	ds_read_b64_tr_b16 v[92:93], v106 offset:0x3200
	ds_read_b64_tr_b16 v[94:95], v106 offset:0x3a00
	s_setprio 2
	ds_read_b64_tr_b16 v[98:99], v106 offset:0x2400
	ds_read_b64_tr_b16 v[100:101], v106 offset:0x2c00
	ds_read_b64_tr_b16 v[102:103], v106 offset:0x3400
	ds_read_b64_tr_b16 v[104:105], v106 offset:0x3c00
	ds_read_b64_tr_b16 v[108:109], v106 offset:0x2600
	ds_read_b64_tr_b16 v[110:111], v106 offset:0x2e00
	ds_read_b64_tr_b16 v[112:113], v106 offset:0x3600
	ds_read_b64_tr_b16 v[114:115], v106 offset:0x3e00
	s_nop 7
	v_exp_f32_e32 v97, v64
	v_exp_f32_e32 v65, v65
	v_exp_f32_e32 v106, v66
	v_exp_f32_e32 v67, v67
	v_exp_f32_e32 v68, v68
	v_exp_f32_e32 v69, v69
	v_add_f32_e32 v64, v65, v97
	v_exp_f32_e32 v70, v70
	v_add_f32_e32 v64, v106, v64
	v_exp_f32_e32 v71, v71
	v_add_f32_e32 v64, v67, v64
	v_exp_f32_e32 v72, v72
	v_add_f32_e32 v64, v68, v64
	v_exp_f32_e32 v73, v73
	v_add_f32_e32 v64, v69, v64
	v_exp_f32_e32 v74, v74
	v_add_f32_e32 v64, v70, v64
	v_exp_f32_e32 v75, v75
	v_add_f32_e32 v64, v71, v64
	v_exp_f32_e32 v76, v76
	v_add_f32_e32 v64, v72, v64
	v_exp_f32_e32 v77, v77
	v_add_f32_e32 v64, v73, v64
	v_exp_f32_e32 v78, v78
	v_add_f32_e32 v64, v74, v64
	v_exp_f32_e32 v79, v79
	v_add_f32_e32 v64, v75, v64
	v_add_f32_e32 v64, v76, v64
	v_add_f32_e32 v64, v77, v64
	v_add_f32_e32 v64, v78, v64
	v_add_f32_e32 v64, v79, v64
	v_add_f32_e32 v64, v96, v64
	v_cvt_pk_bf16_f32 v66, v97, v65
	v_cvt_pk_bf16_f32 v67, v106, v67
	v_cvt_pk_bf16_f32 v68, v68, v69
	v_cvt_pk_bf16_f32 v69, v70, v71
	v_cvt_pk_bf16_f32 v70, v72, v73
	v_cvt_pk_bf16_f32 v71, v74, v75
	v_cvt_pk_bf16_f32 v72, v76, v77
	v_cvt_pk_bf16_f32 v73, v78, v79
	s_nop 0
	v_permlane32_swap_b32_e32 v66, v68
	v_permlane32_swap_b32_e32 v67, v69
	v_permlane32_swap_b32_e32 v70, v72
	v_permlane32_swap_b32_e32 v71, v73
	s_waitcnt lgkmcnt(0)
; template <int TAG = 0> DI int fresh_tid(int wv) { int l; asm volatile("v_mbcnt_lo_u32_b32 %0, -1, 0\n\tv_mbcnt_hi_u32_b32 %0, -1, %0 ; site %1" : "=v"(l) : "n"(TAG)); return wv * 64 + l; }
; DI int crow(int r, int hi) { return (r & 3) + 8 * (r >> 2) + 4 * hi; }
; DI float swap_sum(float v) { auto rr = __builtin_amdgcn_permlane32_swap(__float_as_uint(v), __float_as_uint(v), false, false); return __uint_as_float(rr[0]) + __uint_as_float(rr[1]); }
; template <int DQK, int MODE, int LDQ, int LDK, int LDV> ...
;     ...
;     __builtin_amdgcn_s_setprio(0);
;     ...
;     l_reg = swap_sum(l_reg);
;     { const int lane2 = fresh_tid<110 + MODE>(wv) & 63, r32 = lane2 & 31, hi = lane2 >> 5;
;     if (hi == 0) li_l[r32] = l_reg;
;     asm volatile("s_waitcnt lgkmcnt(0)" ::: "memory");
;     float s0v[MODE == 2 ? 16 : 1][4];
;     if constexpr (MODE == 2) {
; #pragma unroll
;         for (int r = 0; r < 16; ++r)
; #pragma unroll
;             for (int d0 = 0; d0 < 4; ++d0) s0v[r][d0] = S0[(size_t)(wid * 32 + crow(r, hi)) * 512 + d0 * 32 + r32];
	s_setprio 1
	v_mfma_f32_32x32x16_bf16 v[0:15], v[66:69], v[80:83], v[0:15]
	v_mfma_f32_32x32x16_bf16 v[48:63], v[66:69], v[88:91], v[48:63]
	v_mfma_f32_32x32x16_bf16 v[16:31], v[66:69], v[98:101], v[16:31]
	v_mfma_f32_32x32x16_bf16 v[32:47], v[66:69], v[108:111], v[32:47]
	v_mfma_f32_32x32x16_bf16 v[0:15], v[70:73], v[84:87], v[0:15]
	v_mfma_f32_32x32x16_bf16 v[48:63], v[70:73], v[92:95], v[48:63]
	v_mfma_f32_32x32x16_bf16 v[16:31], v[70:73], v[102:105], v[16:31]
	v_mfma_f32_32x32x16_bf16 v[32:47], v[70:73], v[112:115], v[32:47]
	s_setprio 0
	v_mov_b32_e32 v66, v64
	v_mbcnt_lo_u32_b32 v65, -1, 0
	v_mbcnt_hi_u32_b32 v65, -1, v65
	s_nop 1
	v_permlane32_swap_b32_e32 v64, v66
	v_and_b32_e32 v114, 63, v65
	v_and_b32_e32 v170, 31, v65
	v_cmp_gt_u32_e32 vcc, 32, v114
	s_and_saveexec_b64 s[2:3], vcc
	v_lshl_add_u32 v67, v170, 2, s0
	v_add_f32_e32 v64, v64, v66
	ds_write_b32 v67, v64
	s_or_b64 exec, exec, s[2:3]
	v_lshrrev_b32_e32 v64, 3, v65
	v_and_b32_e32 v69, 4, v64
	v_or_b32_e32 v102, s46, v69
	v_lshlrev_b32_e32 v130, 2, v170
	v_ashrrev_i32_e32 v103, 31, v102
	v_or_b32_e32 v66, 1, v102
	v_lshl_add_u64 v[92:93], s[54:55], 0, v[130:131]
	v_lshlrev_b64 v[156:157], 11, v[102:103]
	v_ashrrev_i32_e32 v67, 31, v66
	s_waitcnt lgkmcnt(0)
	v_lshl_add_u64 v[64:65], v[92:93], 0, v[156:157]
	v_lshlrev_b64 v[148:149], 11, v[66:67]
	v_lshl_add_u64 v[66:67], v[92:93], 0, v[148:149]
	global_load_dword v110, v[64:65], off
	global_load_dword v111, v[64:65], off offset:128
	global_load_dword v109, v[64:65], off offset:256
	global_load_dword v108, v[64:65], off offset:384
	global_load_dword v106, v[66:67], off
	global_load_dword v107, v[66:67], off offset:128
	global_load_dword v105, v[66:67], off offset:256
	global_load_dword v104, v[66:67], off offset:384
	v_or_b32_e32 v64, 2, v102
	v_or_b32_e32 v66, 3, v102
	v_ashrrev_i32_e32 v65, 31, v64
	v_ashrrev_i32_e32 v67, 31, v66
	v_lshlrev_b64 v[146:147], 11, v[64:65]
	v_lshlrev_b64 v[136:137], 11, v[66:67]
	v_lshl_add_u64 v[64:65], v[92:93], 0, v[146:147]
	v_lshl_add_u64 v[66:67], v[92:93], 0, v[136:137]
	global_load_dword v158, v[64:65], off
	global_load_dword v159, v[64:65], off offset:128
	global_load_dword v155, v[64:65], off offset:256
	global_load_dword v154, v[64:65], off offset:384
	global_load_dword v152, v[66:67], off
	global_load_dword v153, v[66:67], off offset:128
	global_load_dword v151, v[66:67], off offset:256
	global_load_dword v150, v[66:67], off offset:384
	v_or_b32_e32 v64, 8, v102
	v_or_b32_e32 v66, 9, v102
	v_ashrrev_i32_e32 v65, 31, v64
	v_ashrrev_i32_e32 v67, 31, v66
	v_lshlrev_b64 v[134:135], 11, v[64:65]
	v_lshlrev_b64 v[120:121], 11, v[66:67]
	v_lshl_add_u64 v[64:65], v[92:93], 0, v[134:135]
	v_lshl_add_u64 v[66:67], v[92:93], 0, v[120:121]
	global_load_dword v144, v[64:65], off
	global_load_dword v145, v[64:65], off offset:128
	global_load_dword v143, v[64:65], off offset:256
	global_load_dword v142, v[64:65], off offset:384
	global_load_dword v140, v[66:67], off
	global_load_dword v141, v[66:67], off offset:128
	global_load_dword v139, v[66:67], off offset:256
	global_load_dword v138, v[66:67], off offset:384
	v_or_b32_e32 v64, 10, v102
	v_or_b32_e32 v66, 11, v102
	v_ashrrev_i32_e32 v65, 31, v64
	v_ashrrev_i32_e32 v67, 31, v66
	v_lshlrev_b64 v[118:119], 11, v[64:65]
	v_lshlrev_b64 v[90:91], 11, v[66:67]
	v_lshl_add_u64 v[64:65], v[92:93], 0, v[118:119]
	v_lshl_add_u64 v[66:67], v[92:93], 0, v[90:91]
	global_load_dword v132, v[64:65], off
	global_load_dword v133, v[64:65], off offset:128
	global_load_dword v127, v[64:65], off offset:256
	global_load_dword v126, v[64:65], off offset:384
	global_load_dword v124, v[66:67], off
	global_load_dword v125, v[66:67], off offset:128
	global_load_dword v123, v[66:67], off offset:256
	global_load_dword v122, v[66:67], off offset:384
	v_or_b32_e32 v64, 16, v102
	v_or_b32_e32 v66, 17, v102
	v_ashrrev_i32_e32 v65, 31, v64
	v_ashrrev_i32_e32 v67, 31, v66
	v_lshlrev_b64 v[86:87], 11, v[64:65]
	v_lshlrev_b64 v[78:79], 11, v[66:67]
	v_lshl_add_u64 v[64:65], v[92:93], 0, v[86:87]
	v_lshl_add_u64 v[66:67], v[92:93], 0, v[78:79]
	global_load_dword v100, v[64:65], off
	global_load_dword v101, v[64:65], off offset:128
	global_load_dword v99, v[64:65], off offset:256
	global_load_dword v98, v[64:65], off offset:384
	global_load_dword v96, v[66:67], off
	global_load_dword v97, v[66:67], off offset:128
	global_load_dword v95, v[66:67], off offset:256
	global_load_dword v94, v[66:67], off offset:384
	v_or_b32_e32 v64, 18, v102
	v_or_b32_e32 v66, 19, v102
	v_ashrrev_i32_e32 v65, 31, v64
	v_ashrrev_i32_e32 v67, 31, v66
	v_lshlrev_b64 v[76:77], 11, v[64:65]
	v_lshlrev_b64 v[72:73], 11, v[66:67]
	v_lshl_add_u64 v[64:65], v[92:93], 0, v[76:77]
	v_lshl_add_u64 v[66:67], v[92:93], 0, v[72:73]
	v_lshl_add_u32 v169, v69, 2, s0
	global_load_dword v88, v[64:65], off
	global_load_dword v89, v[64:65], off offset:128
	global_load_dword v85, v[64:65], off offset:256
	global_load_dword v84, v[64:65], off offset:384
	global_load_dword v82, v[66:67], off
	global_load_dword v83, v[66:67], off offset:128
	global_load_dword v81, v[66:67], off offset:256
	global_load_dword v80, v[66:67], off offset:384
	ds_read_b128 v[64:67], v169
	v_or_b32_e32 v68, 24, v102
	v_ashrrev_i32_e32 v69, 31, v68
	v_lshlrev_b64 v[74:75], 11, v[68:69]
	ds_read_b128 v[68:71], v169 offset:32
	s_waitcnt lgkmcnt(0)
; DI unsigned short f2bf(float x) { unsigned u = __float_as_uint(x); u += 0x7fffu + ((u >> 16) & 1u); return (unsigned short)(u >> 16); }
; DI float shx(float v, int mask, int lane) { return __int_as_float(__builtin_amdgcn_ds_bpermute((lane ^ mask) << 2, __float_as_int(v))); }
; DI int crow(int r, int hi) { return (r & 3) + 8 * (r >> 2) + 4 * hi; }
; template <int DQK, int MODE, int LDQ, int LDK, int LDV> ...
;     ...
;     for (int r = 0; r < 16; ++r) { const int orow = wid * 32 + crow(r, hi); const float rl = __builtin_amdgcn_rcpf(li_l[crow(r, hi)]);
;         if constexpr (MODE == 0) {
; #pragma unroll
;             for (int d0 = 0; d0 < 4; ++d0) AOb[(size_t)orow * 1024 + d0 * 32 + r32] = f2bf(o[d0][r] * rl);
;         } else if constexpr (MODE == 1) {
; #pragma unroll
;             for (int d0 = 0; d0 < 4; ++d0) S0[(size_t)orow * 512 + d0 * 32 + r32] = o[d0][r] * rl;
;         } else {
;             float v[4]; float ss = 0.f;
; #pragma unroll
;             for (int d0 = 0; d0 < 4; ++d0) { v[d0] = s0v[r][d0] - lam * (o[d0][r] * rl); ss += v[d0] * v[d0]; }
; #pragma unroll
;             for (int mk = 1; mk <= 16; mk <<= 1) ss += shx(ss, mk, lane2);
;             const float rs = rsqrtf(ss * (1.f / 128.f) + EPS) * 0.8f;
; #pragma unroll
;             for (int d0 = 0; d0 < 4; ++d0) AOb[(size_t)orow * 1024 + d0 * 32 + r32] = f2bf(v[d0] * rs * gout[d0 * 32 + r32]);
;         } }
	v_rcp_f32_e32 v64, v64
	v_mov_b32_e32 v162, v0
	v_mov_b32_e32 v163, v48
	v_rcp_f32_e32 v0, v65
	v_pk_mul_f32 v[162:163], v[162:163], v[64:65] op_sel_hi:[1,0]
	v_mov_b32_e32 v48, v1
	v_lshlrev_b32_e32 v166, 2, v114
	v_pk_mul_f32 v[48:49], v[48:49], v[0:1] op_sel_hi:[1,0]
	v_xor_b32_e32 v164, 4, v166
	v_xor_b32_e32 v165, 8, v166
	v_xor_b32_e32 v168, 16, v166
	v_xor_b32_e32 v167, 32, v166
	v_or_b32_e32 v116, 25, v102
	v_ashrrev_i32_e32 v117, 31, v116
	v_xor_b32_e32 v166, 64, v166
	v_lshl_add_u64 v[112:113], v[92:93], 0, v[74:75]
	s_add_u32 s1, s60, s58
	s_mov_b32 s0, 0x358637bd
	s_addc_u32 s3, s61, s59
	s_lshl_b32 s2, s87, 1
	s_add_u32 s2, s1, s2
	s_addc_u32 s3, s3, 0
	s_waitcnt vmcnt(0)
	v_pk_fma_f32 v[172:173], v[128:129], v[162:163], v[110:111] neg_lo:[1,0,0] neg_hi:[1,0,0]
	v_mov_b32_e32 v162, v32
	v_mov_b32_e32 v163, v16
	v_pk_mul_f32 v[162:163], v[162:163], v[64:65] op_sel_hi:[1,0]
	v_mov_b32_e32 v16, v33
	v_pk_fma_f32 v[174:175], v[128:129], v[162:163], v[108:109] neg_lo:[1,0,0] neg_hi:[1,0,0]
	global_load_dword v163, v130, s[50:51]
	global_load_dword v162, v130, s[50:51] offset:128
	global_load_dword v161, v130, s[50:51] offset:256
	s_nop 0
	global_load_dword v130, v130, s[50:51] offset:384
	v_pk_fma_f32 v[176:177], v[128:129], v[48:49], v[106:107] neg_lo:[1,0,0] neg_hi:[1,0,0]
	v_pk_mul_f32 v[0:1], v[16:17], v[0:1] op_sel_hi:[1,0]
	v_pk_mul_f32 v[110:111], v[172:173], v[172:173]
	v_pk_mul_f32 v[48:49], v[176:177], v[176:177]
	v_pk_fma_f32 v[0:1], v[128:129], v[0:1], v[104:105] neg_lo:[1,0,0] neg_hi:[1,0,0]
	v_pk_mul_f32 v[108:109], v[174:175], v[174:175]
	v_pk_mul_f32 v[16:17], v[0:1], v[0:1]
	v_mov_b32_e32 v32, v48
	v_mov_b32_e32 v33, v110
	v_mov_b32_e32 v110, v49
	v_pk_add_f32 v[32:33], v[32:33], v[110:111]
	v_mov_b32_e32 v48, v17
	v_mov_b32_e32 v49, v109
	v_pk_add_f32 v[32:33], v[48:49], v[32:33]
	v_mov_b32_e32 v17, v108
	v_pk_add_f32 v[16:17], v[16:17], v[32:33]
	ds_bpermute_b32 v33, v164, v17
	ds_bpermute_b32 v32, v164, v16
	v_lshlrev_b64 v[64:65], 11, v[116:117]
	v_lshl_add_u64 v[48:49], v[92:93], 0, v[64:65]
	global_load_dword v116, v[112:113], off
	global_load_dword v117, v[112:113], off offset:128
	global_load_dword v115, v[112:113], off offset:256
	global_load_dword v114, v[112:113], off offset:384
	s_nop 0
	global_load_dword v112, v[48:49], off
	global_load_dword v113, v[48:49], off offset:128
	global_load_dword v111, v[48:49], off offset:256
	global_load_dword v110, v[48:49], off offset:384
	v_or_b32_e32 v48, 26, v102
	s_waitcnt lgkmcnt(0)
	v_pk_add_f32 v[16:17], v[16:17], v[32:33]
	ds_bpermute_b32 v33, v165, v17
	ds_bpermute_b32 v32, v165, v16
	v_or_b32_e32 v102, 27, v102
	v_ashrrev_i32_e32 v49, 31, v48
	v_ashrrev_i32_e32 v103, 31, v102
	v_lshlrev_b64 v[48:49], 11, v[48:49]
	s_waitcnt lgkmcnt(0)
	v_pk_add_f32 v[16:17], v[16:17], v[32:33]
	ds_bpermute_b32 v33, v168, v17
	ds_bpermute_b32 v32, v168, v16
	v_lshl_add_u64 v[104:105], v[92:93], 0, v[48:49]
	v_lshlrev_b32_e32 v170, 1, v170
	v_mov_b32_e32 v171, v131
	v_rcp_f32_e32 v66, v66
	s_waitcnt lgkmcnt(0)
	v_pk_add_f32 v[32:33], v[16:17], v[32:33]
	ds_bpermute_b32 v107, v167, v33
	ds_bpermute_b32 v106, v167, v32
	v_lshlrev_b64 v[16:17], 11, v[102:103]
	v_lshl_add_u64 v[92:93], v[92:93], 0, v[16:17]
	s_waitcnt lgkmcnt(0)
	v_pk_add_f32 v[32:33], v[32:33], v[106:107]
	ds_bpermute_b32 v179, v166, v33
	ds_bpermute_b32 v178, v166, v32
	global_load_dword v108, v[104:105], off
	global_load_dword v109, v[104:105], off offset:128
	global_load_dword v107, v[104:105], off offset:256
	global_load_dword v106, v[104:105], off offset:384
	s_nop 0
	global_load_dword v104, v[92:93], off
	global_load_dword v105, v[92:93], off offset:128
	global_load_dword v103, v[92:93], off offset:256
	global_load_dword v102, v[92:93], off offset:384
	v_mov_b64_e32 v[92:93], s[0:1]
	s_waitcnt lgkmcnt(0)
	v_pk_add_f32 v[32:33], v[32:33], v[178:179]
	s_nop 0
	v_pk_fma_f32 v[178:179], v[32:33], s[24:25], v[92:93] op_sel_hi:[1,0,0]
	s_nop 0
	v_mul_f32_e32 v32, 0x4b800000, v179
	v_cmp_gt_f32_e32 vcc, s67, v179
	s_nop 1
	v_cndmask_b32_e32 v32, v179, v32, vcc
	v_rsq_f32_e32 v179, v32
	v_lshl_add_u64 v[32:33], s[2:3], 0, v[170:171]
	v_lshl_add_u64 v[156:157], v[32:33], 0, v[156:157]
	v_lshl_add_u64 v[148:149], v[32:33], 0, v[148:149]
	v_mul_f32_e32 v170, 0x45800000, v179
	v_cndmask_b32_e32 v170, v179, v170, vcc
	v_mul_f32_e32 v170, 0x3f4ccccd, v170
	v_mul_f32_e32 v171, v172, v170
	v_cmp_gt_f32_e32 vcc, s67, v178
	s_mov_b64 s[2:3], 0
	s_waitcnt vmcnt(19)
	v_mul_f32_e32 v171, v163, v171
	v_bfe_u32 v172, v171, 16, 1
	v_add3_u32 v171, v171, v172, s68
	global_store_short_d16_hi v[156:157], v171, off offset:1024
	v_mul_f32_e32 v171, v173, v170
	s_waitcnt vmcnt(19)
	v_mul_f32_e32 v171, v162, v171
	v_bfe_u32 v172, v171, 16, 1
	v_add3_u32 v171, v171, v172, s68
	global_store_short_d16_hi v[156:157], v171, off offset:1088
	v_mul_f32_e32 v171, v175, v170
	s_waitcnt vmcnt(19)
	v_mul_f32_e32 v171, v161, v171
	v_bfe_u32 v172, v171, 16, 1
	v_add3_u32 v171, v171, v172, s68
	global_store_short_d16_hi v[156:157], v171, off offset:1152
	v_mul_f32_e32 v171, 0x4b800000, v178
	v_cndmask_b32_e32 v171, v178, v171, vcc
	v_mul_f32_e32 v170, v174, v170
	v_rsq_f32_e32 v171, v171
	s_waitcnt vmcnt(19)
; DI unsigned short f2bf(float x) { unsigned u = __float_as_uint(x); u += 0x7fffu + ((u >> 16) & 1u); return (unsigned short)(u >> 16); }
; DI float shx(float v, int mask, int lane) { return __int_as_float(__builtin_amdgcn_ds_bpermute((lane ^ mask) << 2, __float_as_int(v))); }
; DI int crow(int r, int hi) { return (r & 3) + 8 * (r >> 2) + 4 * hi; }
; template <int DQK, int MODE, int LDQ, int LDK, int LDV> ...
;     ...
;     for (int r = 0; r < 16; ++r) { const int orow = wid * 32 + crow(r, hi); const float rl = __builtin_amdgcn_rcpf(li_l[crow(r, hi)]);
;         if constexpr (MODE == 0) {
; #pragma unroll
;             for (int d0 = 0; d0 < 4; ++d0) AOb[(size_t)orow * 1024 + d0 * 32 + r32] = f2bf(o[d0][r] * rl);
;         } else if constexpr (MODE == 1) {
; #pragma unroll
;             for (int d0 = 0; d0 < 4; ++d0) S0[(size_t)orow * 512 + d0 * 32 + r32] = o[d0][r] * rl;
;         } else {
;             float v[4]; float ss = 0.f;
; #pragma unroll
;             for (int d0 = 0; d0 < 4; ++d0) { v[d0] = s0v[r][d0] - lam * (o[d0][r] * rl); ss += v[d0] * v[d0]; }
; #pragma unroll
;             for (int mk = 1; mk <= 16; mk <<= 1) ss += shx(ss, mk, lane2);
;             const float rs = rsqrtf(ss * (1.f / 128.f) + EPS) * 0.8f;
; #pragma unroll
;             for (int d0 = 0; d0 < 4; ++d0) AOb[(size_t)orow * 1024 + d0 * 32 + r32] = f2bf(v[d0] * rs * gout[d0 * 32 + r32]);
;         } }
	v_mul_f32_e32 v170, v130, v170
	v_bfe_u32 v172, v170, 16, 1
	v_add3_u32 v170, v170, v172, s68
	global_store_short_d16_hi v[156:157], v170, off offset:1216
	v_mul_f32_e32 v156, 0x45800000, v171
	v_cndmask_b32_e32 v172, v171, v156, vcc
	v_mov_b32_e32 v156, v2
	v_rcp_f32_e32 v2, v67
	v_mov_b32_e32 v157, v50
	v_mov_b32_e32 v50, v3
	v_pk_mul_f32 v[156:157], v[156:157], v[66:67] op_sel_hi:[1,0]
	v_mov_b32_e32 v170, v34
	v_mov_b32_e32 v171, v18
	v_pk_mul_f32 v[50:51], v[50:51], v[2:3] op_sel_hi:[1,0]
	v_mov_b32_e32 v18, v35
	v_pk_fma_f32 v[156:157], v[128:129], v[156:157], v[158:159] neg_lo:[1,0,0] neg_hi:[1,0,0]
	v_pk_mul_f32 v[170:171], v[170:171], v[66:67] op_sel_hi:[1,0]
	v_pk_fma_f32 v[50:51], v[128:129], v[50:51], v[152:153] neg_lo:[1,0,0] neg_hi:[1,0,0]
	v_pk_mul_f32 v[2:3], v[18:19], v[2:3] op_sel_hi:[1,0]
	v_pk_mul_f32 v[158:159], v[156:157], v[156:157]
	v_pk_fma_f32 v[66:67], v[128:129], v[170:171], v[154:155] neg_lo:[1,0,0] neg_hi:[1,0,0]
	v_pk_mul_f32 v[152:153], v[50:51], v[50:51]
	v_pk_fma_f32 v[2:3], v[128:129], v[2:3], v[150:151] neg_lo:[1,0,0] neg_hi:[1,0,0]
	v_pk_mul_f32 v[154:155], v[66:67], v[66:67]
	v_pk_mul_f32 v[18:19], v[2:3], v[2:3]
	v_mov_b32_e32 v34, v152
	v_mov_b32_e32 v35, v158
	v_mov_b32_e32 v158, v153
	v_pk_add_f32 v[34:35], v[34:35], v[158:159]
	v_mov_b32_e32 v150, v19
	v_mov_b32_e32 v151, v155
	v_pk_add_f32 v[34:35], v[150:151], v[34:35]
	v_mov_b32_e32 v19, v154
	v_pk_add_f32 v[18:19], v[18:19], v[34:35]
	ds_bpermute_b32 v35, v164, v19
	ds_bpermute_b32 v34, v164, v18
	v_mul_f32_e32 v150, 0x3f4ccccd, v172
	v_mul_f32_e32 v151, v176, v150
	v_mul_f32_e32 v151, v163, v151
	v_bfe_u32 v152, v151, 16, 1
	s_waitcnt lgkmcnt(0)
	v_pk_add_f32 v[18:19], v[18:19], v[34:35]
	ds_bpermute_b32 v35, v165, v19
	ds_bpermute_b32 v34, v165, v18
	v_add3_u32 v151, v151, v152, s68
	global_store_short_d16_hi v[148:149], v151, off offset:1024
	v_mul_f32_e32 v151, v177, v150
	v_mul_f32_e32 v151, v162, v151
	s_waitcnt lgkmcnt(0)
	v_pk_add_f32 v[18:19], v[18:19], v[34:35]
	ds_bpermute_b32 v35, v168, v19
	ds_bpermute_b32 v34, v168, v18
	v_bfe_u32 v152, v151, 16, 1
	v_mul_f32_e32 v1, v1, v150
	v_add3_u32 v151, v151, v152, s68
	v_mul_f32_e32 v1, v161, v1
	s_waitcnt lgkmcnt(0)
	v_pk_add_f32 v[18:19], v[18:19], v[34:35]
	ds_bpermute_b32 v35, v167, v19
	ds_bpermute_b32 v34, v167, v18
	global_store_short_d16_hi v[148:149], v151, off offset:1088
	v_bfe_u32 v151, v1, 16, 1
	v_add3_u32 v1, v1, v151, s68
	v_mul_f32_e32 v0, v0, v150
	s_waitcnt lgkmcnt(0)
	v_pk_add_f32 v[18:19], v[18:19], v[34:35]
	ds_bpermute_b32 v35, v166, v19
	ds_bpermute_b32 v34, v166, v18
	global_store_short_d16_hi v[148:149], v1, off offset:1152
	v_mul_f32_e32 v150, v130, v0
	v_bfe_u32 v151, v150, 16, 1
	s_waitcnt lgkmcnt(0)
	v_pk_add_f32 v[0:1], v[18:19], v[34:35]
	s_nop 0
	v_pk_fma_f32 v[0:1], v[0:1], s[24:25], v[92:93] op_sel_hi:[1,0,0]
	s_nop 0
	v_mul_f32_e32 v18, 0x4b800000, v1
	v_cmp_gt_f32_e32 vcc, s67, v1
	s_nop 1
	v_cndmask_b32_e32 v1, v1, v18, vcc
	v_rsq_f32_e32 v1, v1
	v_add3_u32 v18, v150, v151, s68
	global_store_short_d16_hi v[148:149], v18, off offset:1216
	v_lshl_add_u64 v[18:19], v[32:33], 0, v[146:147]
	v_mul_f32_e32 v34, 0x45800000, v1
	v_cndmask_b32_e32 v1, v1, v34, vcc
	v_mul_f32_e32 v1, 0x3f4ccccd, v1
	v_mul_f32_e32 v34, v156, v1
	v_mul_f32_e32 v34, v163, v34
	v_bfe_u32 v35, v34, 16, 1
	v_add3_u32 v34, v34, v35, s68
	global_store_short_d16_hi v[18:19], v34, off offset:1024
	v_mul_f32_e32 v34, v157, v1
	v_mul_f32_e32 v34, v162, v34
	v_bfe_u32 v35, v34, 16, 1
	v_add3_u32 v34, v34, v35, s68
	global_store_short_d16_hi v[18:19], v34, off offset:1088
	v_mul_f32_e32 v34, v67, v1
	v_mul_f32_e32 v34, v161, v34
	v_bfe_u32 v35, v34, 16, 1
	v_add3_u32 v34, v34, v35, s68
	global_store_short_d16_hi v[18:19], v34, off offset:1152
	v_mul_f32_e32 v1, v66, v1
	v_mul_f32_e32 v34, 0x4b800000, v0
	v_cmp_gt_f32_e32 vcc, s67, v0
	v_mul_f32_e32 v1, v130, v1
	v_mov_b32_e32 v66, v36
	v_cndmask_b32_e32 v0, v0, v34, vcc
	v_rsq_f32_e32 v34, v0
	v_bfe_u32 v0, v1, 16, 1
	v_add3_u32 v0, v1, v0, s68
	global_store_short_d16_hi v[18:19], v0, off offset:1216
	v_rcp_f32_e32 v0, v68
	v_mov_b32_e32 v18, v4
	v_rcp_f32_e32 v4, v69
	v_mul_f32_e32 v1, 0x45800000, v34
	v_mov_b32_e32 v19, v52
	v_mov_b32_e32 v52, v5
	v_pk_mul_f32 v[18:19], v[18:19], v[0:1] op_sel_hi:[1,0]
	v_mov_b32_e32 v67, v20
	v_pk_mul_f32 v[52:53], v[52:53], v[4:5] op_sel_hi:[1,0]
	v_mov_b32_e32 v20, v37
	v_cndmask_b32_e32 v146, v34, v1, vcc
	v_pk_fma_f32 v[18:19], v[128:129], v[18:19], v[144:145] neg_lo:[1,0,0] neg_hi:[1,0,0]
	v_pk_mul_f32 v[0:1], v[66:67], v[0:1] op_sel_hi:[1,0]
	v_pk_fma_f32 v[52:53], v[128:129], v[52:53], v[140:141] neg_lo:[1,0,0] neg_hi:[1,0,0]
	v_pk_mul_f32 v[4:5], v[20:21], v[4:5] op_sel_hi:[1,0]
	v_pk_mul_f32 v[34:35], v[18:19], v[18:19]
	v_pk_fma_f32 v[0:1], v[128:129], v[0:1], v[142:143] neg_lo:[1,0,0] neg_hi:[1,0,0]
	v_pk_mul_f32 v[68:69], v[52:53], v[52:53]
	v_pk_fma_f32 v[4:5], v[128:129], v[4:5], v[138:139] neg_lo:[1,0,0] neg_hi:[1,0,0]
	v_pk_mul_f32 v[66:67], v[0:1], v[0:1]
	v_pk_mul_f32 v[20:21], v[4:5], v[4:5]
	v_mov_b32_e32 v36, v68
	v_mov_b32_e32 v37, v34
	v_mov_b32_e32 v34, v69
	v_pk_add_f32 v[34:35], v[36:37], v[34:35]
	v_mov_b32_e32 v36, v21
	v_mov_b32_e32 v37, v67
	v_pk_add_f32 v[34:35], v[36:37], v[34:35]
	v_mov_b32_e32 v21, v66
	v_pk_add_f32 v[20:21], v[20:21], v[34:35]
	ds_bpermute_b32 v35, v164, v21
	ds_bpermute_b32 v34, v164, v20
	v_mul_f32_e32 v66, 0x3f4ccccd, v146
	v_mul_f32_e32 v50, v50, v66
	v_mul_f32_e32 v50, v163, v50
	v_bfe_u32 v67, v50, 16, 1
	s_waitcnt lgkmcnt(0)
; DI unsigned short f2bf(float x) { unsigned u = __float_as_uint(x); u += 0x7fffu + ((u >> 16) & 1u); return (unsigned short)(u >> 16); }
; DI float shx(float v, int mask, int lane) { return __int_as_float(__builtin_amdgcn_ds_bpermute((lane ^ mask) << 2, __float_as_int(v))); }
; template <int DQK, int MODE, int LDQ, int LDK, int LDV> ...
;     ...
;         } else {
;             float v[4]; float ss = 0.f;
; #pragma unroll
;             for (int d0 = 0; d0 < 4; ++d0) { v[d0] = s0v[r][d0] - lam * (o[d0][r] * rl); ss += v[d0] * v[d0]; }
; #pragma unroll
;             for (int mk = 1; mk <= 16; mk <<= 1) ss += shx(ss, mk, lane2);
;             const float rs = rsqrtf(ss * (1.f / 128.f) + EPS) * 0.8f;
; #pragma unroll
;             for (int d0 = 0; d0 < 4; ++d0) AOb[(size_t)orow * 1024 + d0 * 32 + r32] = f2bf(v[d0] * rs * gout[d0 * 32 + r32]);
	v_pk_add_f32 v[20:21], v[20:21], v[34:35]
	ds_bpermute_b32 v35, v165, v21
	ds_bpermute_b32 v34, v165, v20
	v_lshl_add_u64 v[36:37], v[32:33], 0, v[136:137]
	v_add3_u32 v50, v50, v67, s68
	global_store_short_d16_hi v[36:37], v50, off offset:1024
	v_mul_f32_e32 v50, v51, v66
	s_waitcnt lgkmcnt(0)
	v_pk_add_f32 v[20:21], v[20:21], v[34:35]
	ds_bpermute_b32 v35, v168, v21
	ds_bpermute_b32 v34, v168, v20
	v_mul_f32_e32 v50, v162, v50
	v_bfe_u32 v51, v50, 16, 1
	v_mul_f32_e32 v3, v3, v66
	v_add3_u32 v50, v50, v51, s68
	s_waitcnt lgkmcnt(0)
	v_pk_add_f32 v[20:21], v[20:21], v[34:35]
	ds_bpermute_b32 v35, v167, v21
	ds_bpermute_b32 v34, v167, v20
	v_mul_f32_e32 v3, v161, v3
	global_store_short_d16_hi v[36:37], v50, off offset:1088
	v_bfe_u32 v50, v3, 16, 1
	v_add3_u32 v3, v3, v50, s68
	s_waitcnt lgkmcnt(0)
	v_pk_add_f32 v[20:21], v[20:21], v[34:35]
	ds_bpermute_b32 v35, v166, v21
	ds_bpermute_b32 v34, v166, v20
	v_mul_f32_e32 v2, v2, v66
	global_store_short_d16_hi v[36:37], v3, off offset:1152
	v_mul_f32_e32 v50, v130, v2
	v_bfe_u32 v51, v50, 16, 1
	s_waitcnt lgkmcnt(0)
	v_pk_add_f32 v[2:3], v[20:21], v[34:35]
	s_nop 0
	v_pk_fma_f32 v[2:3], v[2:3], s[24:25], v[92:93] op_sel_hi:[1,0,0]
	s_nop 0
	v_mul_f32_e32 v20, 0x4b800000, v3
	v_cmp_gt_f32_e32 vcc, s67, v3
	s_nop 1
	v_cndmask_b32_e32 v3, v3, v20, vcc
	v_rsq_f32_e32 v3, v3
	v_add3_u32 v20, v50, v51, s68
	global_store_short_d16_hi v[36:37], v20, off offset:1216
	v_lshl_add_u64 v[20:21], v[32:33], 0, v[134:135]
	v_mul_f32_e32 v34, 0x45800000, v3
	v_cndmask_b32_e32 v3, v3, v34, vcc
	v_mul_f32_e32 v3, 0x3f4ccccd, v3
	v_mul_f32_e32 v18, v18, v3
	v_mul_f32_e32 v18, v163, v18
	v_bfe_u32 v34, v18, 16, 1
	v_add3_u32 v18, v18, v34, s68
	global_store_short_d16_hi v[20:21], v18, off offset:1024
	v_mul_f32_e32 v18, v19, v3
	v_mul_f32_e32 v18, v162, v18
	v_bfe_u32 v19, v18, 16, 1
	v_mul_f32_e32 v1, v1, v3
	v_add3_u32 v18, v18, v19, s68
	v_mul_f32_e32 v1, v161, v1
	global_store_short_d16_hi v[20:21], v18, off offset:1088
	v_bfe_u32 v18, v1, 16, 1
	v_add3_u32 v1, v1, v18, s68
	global_store_short_d16_hi v[20:21], v1, off offset:1152
	v_mul_f32_e32 v1, 0x4b800000, v2
	v_cmp_gt_f32_e32 vcc, s67, v2
	v_mul_f32_e32 v0, v0, v3
	v_mul_f32_e32 v0, v130, v0
	v_cndmask_b32_e32 v1, v2, v1, vcc
	v_rsq_f32_e32 v1, v1
	v_bfe_u32 v2, v0, 16, 1
	v_add3_u32 v0, v0, v2, s68
	global_store_short_d16_hi v[20:21], v0, off offset:1216
	v_mul_f32_e32 v2, 0x45800000, v1
	v_rcp_f32_e32 v0, v70
	v_cndmask_b32_e32 v66, v1, v2, vcc
	v_mov_b32_e32 v2, v6
	v_rcp_f32_e32 v6, v71
	v_mov_b32_e32 v3, v54
	v_mov_b32_e32 v18, v38
	v_mov_b32_e32 v19, v22
	v_mov_b32_e32 v54, v7
	v_pk_mul_f32 v[2:3], v[2:3], v[0:1] op_sel_hi:[1,0]
	v_pk_mul_f32 v[0:1], v[18:19], v[0:1] op_sel_hi:[1,0]
	v_pk_mul_f32 v[18:19], v[54:55], v[6:7] op_sel_hi:[1,0]
	v_mov_b32_e32 v22, v39
	v_pk_fma_f32 v[2:3], v[128:129], v[2:3], v[132:133] neg_lo:[1,0,0] neg_hi:[1,0,0]
	v_pk_fma_f32 v[20:21], v[128:129], v[18:19], v[124:125] neg_lo:[1,0,0] neg_hi:[1,0,0]
	v_pk_mul_f32 v[6:7], v[22:23], v[6:7] op_sel_hi:[1,0]
	v_pk_mul_f32 v[34:35], v[2:3], v[2:3]
	v_pk_fma_f32 v[0:1], v[128:129], v[0:1], v[126:127] neg_lo:[1,0,0] neg_hi:[1,0,0]
	v_pk_mul_f32 v[50:51], v[20:21], v[20:21]
	v_pk_fma_f32 v[18:19], v[128:129], v[6:7], v[122:123] neg_lo:[1,0,0] neg_hi:[1,0,0]
	v_pk_mul_f32 v[36:37], v[0:1], v[0:1]
	v_pk_mul_f32 v[6:7], v[18:19], v[18:19]
	v_mov_b32_e32 v22, v50
	v_mov_b32_e32 v23, v34
	v_mov_b32_e32 v34, v51
	v_pk_add_f32 v[22:23], v[22:23], v[34:35]
	v_mov_b32_e32 v34, v7
	v_mov_b32_e32 v35, v37
	v_pk_add_f32 v[22:23], v[34:35], v[22:23]
	v_mov_b32_e32 v7, v36
	v_pk_add_f32 v[6:7], v[6:7], v[22:23]
	ds_bpermute_b32 v23, v164, v7
	ds_bpermute_b32 v22, v164, v6
	v_mul_f32_e32 v36, 0x3f4ccccd, v66
	v_mul_f32_e32 v37, v52, v36
	v_mul_f32_e32 v37, v163, v37
	v_bfe_u32 v38, v37, 16, 1
	s_waitcnt lgkmcnt(0)
	v_pk_add_f32 v[6:7], v[6:7], v[22:23]
	ds_bpermute_b32 v23, v165, v7
	ds_bpermute_b32 v22, v165, v6
	v_lshl_add_u64 v[34:35], v[32:33], 0, v[120:121]
	v_add3_u32 v37, v37, v38, s68
	global_store_short_d16_hi v[34:35], v37, off offset:1024
	v_mul_f32_e32 v37, v53, v36
	s_waitcnt lgkmcnt(0)
	v_pk_add_f32 v[6:7], v[6:7], v[22:23]
	ds_bpermute_b32 v23, v168, v7
	ds_bpermute_b32 v22, v168, v6
	v_mul_f32_e32 v37, v162, v37
	v_bfe_u32 v38, v37, 16, 1
	v_mul_f32_e32 v5, v5, v36
	v_add3_u32 v37, v37, v38, s68
	s_waitcnt lgkmcnt(0)
	v_pk_add_f32 v[6:7], v[6:7], v[22:23]
	ds_bpermute_b32 v23, v167, v7
	ds_bpermute_b32 v22, v167, v6
	v_mul_f32_e32 v5, v161, v5
	global_store_short_d16_hi v[34:35], v37, off offset:1088
	v_bfe_u32 v37, v5, 16, 1
	v_add3_u32 v5, v5, v37, s68
	s_waitcnt lgkmcnt(0)
	v_pk_add_f32 v[6:7], v[6:7], v[22:23]
	ds_bpermute_b32 v23, v166, v7
	ds_bpermute_b32 v22, v166, v6
	v_mul_f32_e32 v4, v4, v36
	global_store_short_d16_hi v[34:35], v5, off offset:1152
	v_mul_f32_e32 v36, v130, v4
	v_bfe_u32 v37, v36, 16, 1
	s_waitcnt lgkmcnt(0)
	v_pk_add_f32 v[4:5], v[6:7], v[22:23]
	v_lshl_add_u64 v[22:23], v[32:33], 0, v[118:119]
	v_pk_fma_f32 v[4:5], v[4:5], s[24:25], v[92:93] op_sel_hi:[1,0,0]
	s_nop 0
	v_mul_f32_e32 v6, 0x4b800000, v5
	v_cmp_gt_f32_e32 vcc, s67, v5
	s_nop 1
	v_cndmask_b32_e32 v5, v5, v6, vcc
	v_rsq_f32_e32 v5, v5
	v_add3_u32 v6, v36, v37, s68
	global_store_short_d16_hi v[34:35], v6, off offset:1216
	v_mov_b32_e32 v36, v40
	v_mul_f32_e32 v6, 0x45800000, v5
	v_cndmask_b32_e32 v5, v5, v6, vcc
	v_mul_f32_e32 v5, 0x3f4ccccd, v5
	v_mul_f32_e32 v2, v2, v5
	v_mul_f32_e32 v2, v163, v2
	v_bfe_u32 v6, v2, 16, 1
	v_add3_u32 v2, v2, v6, s68
	global_store_short_d16_hi v[22:23], v2, off offset:1024
	v_mul_f32_e32 v2, v3, v5
	v_mul_f32_e32 v2, v162, v2
	v_bfe_u32 v3, v2, 16, 1
	v_mul_f32_e32 v1, v1, v5
	v_add3_u32 v2, v2, v3, s68
	v_mul_f32_e32 v1, v161, v1
	global_store_short_d16_hi v[22:23], v2, off offset:1088
	v_bfe_u32 v2, v1, 16, 1
	v_add3_u32 v1, v1, v2, s68
	v_mul_f32_e32 v2, 0x4b800000, v4
	v_cmp_gt_f32_e32 vcc, s67, v4
	v_mul_f32_e32 v0, v0, v5
	v_mul_f32_e32 v0, v130, v0
	v_cndmask_b32_e32 v2, v4, v2, vcc
	ds_read_b128 v[4:7], v169 offset:64
	global_store_short_d16_hi v[22:23], v1, off offset:1152
	v_bfe_u32 v1, v0, 16, 1
	v_rsq_f32_e32 v34, v2
	v_add3_u32 v0, v0, v1, s68
	global_store_short_d16_hi v[22:23], v0, off offset:1216
	ds_read_b128 v[0:3], v169 offset:96
	s_waitcnt lgkmcnt(1)
; DI unsigned short f2bf(float x) { unsigned u = __float_as_uint(x); u += 0x7fffu + ((u >> 16) & 1u); return (unsigned short)(u >> 16); }
; DI float shx(float v, int mask, int lane) { return __int_as_float(__builtin_amdgcn_ds_bpermute((lane ^ mask) << 2, __float_as_int(v))); }
; template <int DQK, int MODE, int LDQ, int LDK, int LDV> ...
;     ...
;         } else {
;             float v[4]; float ss = 0.f;
; #pragma unroll
;             for (int d0 = 0; d0 < 4; ++d0) { v[d0] = s0v[r][d0] - lam * (o[d0][r] * rl); ss += v[d0] * v[d0]; }
; #pragma unroll
;             for (int mk = 1; mk <= 16; mk <<= 1) ss += shx(ss, mk, lane2);
;             const float rs = rsqrtf(ss * (1.f / 128.f) + EPS) * 0.8f;
; #pragma unroll
;             for (int d0 = 0; d0 < 4; ++d0) AOb[(size_t)orow * 1024 + d0 * 32 + r32] = f2bf(v[d0] * rs * gout[d0 * 32 + r32]);
	v_rcp_f32_e32 v4, v4
	v_mul_f32_e32 v22, 0x45800000, v34
	v_cndmask_b32_e32 v52, v34, v22, vcc
	v_mov_b32_e32 v22, v8
	v_mov_b32_e32 v23, v56
	v_mov_b32_e32 v37, v24
	v_pk_mul_f32 v[22:23], v[22:23], v[4:5] op_sel_hi:[1,0]
	v_pk_mul_f32 v[36:37], v[36:37], v[4:5] op_sel_hi:[1,0]
	v_rcp_f32_e32 v4, v5
	v_mov_b32_e32 v56, v9
	v_mov_b32_e32 v24, v41
	v_pk_fma_f32 v[22:23], v[128:129], v[22:23], v[100:101] neg_lo:[1,0,0] neg_hi:[1,0,0]
	v_pk_mul_f32 v[8:9], v[56:57], v[4:5] op_sel_hi:[1,0]
	v_pk_mul_f32 v[4:5], v[24:25], v[4:5] op_sel_hi:[1,0]
	v_pk_fma_f32 v[8:9], v[128:129], v[8:9], v[96:97] neg_lo:[1,0,0] neg_hi:[1,0,0]
	v_pk_mul_f32 v[34:35], v[22:23], v[22:23]
	v_pk_fma_f32 v[36:37], v[128:129], v[36:37], v[98:99] neg_lo:[1,0,0] neg_hi:[1,0,0]
	v_pk_mul_f32 v[50:51], v[8:9], v[8:9]
	v_pk_fma_f32 v[4:5], v[128:129], v[4:5], v[94:95] neg_lo:[1,0,0] neg_hi:[1,0,0]
	v_pk_mul_f32 v[38:39], v[36:37], v[36:37]
	v_pk_mul_f32 v[24:25], v[4:5], v[4:5]
	v_mov_b32_e32 v40, v50
	v_mov_b32_e32 v41, v34
	v_mov_b32_e32 v34, v51
	v_pk_add_f32 v[34:35], v[40:41], v[34:35]
	v_mov_b32_e32 v40, v25
	v_mov_b32_e32 v41, v39
	v_pk_add_f32 v[34:35], v[40:41], v[34:35]
	v_mov_b32_e32 v25, v38
	v_pk_add_f32 v[24:25], v[24:25], v[34:35]
	ds_bpermute_b32 v35, v164, v25
	ds_bpermute_b32 v34, v164, v24
	v_mul_f32_e32 v40, 0x3f4ccccd, v52
	v_mul_f32_e32 v20, v20, v40
	v_mul_f32_e32 v20, v163, v20
	v_bfe_u32 v41, v20, 16, 1
	s_waitcnt lgkmcnt(0)
	v_pk_add_f32 v[24:25], v[24:25], v[34:35]
	ds_bpermute_b32 v35, v165, v25
	ds_bpermute_b32 v34, v165, v24
	v_lshl_add_u64 v[38:39], v[32:33], 0, v[90:91]
	v_add3_u32 v20, v20, v41, s68
	global_store_short_d16_hi v[38:39], v20, off offset:1024
	v_mul_f32_e32 v41, v21, v40
	s_waitcnt lgkmcnt(0)
	v_pk_add_f32 v[20:21], v[24:25], v[34:35]
	ds_bpermute_b32 v25, v168, v21
	ds_bpermute_b32 v24, v168, v20
	v_mul_f32_e32 v34, v162, v41
	v_bfe_u32 v35, v34, 16, 1
	v_mul_f32_e32 v19, v19, v40
	v_add3_u32 v34, v34, v35, s68
	s_waitcnt lgkmcnt(0)
	v_pk_add_f32 v[20:21], v[20:21], v[24:25]
	ds_bpermute_b32 v25, v167, v21
	ds_bpermute_b32 v24, v167, v20
	v_mul_f32_e32 v19, v161, v19
	global_store_short_d16_hi v[38:39], v34, off offset:1088
	v_bfe_u32 v34, v19, 16, 1
	v_add3_u32 v19, v19, v34, s68
	s_waitcnt lgkmcnt(0)
	v_pk_add_f32 v[20:21], v[20:21], v[24:25]
	ds_bpermute_b32 v25, v166, v21
	ds_bpermute_b32 v24, v166, v20
	v_mul_f32_e32 v18, v18, v40
	global_store_short_d16_hi v[38:39], v19, off offset:1152
	v_mul_f32_e32 v34, v130, v18
	v_bfe_u32 v35, v34, 16, 1
	s_waitcnt lgkmcnt(0)
	v_pk_add_f32 v[18:19], v[20:21], v[24:25]
	v_rcp_f32_e32 v6, v6
	v_pk_fma_f32 v[18:19], v[18:19], s[24:25], v[92:93] op_sel_hi:[1,0,0]
	v_rcp_f32_e32 v0, v0
	v_mul_f32_e32 v20, 0x4b800000, v19
	v_cmp_gt_f32_e32 vcc, s67, v19
	v_rcp_f32_e32 v2, v2
	s_nop 0
	v_cndmask_b32_e32 v19, v19, v20, vcc
	v_rsq_f32_e32 v19, v19
	v_add3_u32 v20, v34, v35, s68
	global_store_short_d16_hi v[38:39], v20, off offset:1216
	v_lshl_add_u64 v[20:21], v[32:33], 0, v[86:87]
	v_mul_f32_e32 v24, 0x45800000, v19
	v_cndmask_b32_e32 v19, v19, v24, vcc
	v_mul_f32_e32 v19, 0x3f4ccccd, v19
	v_mul_f32_e32 v22, v22, v19
	v_mul_f32_e32 v22, v163, v22
	v_bfe_u32 v24, v22, 16, 1
	v_add3_u32 v22, v22, v24, s68
	global_store_short_d16_hi v[20:21], v22, off offset:1024
	v_mul_f32_e32 v22, v23, v19
	v_mul_f32_e32 v22, v162, v22
	v_bfe_u32 v23, v22, 16, 1
	v_add3_u32 v22, v22, v23, s68
	global_store_short_d16_hi v[20:21], v22, off offset:1088
	v_mul_f32_e32 v22, v37, v19
	v_mul_f32_e32 v22, v161, v22
	v_bfe_u32 v23, v22, 16, 1
	v_add3_u32 v22, v22, v23, s68
	global_store_short_d16_hi v[20:21], v22, off offset:1152
	v_mul_f32_e32 v22, 0x4b800000, v18
	v_cmp_gt_f32_e32 vcc, s67, v18
	v_mul_f32_e32 v19, v36, v19
	v_mul_f32_e32 v19, v130, v19
	v_cndmask_b32_e32 v18, v18, v22, vcc
	v_rsq_f32_e32 v18, v18
	v_bfe_u32 v22, v19, 16, 1
	v_add3_u32 v19, v19, v22, s68
	global_store_short_d16_hi v[20:21], v19, off offset:1216
	v_mul_f32_e32 v19, 0x45800000, v18
	v_cndmask_b32_e32 v38, v18, v19, vcc
	v_mov_b32_e32 v18, v10
	v_mov_b32_e32 v19, v58
	v_mov_b32_e32 v22, v42
	v_mov_b32_e32 v23, v26
	v_pk_mul_f32 v[18:19], v[18:19], v[6:7] op_sel_hi:[1,0]
	v_pk_mul_f32 v[22:23], v[22:23], v[6:7] op_sel_hi:[1,0]
	v_rcp_f32_e32 v6, v7
	v_mov_b32_e32 v58, v11
	v_mov_b32_e32 v26, v43
	v_pk_fma_f32 v[18:19], v[128:129], v[18:19], v[88:89] neg_lo:[1,0,0] neg_hi:[1,0,0]
	v_pk_mul_f32 v[10:11], v[58:59], v[6:7] op_sel_hi:[1,0]
	v_pk_mul_f32 v[6:7], v[26:27], v[6:7] op_sel_hi:[1,0]
	v_pk_fma_f32 v[10:11], v[128:129], v[10:11], v[82:83] neg_lo:[1,0,0] neg_hi:[1,0,0]
	v_pk_mul_f32 v[20:21], v[18:19], v[18:19]
	v_pk_fma_f32 v[22:23], v[128:129], v[22:23], v[84:85] neg_lo:[1,0,0] neg_hi:[1,0,0]
	v_pk_mul_f32 v[34:35], v[10:11], v[10:11]
	v_pk_fma_f32 v[6:7], v[128:129], v[6:7], v[80:81] neg_lo:[1,0,0] neg_hi:[1,0,0]
	v_pk_mul_f32 v[24:25], v[22:23], v[22:23]
	v_pk_mul_f32 v[26:27], v[6:7], v[6:7]
	v_mov_b32_e32 v36, v34
	v_mov_b32_e32 v37, v20
	v_mov_b32_e32 v20, v35
	v_pk_add_f32 v[20:21], v[36:37], v[20:21]
	v_mov_b32_e32 v34, v27
	v_mov_b32_e32 v35, v25
	v_pk_add_f32 v[20:21], v[34:35], v[20:21]
	v_mov_b32_e32 v27, v24
	v_pk_add_f32 v[20:21], v[26:27], v[20:21]
	ds_bpermute_b32 v25, v164, v21
	ds_bpermute_b32 v24, v164, v20
	v_mul_f32_e32 v34, 0x3f4ccccd, v38
	v_mul_f32_e32 v8, v8, v34
	v_mul_f32_e32 v8, v163, v8
	v_bfe_u32 v35, v8, 16, 1
	s_waitcnt lgkmcnt(0)
	v_pk_add_f32 v[20:21], v[20:21], v[24:25]
	ds_bpermute_b32 v25, v165, v21
	ds_bpermute_b32 v24, v165, v20
	v_lshl_add_u64 v[26:27], v[32:33], 0, v[78:79]
	v_add3_u32 v8, v8, v35, s68
	global_store_short_d16_hi v[26:27], v8, off offset:1024
	v_mul_f32_e32 v35, v9, v34
	s_waitcnt lgkmcnt(0)
; DI unsigned short f2bf(float x) { unsigned u = __float_as_uint(x); u += 0x7fffu + ((u >> 16) & 1u); return (unsigned short)(u >> 16); }
; DI float shx(float v, int mask, int lane) { return __int_as_float(__builtin_amdgcn_ds_bpermute((lane ^ mask) << 2, __float_as_int(v))); }
; template <int DQK, int MODE, int LDQ, int LDK, int LDV> ...
;     ...
;         } else {
;             float v[4]; float ss = 0.f;
; #pragma unroll
;             for (int d0 = 0; d0 < 4; ++d0) { v[d0] = s0v[r][d0] - lam * (o[d0][r] * rl); ss += v[d0] * v[d0]; }
; #pragma unroll
;             for (int mk = 1; mk <= 16; mk <<= 1) ss += shx(ss, mk, lane2);
;             const float rs = rsqrtf(ss * (1.f / 128.f) + EPS) * 0.8f;
; #pragma unroll
;             for (int d0 = 0; d0 < 4; ++d0) AOb[(size_t)orow * 1024 + d0 * 32 + r32] = f2bf(v[d0] * rs * gout[d0 * 32 + r32]);
	v_pk_add_f32 v[8:9], v[20:21], v[24:25]
	ds_bpermute_b32 v21, v168, v9
	ds_bpermute_b32 v20, v168, v8
	v_mul_f32_e32 v24, v162, v35
	v_bfe_u32 v25, v24, 16, 1
	v_mul_f32_e32 v5, v5, v34
	v_add3_u32 v24, v24, v25, s68
	s_waitcnt lgkmcnt(0)
	v_pk_add_f32 v[8:9], v[8:9], v[20:21]
	ds_bpermute_b32 v21, v167, v9
	ds_bpermute_b32 v20, v167, v8
	v_mul_f32_e32 v5, v161, v5
	global_store_short_d16_hi v[26:27], v24, off offset:1088
	v_bfe_u32 v24, v5, 16, 1
	v_add3_u32 v5, v5, v24, s68
	s_waitcnt lgkmcnt(0)
	v_pk_add_f32 v[8:9], v[8:9], v[20:21]
	ds_bpermute_b32 v21, v166, v9
	ds_bpermute_b32 v20, v166, v8
	v_mul_f32_e32 v4, v4, v34
	global_store_short_d16_hi v[26:27], v5, off offset:1152
	v_mul_f32_e32 v24, v130, v4
	v_bfe_u32 v25, v24, 16, 1
	s_waitcnt lgkmcnt(0)
	v_pk_add_f32 v[4:5], v[8:9], v[20:21]
	s_nop 0
	v_pk_fma_f32 v[4:5], v[4:5], s[24:25], v[92:93] op_sel_hi:[1,0,0]
	s_nop 0
	v_mul_f32_e32 v8, 0x4b800000, v5
	v_cmp_gt_f32_e32 vcc, s67, v5
	s_nop 1
	v_cndmask_b32_e32 v5, v5, v8, vcc
	v_rsq_f32_e32 v5, v5
	v_add3_u32 v8, v24, v25, s68
	global_store_short_d16_hi v[26:27], v8, off offset:1216
	v_lshl_add_u64 v[8:9], v[32:33], 0, v[76:77]
	v_mul_f32_e32 v20, 0x45800000, v5
	v_cndmask_b32_e32 v5, v5, v20, vcc
	v_mul_f32_e32 v5, 0x3f4ccccd, v5
	v_mul_f32_e32 v18, v18, v5
	v_mul_f32_e32 v18, v163, v18
	v_bfe_u32 v20, v18, 16, 1
	v_add3_u32 v18, v18, v20, s68
	global_store_short_d16_hi v[8:9], v18, off offset:1024
	v_mul_f32_e32 v18, v19, v5
	v_mul_f32_e32 v18, v162, v18
	v_bfe_u32 v19, v18, 16, 1
	v_add3_u32 v18, v18, v19, s68
	global_store_short_d16_hi v[8:9], v18, off offset:1088
	v_mul_f32_e32 v18, v23, v5
	v_mul_f32_e32 v18, v161, v18
	v_bfe_u32 v19, v18, 16, 1
	v_add3_u32 v18, v18, v19, s68
	global_store_short_d16_hi v[8:9], v18, off offset:1152
	v_mul_f32_e32 v18, 0x4b800000, v4
	v_cmp_gt_f32_e32 vcc, s67, v4
	v_mul_f32_e32 v5, v22, v5
	v_mul_f32_e32 v5, v130, v5
	v_cndmask_b32_e32 v4, v4, v18, vcc
	v_rsq_f32_e32 v4, v4
	v_bfe_u32 v18, v5, 16, 1
	v_add3_u32 v5, v5, v18, s68
	global_store_short_d16_hi v[8:9], v5, off offset:1216
	v_mul_f32_e32 v5, 0x45800000, v4
	v_cndmask_b32_e32 v34, v4, v5, vcc
	v_mov_b32_e32 v4, v12
	v_mov_b32_e32 v5, v60
	v_mov_b32_e32 v18, v44
	v_mov_b32_e32 v19, v28
	v_pk_mul_f32 v[4:5], v[4:5], v[0:1] op_sel_hi:[1,0]
	v_pk_mul_f32 v[18:19], v[18:19], v[0:1] op_sel_hi:[1,0]
	v_rcp_f32_e32 v0, v1
	v_mov_b32_e32 v60, v13
	v_mov_b32_e32 v28, v45
	s_waitcnt vmcnt(58)
	v_pk_fma_f32 v[4:5], v[128:129], v[4:5], v[116:117] neg_lo:[1,0,0] neg_hi:[1,0,0]
	v_pk_mul_f32 v[12:13], v[60:61], v[0:1] op_sel_hi:[1,0]
	v_pk_mul_f32 v[0:1], v[28:29], v[0:1] op_sel_hi:[1,0]
	s_waitcnt vmcnt(54)
	v_pk_fma_f32 v[12:13], v[128:129], v[12:13], v[112:113] neg_lo:[1,0,0] neg_hi:[1,0,0]
	v_pk_mul_f32 v[8:9], v[4:5], v[4:5]
	v_pk_fma_f32 v[18:19], v[128:129], v[18:19], v[114:115] neg_lo:[1,0,0] neg_hi:[1,0,0]
	v_pk_mul_f32 v[22:23], v[12:13], v[12:13]
	s_waitcnt vmcnt(52)
	v_pk_fma_f32 v[0:1], v[128:129], v[0:1], v[110:111] neg_lo:[1,0,0] neg_hi:[1,0,0]
	v_pk_mul_f32 v[20:21], v[18:19], v[18:19]
	v_pk_mul_f32 v[24:25], v[0:1], v[0:1]
	v_mov_b32_e32 v26, v22
	v_mov_b32_e32 v27, v8
	v_mov_b32_e32 v8, v23
	v_pk_add_f32 v[8:9], v[26:27], v[8:9]
	v_mov_b32_e32 v22, v25
	v_mov_b32_e32 v23, v21
	v_pk_add_f32 v[8:9], v[22:23], v[8:9]
	v_mov_b32_e32 v25, v20
	v_pk_add_f32 v[8:9], v[24:25], v[8:9]
	ds_bpermute_b32 v21, v164, v9
	ds_bpermute_b32 v20, v164, v8
	v_mul_f32_e32 v24, 0x3f4ccccd, v34
	v_mul_f32_e32 v10, v10, v24
	v_mul_f32_e32 v10, v163, v10
	v_bfe_u32 v25, v10, 16, 1
	s_waitcnt lgkmcnt(0)
	v_pk_add_f32 v[8:9], v[8:9], v[20:21]
	ds_bpermute_b32 v21, v165, v9
	ds_bpermute_b32 v20, v165, v8
	v_lshl_add_u64 v[22:23], v[32:33], 0, v[72:73]
	v_add3_u32 v10, v10, v25, s68
	global_store_short_d16_hi v[22:23], v10, off offset:1024
	v_mul_f32_e32 v25, v11, v24
	s_waitcnt lgkmcnt(0)
	v_pk_add_f32 v[8:9], v[8:9], v[20:21]
	ds_bpermute_b32 v11, v168, v9
	ds_bpermute_b32 v10, v168, v8
	v_mul_f32_e32 v20, v162, v25
	v_bfe_u32 v21, v20, 16, 1
	v_mul_f32_e32 v7, v7, v24
	v_add3_u32 v20, v20, v21, s68
	s_waitcnt lgkmcnt(0)
	v_pk_add_f32 v[8:9], v[8:9], v[10:11]
	ds_bpermute_b32 v11, v167, v9
	ds_bpermute_b32 v10, v167, v8
	v_mul_f32_e32 v7, v161, v7
	global_store_short_d16_hi v[22:23], v20, off offset:1088
	v_bfe_u32 v20, v7, 16, 1
	v_add3_u32 v7, v7, v20, s68
	s_waitcnt lgkmcnt(0)
	v_pk_add_f32 v[8:9], v[8:9], v[10:11]
	ds_bpermute_b32 v11, v166, v9
	ds_bpermute_b32 v10, v166, v8
	v_mul_f32_e32 v6, v6, v24
	global_store_short_d16_hi v[22:23], v7, off offset:1152
	v_mul_f32_e32 v20, v130, v6
	v_bfe_u32 v21, v20, 16, 1
	s_waitcnt lgkmcnt(0)
; DI unsigned short f2bf(float x) { unsigned u = __float_as_uint(x); u += 0x7fffu + ((u >> 16) & 1u); return (unsigned short)(u >> 16); }
; DI float shx(float v, int mask, int lane) { return __int_as_float(__builtin_amdgcn_ds_bpermute((lane ^ mask) << 2, __float_as_int(v))); }
; template <int DQK, int MODE, int LDQ, int LDK, int LDV> ...
;     ...
;         } else {
;             float v[4]; float ss = 0.f;
; #pragma unroll
;             for (int d0 = 0; d0 < 4; ++d0) { v[d0] = s0v[r][d0] - lam * (o[d0][r] * rl); ss += v[d0] * v[d0]; }
; #pragma unroll
;             for (int mk = 1; mk <= 16; mk <<= 1) ss += shx(ss, mk, lane2);
;             const float rs = rsqrtf(ss * (1.f / 128.f) + EPS) * 0.8f;
; #pragma unroll
;             for (int d0 = 0; d0 < 4; ++d0) AOb[(size_t)orow * 1024 + d0 * 32 + r32] = f2bf(v[d0] * rs * gout[d0 * 32 + r32]);
	v_pk_add_f32 v[6:7], v[8:9], v[10:11]
	s_nop 0
	v_pk_fma_f32 v[6:7], v[6:7], s[24:25], v[92:93] op_sel_hi:[1,0,0]
	s_nop 0
	v_mul_f32_e32 v8, 0x4b800000, v7
	v_cmp_gt_f32_e32 vcc, s67, v7
	s_nop 1
	v_cndmask_b32_e32 v7, v7, v8, vcc
	v_rsq_f32_e32 v7, v7
	v_add3_u32 v8, v20, v21, s68
	global_store_short_d16_hi v[22:23], v8, off offset:1216
	v_lshl_add_u64 v[8:9], v[32:33], 0, v[74:75]
	v_mul_f32_e32 v10, 0x45800000, v7
	v_cndmask_b32_e32 v7, v7, v10, vcc
	v_mul_f32_e32 v7, 0x3f4ccccd, v7
	v_mul_f32_e32 v4, v4, v7
	v_mul_f32_e32 v4, v163, v4
	v_bfe_u32 v10, v4, 16, 1
	v_add3_u32 v4, v4, v10, s68
	global_store_short_d16_hi v[8:9], v4, off offset:1024
	v_mul_f32_e32 v4, v5, v7
	v_mul_f32_e32 v4, v162, v4
	v_bfe_u32 v5, v4, 16, 1
	v_add3_u32 v4, v4, v5, s68
	global_store_short_d16_hi v[8:9], v4, off offset:1088
	v_mul_f32_e32 v4, v19, v7
	v_mul_f32_e32 v4, v161, v4
	v_bfe_u32 v5, v4, 16, 1
	v_add3_u32 v4, v4, v5, s68
	v_mul_f32_e32 v5, 0x4b800000, v6
	v_cmp_gt_f32_e32 vcc, s67, v6
	global_store_short_d16_hi v[8:9], v4, off offset:1152
	v_mul_f32_e32 v4, v18, v7
	v_cndmask_b32_e32 v5, v6, v5, vcc
	v_rsq_f32_e32 v5, v5
	v_mul_f32_e32 v4, v130, v4
	v_bfe_u32 v6, v4, 16, 1
	v_add3_u32 v4, v4, v6, s68
	global_store_short_d16_hi v[8:9], v4, off offset:1216
	v_mul_f32_e32 v4, 0x45800000, v5
	v_cndmask_b32_e32 v24, v5, v4, vcc
	v_mov_b32_e32 v4, v14
	v_mov_b32_e32 v5, v62
	v_mov_b32_e32 v8, v46
	v_mov_b32_e32 v9, v30
	v_pk_mul_f32 v[4:5], v[4:5], v[2:3] op_sel_hi:[1,0]
	v_pk_mul_f32 v[8:9], v[8:9], v[2:3] op_sel_hi:[1,0]
	v_rcp_f32_e32 v2, v3
	v_mov_b32_e32 v62, v15
	v_mov_b32_e32 v30, v47
	s_waitcnt vmcnt(58)
	v_pk_fma_f32 v[4:5], v[128:129], v[4:5], v[108:109] neg_lo:[1,0,0] neg_hi:[1,0,0]
	v_pk_mul_f32 v[14:15], v[62:63], v[2:3] op_sel_hi:[1,0]
	v_pk_mul_f32 v[2:3], v[30:31], v[2:3] op_sel_hi:[1,0]
	s_waitcnt vmcnt(54)
	v_pk_fma_f32 v[14:15], v[128:129], v[14:15], v[104:105] neg_lo:[1,0,0] neg_hi:[1,0,0]
	v_pk_mul_f32 v[6:7], v[4:5], v[4:5]
	v_pk_fma_f32 v[8:9], v[128:129], v[8:9], v[106:107] neg_lo:[1,0,0] neg_hi:[1,0,0]
	v_pk_mul_f32 v[18:19], v[14:15], v[14:15]
	s_waitcnt vmcnt(52)
	v_pk_fma_f32 v[2:3], v[128:129], v[2:3], v[102:103] neg_lo:[1,0,0] neg_hi:[1,0,0]
	v_pk_mul_f32 v[10:11], v[8:9], v[8:9]
	v_pk_mul_f32 v[20:21], v[2:3], v[2:3]
	v_mov_b32_e32 v22, v18
	v_mov_b32_e32 v23, v6
	v_mov_b32_e32 v6, v19
	v_pk_add_f32 v[6:7], v[22:23], v[6:7]
	v_mov_b32_e32 v18, v21
	v_mov_b32_e32 v19, v11
	v_pk_add_f32 v[6:7], v[18:19], v[6:7]
	v_mov_b32_e32 v21, v10
	v_pk_add_f32 v[6:7], v[20:21], v[6:7]
	ds_bpermute_b32 v11, v164, v7
	ds_bpermute_b32 v10, v164, v6
	v_mul_f32_e32 v20, 0x3f4ccccd, v24
	v_mul_f32_e32 v12, v12, v20
	v_mul_f32_e32 v12, v163, v12
	v_bfe_u32 v21, v12, 16, 1
	s_waitcnt lgkmcnt(0)
	v_pk_add_f32 v[6:7], v[6:7], v[10:11]
	ds_bpermute_b32 v11, v165, v7
	ds_bpermute_b32 v10, v165, v6
	v_lshl_add_u64 v[18:19], v[32:33], 0, v[64:65]
	v_add3_u32 v12, v12, v21, s68
	global_store_short_d16_hi v[18:19], v12, off offset:1024
	v_mul_f32_e32 v12, v13, v20
	s_waitcnt lgkmcnt(0)
	v_pk_add_f32 v[6:7], v[6:7], v[10:11]
	ds_bpermute_b32 v11, v168, v7
	ds_bpermute_b32 v10, v168, v6
	v_mul_f32_e32 v12, v162, v12
	v_bfe_u32 v13, v12, 16, 1
	v_mul_f32_e32 v1, v1, v20
	v_add3_u32 v12, v12, v13, s68
	s_waitcnt lgkmcnt(0)
	v_pk_add_f32 v[6:7], v[6:7], v[10:11]
	ds_bpermute_b32 v11, v167, v7
	ds_bpermute_b32 v10, v167, v6
	v_mul_f32_e32 v1, v161, v1
	global_store_short_d16_hi v[18:19], v12, off offset:1088
	v_bfe_u32 v12, v1, 16, 1
	v_add3_u32 v1, v1, v12, s68
	s_waitcnt lgkmcnt(0)
	v_pk_add_f32 v[6:7], v[6:7], v[10:11]
	ds_bpermute_b32 v11, v166, v7
	ds_bpermute_b32 v10, v166, v6
	v_mul_f32_e32 v0, v0, v20
	global_store_short_d16_hi v[18:19], v1, off offset:1152
	v_mul_f32_e32 v12, v130, v0
	v_bfe_u32 v13, v12, 16, 1
	s_waitcnt lgkmcnt(0)
	v_pk_add_f32 v[0:1], v[6:7], v[10:11]
	s_nop 0
	v_pk_fma_f32 v[0:1], v[0:1], s[24:25], v[92:93] op_sel_hi:[1,0,0]
	s_nop 0
	v_mul_f32_e32 v6, 0x4b800000, v1
	v_cmp_gt_f32_e32 vcc, s67, v1
	s_nop 1
	v_cndmask_b32_e32 v1, v1, v6, vcc
	v_rsq_f32_e32 v1, v1
	v_add3_u32 v6, v12, v13, s68
	global_store_short_d16_hi v[18:19], v6, off offset:1216
	v_lshl_add_u64 v[6:7], v[32:33], 0, v[48:49]
	v_mul_f32_e32 v10, 0x45800000, v1
	v_cndmask_b32_e32 v1, v1, v10, vcc
	v_mul_f32_e32 v1, 0x3f4ccccd, v1
	v_mul_f32_e32 v4, v4, v1
	v_mul_f32_e32 v4, v163, v4
	v_bfe_u32 v10, v4, 16, 1
	v_add3_u32 v4, v4, v10, s68
	global_store_short_d16_hi v[6:7], v4, off offset:1024
	v_mul_f32_e32 v4, v5, v1
	v_mul_f32_e32 v4, v162, v4
	v_bfe_u32 v5, v4, 16, 1
	v_add3_u32 v4, v4, v5, s68
	global_store_short_d16_hi v[6:7], v4, off offset:1088
	v_mul_f32_e32 v4, v9, v1
	v_mul_f32_e32 v4, v161, v4
	v_bfe_u32 v5, v4, 16, 1
	v_add3_u32 v4, v4, v5, s68
	global_store_short_d16_hi v[6:7], v4, off offset:1152
	v_mul_f32_e32 v4, 0x4b800000, v0
	v_cmp_gt_f32_e32 vcc, s67, v0
	v_mul_f32_e32 v1, v8, v1
	v_mul_f32_e32 v1, v130, v1
	v_cndmask_b32_e32 v0, v0, v4, vcc
	v_rsq_f32_e32 v0, v0
	v_bfe_u32 v4, v1, 16, 1
	v_add3_u32 v1, v1, v4, s68
	global_store_short_d16_hi v[6:7], v1, off offset:1216
	v_mul_f32_e32 v1, 0x45800000, v0
	v_cndmask_b32_e32 v0, v0, v1, vcc
	v_mul_f32_e32 v4, 0x3f4ccccd, v0
	v_mul_f32_e32 v5, v14, v4
	v_mul_f32_e32 v5, v163, v5
	v_bfe_u32 v6, v5, 16, 1
	v_lshl_add_u64 v[0:1], v[32:33], 0, v[16:17]
	v_add3_u32 v5, v5, v6, s68
	global_store_short_d16_hi v[0:1], v5, off offset:1024
	v_mul_f32_e32 v5, v15, v4
	v_mul_f32_e32 v5, v162, v5
	v_bfe_u32 v6, v5, 16, 1
	v_mul_f32_e32 v3, v3, v4
	v_add3_u32 v5, v5, v6, s68
	v_mul_f32_e32 v3, v161, v3
	global_store_short_d16_hi v[0:1], v5, off offset:1088
	v_bfe_u32 v5, v3, 16, 1
	v_mul_f32_e32 v2, v2, v4
	v_add3_u32 v3, v3, v5, s68
	v_mul_f32_e32 v2, v130, v2
	global_store_short_d16_hi v[0:1], v3, off offset:1152
	v_bfe_u32 v3, v2, 16, 1
	v_add3_u32 v2, v2, v3, s68
	global_store_short_d16_hi v[0:1], v2, off offset:1216
	s_waitcnt vmcnt(63) expcnt(7) lgkmcnt(15)
	s_barrier

; DI void expsum(f32x16& p, float& l_reg, bf16x8& pa0, bf16x8& pa1) {
; #pragma unroll
;     for (int r = 0; r < 16; ++r) p[r] = __builtin_amdgcn_exp2f(p[r]);
;     float ps = 0.f;
; #pragma unroll
;     for (int r = 0; r < 16; ++r) ps += p[r];
;     l_reg += ps; asm volatile("" : "+v"(l_reg));
;     ...
;     ATT_PK4(p, 0, pa0); ATT_PK4(p, 8, pa1);
.Lstg_mla_top_2:
	s_setprio 0
	s_mov_b32 m0, s1
	s_mov_b32 s0, s5
	s_mov_b32 s5, s44
	s_mov_b32 s44, s4
	s_lshl_b32 s4, s4, 14
	global_load_lds_dwordx4 v136, s[34:35]
	s_add_i32 m0, s1, 0x2000
	s_add_i32 s4, s52, s4
	global_load_lds_dwordx4 v138, s[34:35]
	s_add_i32 m0, s1, 0x4000
	s_add_i32 s6, s4, 0x400
	global_load_lds_dwordx4 v140, s[34:35]
	s_mov_b32 m0, s4
	s_add_i32 s1, s43, -3
	global_load_lds_dwordx4 v144, s[34:35]
	s_mov_b32 m0, s6
	s_nop 0
	global_load_lds_dwordx4 v142, s[34:35]
	s_and_b32 s1, s1, 3
	s_mulk_i32 s1, 0x6000
	v_add_u32_e32 v246, s1, v158
	v_add_u32_e32 v174, v246, v151
	v_add_u32_e32 v178, v246, v149
	v_add_u32_e32 v182, v246, v148
	v_add_u32_e32 v186, v246, v147
	s_lshl_b32 s1, s0, 14
	ds_read_b128 v[190:193], v174 offset:12416
	ds_read_b128 v[194:197], v178 offset:12416
	ds_read_b128 v[174:177], v174 offset:12288
	ds_read_b128 v[178:181], v178 offset:12288
	ds_read_b128 v[182:185], v182 offset:12288
	ds_read_b128 v[186:189], v186 offset:12288
	v_add_u32_e32 v254, s1, v130
	ds_read_b64_tr_b16 v[198:199], v254 offset:0
	ds_read_b64_tr_b16 v[200:201], v254 offset:0x800
	ds_read_b64_tr_b16 v[202:203], v254 offset:0x1000
	ds_read_b64_tr_b16 v[204:205], v254 offset:0x1800
	ds_read_b64_tr_b16 v[206:207], v254 offset:0x200
	ds_read_b64_tr_b16 v[208:209], v254 offset:0xa00
	ds_read_b64_tr_b16 v[210:211], v254 offset:0x1200
	ds_read_b64_tr_b16 v[212:213], v254 offset:0x1a00
	s_setprio 2
	ds_read_b64_tr_b16 v[214:215], v254 offset:0x400
	ds_read_b64_tr_b16 v[216:217], v254 offset:0xc00
	ds_read_b64_tr_b16 v[218:219], v254 offset:0x1400
	ds_read_b64_tr_b16 v[220:221], v254 offset:0x1c00
	ds_read_b64_tr_b16 v[222:223], v254 offset:0x600
	ds_read_b64_tr_b16 v[224:225], v254 offset:0xe00
	ds_read_b64_tr_b16 v[226:227], v254 offset:0x1600
	ds_read_b64_tr_b16 v[228:229], v254 offset:0x1e00
	v_exp_f32_e32 v64, v64
	v_exp_f32_e32 v65, v65
	v_exp_f32_e32 v66, v66
	v_exp_f32_e32 v67, v67
	v_exp_f32_e32 v68, v68
	v_exp_f32_e32 v69, v69
	v_add_f32_e32 v230, v65, v64
	v_exp_f32_e32 v70, v70
	v_add_f32_e32 v230, v66, v230
	v_exp_f32_e32 v71, v71
	v_add_f32_e32 v230, v67, v230
	v_exp_f32_e32 v72, v72
	v_add_f32_e32 v230, v68, v230
	v_exp_f32_e32 v73, v73
	v_add_f32_e32 v230, v69, v230
	v_exp_f32_e32 v74, v74
	v_add_f32_e32 v230, v70, v230
	v_exp_f32_e32 v75, v75
	v_add_f32_e32 v230, v71, v230
	v_exp_f32_e32 v76, v76
	v_add_f32_e32 v230, v72, v230
	v_exp_f32_e32 v77, v77
	v_add_f32_e32 v230, v73, v230
	v_exp_f32_e32 v78, v78
	v_add_f32_e32 v230, v74, v230
	v_exp_f32_e32 v79, v79
	v_add_f32_e32 v230, v75, v230
	v_add_f32_e32 v230, v76, v230
	v_add_f32_e32 v230, v77, v230
	v_add_f32_e32 v230, v78, v230
	v_add_f32_e32 v230, v79, v230
	v_add_f32_e32 v173, v173, v230
	v_cvt_pk_bf16_f32 v64, v64, v65
	v_cvt_pk_bf16_f32 v65, v66, v67
	v_cvt_pk_bf16_f32 v66, v68, v69
	v_cvt_pk_bf16_f32 v67, v70, v71
	v_cvt_pk_bf16_f32 v68, v72, v73
	v_cvt_pk_bf16_f32 v69, v74, v75
	v_cvt_pk_bf16_f32 v70, v76, v77
	v_cvt_pk_bf16_f32 v71, v78, v79
	s_nop 0
	v_permlane32_swap_b32_e32 v64, v66
	v_permlane32_swap_b32_e32 v65, v67
	v_permlane32_swap_b32_e32 v68, v70
	v_permlane32_swap_b32_e32 v69, v71
	s_waitcnt lgkmcnt(0)
	v_add_u32_e32 v72, v246, v151
	v_add_u32_e32 v73, v246, v149
	v_add_u32_e32 v74, v246, v148
	v_add_u32_e32 v75, v246, v147
	ds_read_b128 v[230:233], v74 offset:12416
	ds_read_b128 v[234:237], v75 offset:12416
	ds_read_b128 v[238:241], v72 offset:12544
	ds_read_b128 v[242:245], v73 offset:12544
	ds_read_b128 v[246:249], v74 offset:12544
	ds_read_b128 v[250:253], v75 offset:12544
	s_setprio 1
	v_mfma_f32_32x32x16_bf16 v[48:63], v[64:67], v[198:201], v[48:63]
	v_mfma_f32_32x32x16_bf16 v[32:47], v[64:67], v[206:209], v[32:47]
	v_mfma_f32_32x32x16_bf16 v[16:31], v[64:67], v[214:217], v[16:31]
	v_mfma_f32_32x32x16_bf16 v[0:15], v[64:67], v[222:225], v[0:15]
	v_mfma_f32_32x32x16_bf16 v[48:63], v[68:71], v[202:205], v[48:63]
	v_mfma_f32_32x32x16_bf16 v[32:47], v[68:71], v[210:213], v[32:47]
	v_mfma_f32_32x32x16_bf16 v[16:31], v[68:71], v[218:221], v[16:31]
	v_mfma_f32_32x32x16_bf16 v[0:15], v[68:71], v[226:229], v[0:15]
	s_waitcnt lgkmcnt(0)
; template <int D0A, int D0B> DI void qk_mma(f32x16& p, const bf16x8* kf, const bf16x8* qr) {
; #pragma unroll
;     for (int d0 = D0A; d0 < D0B; ++d0) {
;         if (d0 == 0) { f32x16 z; _Pragma("unroll") for (int r = 0; r < 16; ++r) z[r] = 0.f; p = __builtin_amdgcn_mfma_f32_32x32x16_bf16(kf[0], qr[0], z, 0, 0, 0); }
;         else p = __builtin_amdgcn_mfma_f32_32x32x16_bf16(kf[d0 - D0A], qr[d0], p, 0, 0, 0); }
; }
	v_mfma_f32_32x32x16_bf16 v[64:79], v[174:177], v[80:83], 0
	v_mfma_f32_32x32x16_bf16 v[64:79], v[178:181], v[84:87], v[64:79]
	v_mfma_f32_32x32x16_bf16 v[64:79], v[182:185], v[88:91], v[64:79]
	v_mfma_f32_32x32x16_bf16 v[64:79], v[186:189], v[92:95], v[64:79]
	v_mfma_f32_32x32x16_bf16 v[64:79], v[190:193], v[96:99], v[64:79]
	v_mfma_f32_32x32x16_bf16 v[64:79], v[194:197], v[100:103], v[64:79]
	v_mfma_f32_32x32x16_bf16 v[64:79], v[230:233], v[104:107], v[64:79]
	v_mfma_f32_32x32x16_bf16 v[64:79], v[234:237], v[108:111], v[64:79]
	v_mfma_f32_32x32x16_bf16 v[64:79], v[238:241], v[112:115], v[64:79]
	v_mfma_f32_32x32x16_bf16 v[64:79], v[242:245], v[116:119], v[64:79]
	v_mfma_f32_32x32x16_bf16 v[64:79], v[246:249], v[120:123], v[64:79]
	v_mfma_f32_32x32x16_bf16 v[64:79], v[250:253], v[124:127], v[64:79]
	s_setprio 0
	s_add_i32 s4, s43, -2
	s_and_b32 s4, s4, 3
	s_mulk_i32 s4, 0x6000
	v_add_u32_e32 v246, s4, v158
	v_add_u32_e32 v174, v246, v151
	v_add_u32_e32 v178, v246, v149
	v_add_u32_e32 v182, v246, v148
	v_add_u32_e32 v186, v246, v147
	ds_read_b128 v[190:193], v174 offset:128
	ds_read_b128 v[194:197], v178 offset:128
	ds_read_b128 v[174:177], v174
	ds_read_b128 v[178:181], v178
	ds_read_b128 v[182:185], v182
	ds_read_b128 v[186:189], v186
	ds_read_b64_tr_b16 v[198:199], v254 offset:0x2000
	ds_read_b64_tr_b16 v[200:201], v254 offset:0x2800
	ds_read_b64_tr_b16 v[202:203], v254 offset:0x3000
	ds_read_b64_tr_b16 v[204:205], v254 offset:0x3800
	ds_read_b64_tr_b16 v[206:207], v254 offset:0x2200
	ds_read_b64_tr_b16 v[208:209], v254 offset:0x2a00
	ds_read_b64_tr_b16 v[210:211], v254 offset:0x3200
	ds_read_b64_tr_b16 v[212:213], v254 offset:0x3a00
	s_setprio 2
	ds_read_b64_tr_b16 v[214:215], v254 offset:0x2400
	ds_read_b64_tr_b16 v[216:217], v254 offset:0x2c00
	ds_read_b64_tr_b16 v[218:219], v254 offset:0x3400
	ds_read_b64_tr_b16 v[220:221], v254 offset:0x3c00
	ds_read_b64_tr_b16 v[222:223], v254 offset:0x2600
	ds_read_b64_tr_b16 v[224:225], v254 offset:0x2e00
	ds_read_b64_tr_b16 v[226:227], v254 offset:0x3600
	ds_read_b64_tr_b16 v[228:229], v254 offset:0x3e00
	v_exp_f32_e32 v64, v64
	v_exp_f32_e32 v65, v65
	v_exp_f32_e32 v66, v66
	v_exp_f32_e32 v67, v67
	v_exp_f32_e32 v68, v68
	v_exp_f32_e32 v69, v69
	v_add_f32_e32 v230, v65, v64
	v_exp_f32_e32 v70, v70
	v_add_f32_e32 v230, v66, v230
	v_exp_f32_e32 v71, v71
	v_add_f32_e32 v230, v67, v230
	v_exp_f32_e32 v72, v72
	v_add_f32_e32 v230, v68, v230
	v_exp_f32_e32 v73, v73
	v_add_f32_e32 v230, v69, v230
	v_exp_f32_e32 v74, v74
	v_add_f32_e32 v230, v70, v230
	v_exp_f32_e32 v75, v75
	v_add_f32_e32 v230, v71, v230
	v_exp_f32_e32 v76, v76
	v_add_f32_e32 v230, v72, v230
	v_exp_f32_e32 v77, v77
	v_add_f32_e32 v230, v73, v230
	v_exp_f32_e32 v78, v78
	v_add_f32_e32 v230, v74, v230
	v_exp_f32_e32 v79, v79
	v_add_f32_e32 v230, v75, v230
	v_add_f32_e32 v230, v76, v230
	v_add_f32_e32 v230, v77, v230
	v_add_f32_e32 v230, v78, v230
	v_add_f32_e32 v230, v79, v230
	v_add_f32_e32 v173, v173, v230
	v_cvt_pk_bf16_f32 v64, v64, v65
	v_cvt_pk_bf16_f32 v65, v66, v67
	v_cvt_pk_bf16_f32 v66, v68, v69
	v_cvt_pk_bf16_f32 v67, v70, v71
	v_cvt_pk_bf16_f32 v68, v72, v73
	v_cvt_pk_bf16_f32 v69, v74, v75
	v_cvt_pk_bf16_f32 v70, v76, v77
	v_cvt_pk_bf16_f32 v71, v78, v79
	s_nop 0
	v_permlane32_swap_b32_e32 v64, v66
	v_permlane32_swap_b32_e32 v65, v67
	v_permlane32_swap_b32_e32 v68, v70
	v_permlane32_swap_b32_e32 v69, v71
	s_waitcnt lgkmcnt(0)
	v_add_u32_e32 v72, v246, v151
	v_add_u32_e32 v73, v246, v149
	v_add_u32_e32 v74, v246, v148
	v_add_u32_e32 v75, v246, v147
	ds_read_b128 v[230:233], v74 offset:128
	ds_read_b128 v[234:237], v75 offset:128
	ds_read_b128 v[238:241], v72 offset:256
	ds_read_b128 v[242:245], v73 offset:256
	ds_read_b128 v[246:249], v74 offset:256
	ds_read_b128 v[250:253], v75 offset:256
	s_setprio 1
	s_cmp_lt_u32 s33, 0x100
	s_cbranch_scc1 .Lstg_mla_mid_3
	s_waitcnt vmcnt(5)
	s_barrier

.Lstg_mla_t61_4:
	s_setprio 0
	v_lshl_add_u64 v[132:133], v[132:133], 1, s[0:1]
	s_mov_b32 m0, s6
	v_lshl_add_u64 v[134:135], v[134:135], 1, s[0:1]
	global_load_lds_dwordx4 v[132:133], off
	s_mov_b32 m0, s7
	s_nop 0
	global_load_lds_dwordx4 v[134:135], off
	ds_read_b128 v[132:135], v161 offset:36864
	ds_read_b128 v[136:139], v162 offset:36864
	ds_read_b128 v[140:143], v163 offset:36864
	ds_read_b128 v[174:177], v164 offset:36864
	ds_read_b128 v[178:181], v165 offset:36864
	ds_read_b128 v[182:185], v166 offset:36864
	v_lshl_add_u32 v144, s5, 14, v130
	ds_read_b64_tr_b16 v[186:187], v144 offset:0
	ds_read_b64_tr_b16 v[188:189], v144 offset:0x800
	ds_read_b64_tr_b16 v[190:191], v144 offset:0x1000
	ds_read_b64_tr_b16 v[192:193], v144 offset:0x1800
	ds_read_b64_tr_b16 v[194:195], v144 offset:0x200
	ds_read_b64_tr_b16 v[196:197], v144 offset:0xa00
	ds_read_b64_tr_b16 v[198:199], v144 offset:0x1200
	ds_read_b64_tr_b16 v[200:201], v144 offset:0x1a00
	s_setprio 2
	ds_read_b64_tr_b16 v[202:203], v144 offset:0x400
	ds_read_b64_tr_b16 v[204:205], v144 offset:0xc00
	ds_read_b64_tr_b16 v[206:207], v144 offset:0x1400
	ds_read_b64_tr_b16 v[208:209], v144 offset:0x1c00
	ds_read_b64_tr_b16 v[210:211], v144 offset:0x600
	ds_read_b64_tr_b16 v[212:213], v144 offset:0xe00
	ds_read_b64_tr_b16 v[214:215], v144 offset:0x1600
	ds_read_b64_tr_b16 v[216:217], v144 offset:0x1e00
	v_exp_f32_e32 v64, v64
	v_exp_f32_e32 v65, v65
	v_exp_f32_e32 v66, v66
	v_exp_f32_e32 v67, v67
	v_exp_f32_e32 v68, v68
	v_exp_f32_e32 v69, v69
	v_add_f32_e32 v145, v65, v64
	v_exp_f32_e32 v70, v70
	v_add_f32_e32 v145, v66, v145
	v_exp_f32_e32 v71, v71
	v_add_f32_e32 v145, v67, v145
	v_exp_f32_e32 v72, v72
	v_add_f32_e32 v145, v68, v145
	v_exp_f32_e32 v73, v73
	v_add_f32_e32 v145, v69, v145
	v_exp_f32_e32 v74, v74
	v_add_f32_e32 v145, v70, v145
	v_exp_f32_e32 v75, v75
	v_add_f32_e32 v145, v71, v145
	v_exp_f32_e32 v76, v76
	v_add_f32_e32 v145, v72, v145
	v_exp_f32_e32 v77, v77
	v_add_f32_e32 v145, v73, v145
	v_exp_f32_e32 v78, v78
	v_add_f32_e32 v145, v74, v145
	v_exp_f32_e32 v79, v79
	v_add_f32_e32 v145, v75, v145
	v_add_f32_e32 v145, v76, v145
	v_add_f32_e32 v145, v77, v145
	v_add_f32_e32 v145, v78, v145
	v_add_f32_e32 v145, v79, v145
	v_add_f32_e32 v145, v173, v145
	v_cvt_pk_bf16_f32 v64, v64, v65
	v_cvt_pk_bf16_f32 v65, v66, v67
	v_cvt_pk_bf16_f32 v66, v68, v69
	v_cvt_pk_bf16_f32 v67, v70, v71
	v_cvt_pk_bf16_f32 v68, v72, v73
	v_cvt_pk_bf16_f32 v69, v74, v75
	v_cvt_pk_bf16_f32 v70, v76, v77
	v_cvt_pk_bf16_f32 v71, v78, v79
	s_nop 0
	v_permlane32_swap_b32_e32 v64, v66
	v_permlane32_swap_b32_e32 v65, v67
	v_permlane32_swap_b32_e32 v68, v70
	v_permlane32_swap_b32_e32 v69, v71
	s_waitcnt lgkmcnt(0)
	ds_read_b128 v[218:221], v167 offset:36864
	ds_read_b128 v[222:225], v168 offset:36864
	ds_read_b128 v[226:229], v169 offset:36864
	ds_read_b128 v[230:233], v170 offset:36864
	ds_read_b128 v[234:237], v171 offset:36864
	ds_read_b128 v[238:241], v172 offset:36864
	s_setprio 1
	v_mfma_f32_32x32x16_bf16 v[48:63], v[64:67], v[186:189], v[48:63]
	v_mfma_f32_32x32x16_bf16 v[32:47], v[64:67], v[194:197], v[32:47]
	v_mfma_f32_32x32x16_bf16 v[16:31], v[64:67], v[202:205], v[16:31]
	v_mfma_f32_32x32x16_bf16 v[0:15], v[64:67], v[210:213], v[0:15]
	v_mfma_f32_32x32x16_bf16 v[48:63], v[68:71], v[190:193], v[48:63]
	v_mfma_f32_32x32x16_bf16 v[32:47], v[68:71], v[198:201], v[32:47]
	v_mfma_f32_32x32x16_bf16 v[16:31], v[68:71], v[206:209], v[16:31]
	v_mfma_f32_32x32x16_bf16 v[0:15], v[68:71], v[214:217], v[0:15]
	s_waitcnt lgkmcnt(0)
; template <int D0A, int D0B> DI void qk_mma(f32x16& p, const bf16x8* kf, const bf16x8* qr) {
; #pragma unroll
;     for (int d0 = D0A; d0 < D0B; ++d0) {
;         if (d0 == 0) { f32x16 z; _Pragma("unroll") for (int r = 0; r < 16; ++r) z[r] = 0.f; p = __builtin_amdgcn_mfma_f32_32x32x16_bf16(kf[0], qr[0], z, 0, 0, 0); }
;         else p = __builtin_amdgcn_mfma_f32_32x32x16_bf16(kf[d0 - D0A], qr[d0], p, 0, 0, 0); }
; }
	v_mfma_f32_32x32x16_bf16 v[64:79], v[132:135], v[80:83], 0
	v_mfma_f32_32x32x16_bf16 v[64:79], v[136:139], v[84:87], v[64:79]
	v_mfma_f32_32x32x16_bf16 v[64:79], v[140:143], v[88:91], v[64:79]
	v_mfma_f32_32x32x16_bf16 v[64:79], v[174:177], v[92:95], v[64:79]
	v_mfma_f32_32x32x16_bf16 v[64:79], v[178:181], v[96:99], v[64:79]
	v_mfma_f32_32x32x16_bf16 v[64:79], v[182:185], v[100:103], v[64:79]
	s_waitcnt lgkmcnt(0)
	v_mfma_f32_32x32x16_bf16 v[64:79], v[218:221], v[104:107], v[64:79]
	v_mfma_f32_32x32x16_bf16 v[64:79], v[222:225], v[108:111], v[64:79]
	v_mfma_f32_32x32x16_bf16 v[64:79], v[226:229], v[112:115], v[64:79]
	v_mfma_f32_32x32x16_bf16 v[64:79], v[230:233], v[116:119], v[64:79]
	v_mfma_f32_32x32x16_bf16 v[64:79], v[234:237], v[120:123], v[64:79]
	v_mfma_f32_32x32x16_bf16 v[64:79], v[238:241], v[124:127], v[64:79]
	s_setprio 0
	ds_read_b128 v[132:135], v161 offset:49152
	ds_read_b128 v[136:139], v162 offset:49152
	ds_read_b128 v[140:143], v163 offset:49152
	ds_read_b128 v[174:177], v164 offset:49152
	ds_read_b128 v[178:181], v165 offset:49152
	ds_read_b128 v[182:185], v166 offset:49152
	ds_read_b64_tr_b16 v[186:187], v144 offset:0x2000
	ds_read_b64_tr_b16 v[188:189], v144 offset:0x2800
	ds_read_b64_tr_b16 v[190:191], v144 offset:0x3000
	ds_read_b64_tr_b16 v[192:193], v144 offset:0x3800
	ds_read_b64_tr_b16 v[194:195], v144 offset:0x2200
	ds_read_b64_tr_b16 v[196:197], v144 offset:0x2a00
	ds_read_b64_tr_b16 v[198:199], v144 offset:0x3200
	ds_read_b64_tr_b16 v[200:201], v144 offset:0x3a00
	s_setprio 2
	ds_read_b64_tr_b16 v[202:203], v144 offset:0x2400
	ds_read_b64_tr_b16 v[204:205], v144 offset:0x2c00
	ds_read_b64_tr_b16 v[206:207], v144 offset:0x3400
	ds_read_b64_tr_b16 v[208:209], v144 offset:0x3c00
	ds_read_b64_tr_b16 v[210:211], v144 offset:0x2600
	ds_read_b64_tr_b16 v[212:213], v144 offset:0x2e00
	ds_read_b64_tr_b16 v[214:215], v144 offset:0x3600
	ds_read_b64_tr_b16 v[216:217], v144 offset:0x3e00
	s_nop 5
	v_exp_f32_e32 v64, v64
	v_exp_f32_e32 v65, v65
	v_exp_f32_e32 v66, v66
	v_exp_f32_e32 v67, v67
	v_exp_f32_e32 v68, v68
	v_exp_f32_e32 v69, v69
	v_add_f32_e32 v144, v65, v64
	v_exp_f32_e32 v70, v70
	v_add_f32_e32 v144, v66, v144
	v_exp_f32_e32 v71, v71
	v_add_f32_e32 v144, v67, v144
	v_exp_f32_e32 v72, v72
	v_add_f32_e32 v144, v68, v144
	v_exp_f32_e32 v73, v73
	v_add_f32_e32 v144, v69, v144
	v_exp_f32_e32 v74, v74
	v_add_f32_e32 v144, v70, v144
	v_exp_f32_e32 v75, v75
	v_add_f32_e32 v144, v71, v144
	v_exp_f32_e32 v76, v76
	v_add_f32_e32 v144, v72, v144
	v_exp_f32_e32 v77, v77
	v_add_f32_e32 v144, v73, v144
	v_exp_f32_e32 v78, v78
	v_add_f32_e32 v144, v74, v144
	v_exp_f32_e32 v79, v79
	v_add_f32_e32 v144, v75, v144
	v_add_f32_e32 v144, v76, v144
	v_add_f32_e32 v144, v77, v144
	v_add_f32_e32 v144, v78, v144
	v_add_f32_e32 v144, v79, v144
	v_add_f32_e32 v144, v145, v144
	v_cvt_pk_bf16_f32 v64, v64, v65
	v_cvt_pk_bf16_f32 v65, v66, v67
	v_cvt_pk_bf16_f32 v66, v68, v69
	v_cvt_pk_bf16_f32 v67, v70, v71
	v_cvt_pk_bf16_f32 v68, v72, v73
	v_cvt_pk_bf16_f32 v69, v74, v75
	v_cvt_pk_bf16_f32 v70, v76, v77
	v_cvt_pk_bf16_f32 v71, v78, v79
	s_nop 0
	v_permlane32_swap_b32_e32 v64, v66
	v_permlane32_swap_b32_e32 v65, v67
	v_permlane32_swap_b32_e32 v68, v70
	v_permlane32_swap_b32_e32 v69, v71
	s_waitcnt lgkmcnt(0)
	ds_read_b128 v[218:221], v167 offset:49152
	ds_read_b128 v[222:225], v168 offset:49152
	ds_read_b128 v[226:229], v169 offset:49152
	ds_read_b128 v[230:233], v170 offset:49152
	ds_read_b128 v[234:237], v171 offset:49152
	ds_read_b128 v[238:241], v172 offset:49152
	s_setprio 1
	s_cmp_lt_u32 s33, 0x100
	s_cbranch_scc1 .Lstg_mla_m61_5
	s_waitcnt vmcnt(0)
	s_barrier

.Lstg_mla_t62_6:
	s_setprio 0
	ds_read_b128 v[132:135], v161 offset:61440
	ds_read_b128 v[136:139], v162 offset:61440
	ds_read_b128 v[140:143], v163 offset:61440
	ds_read_b128 v[174:177], v164 offset:61440
	ds_read_b128 v[162:165], v165 offset:61440
	ds_read_b128 v[178:181], v166 offset:61440
	v_add_u32_e32 v145, 0x8000, v130
	ds_read_b64_tr_b16 v[182:183], v145 offset:0
	ds_read_b64_tr_b16 v[184:185], v145 offset:0x800
	ds_read_b64_tr_b16 v[186:187], v145 offset:0x1000
	ds_read_b64_tr_b16 v[188:189], v145 offset:0x1800
	ds_read_b64_tr_b16 v[190:191], v145 offset:0x200
	ds_read_b64_tr_b16 v[192:193], v145 offset:0xa00
	ds_read_b64_tr_b16 v[194:195], v145 offset:0x1200
	ds_read_b64_tr_b16 v[196:197], v145 offset:0x1a00
	s_setprio 2
	ds_read_b64_tr_b16 v[198:199], v145 offset:0x400
	ds_read_b64_tr_b16 v[200:201], v145 offset:0xc00
	ds_read_b64_tr_b16 v[202:203], v145 offset:0x1400
	ds_read_b64_tr_b16 v[204:205], v145 offset:0x1c00
	ds_read_b64_tr_b16 v[206:207], v145 offset:0x600
	ds_read_b64_tr_b16 v[208:209], v145 offset:0xe00
	ds_read_b64_tr_b16 v[210:211], v145 offset:0x1600
	ds_read_b64_tr_b16 v[212:213], v145 offset:0x1e00
	s_nop 3
	v_exp_f32_e32 v64, v64
	v_exp_f32_e32 v65, v65
	v_exp_f32_e32 v66, v66
	v_exp_f32_e32 v67, v67
	v_exp_f32_e32 v68, v68
	v_exp_f32_e32 v69, v69
	v_add_f32_e32 v161, v65, v64
	v_exp_f32_e32 v70, v70
	v_add_f32_e32 v161, v66, v161
	v_exp_f32_e32 v71, v71
	v_add_f32_e32 v161, v67, v161
	v_exp_f32_e32 v72, v72
	v_add_f32_e32 v161, v68, v161
	v_exp_f32_e32 v73, v73
	v_add_f32_e32 v161, v69, v161
	v_exp_f32_e32 v74, v74
	v_add_f32_e32 v161, v70, v161
	v_exp_f32_e32 v75, v75
	v_add_f32_e32 v161, v71, v161
	v_exp_f32_e32 v76, v76
	v_add_f32_e32 v161, v72, v161
	v_exp_f32_e32 v77, v77
	v_add_f32_e32 v161, v73, v161
	v_exp_f32_e32 v78, v78
	v_add_f32_e32 v161, v74, v161
	v_exp_f32_e32 v79, v79
	v_add_f32_e32 v161, v75, v161
	v_add_f32_e32 v161, v76, v161
	v_add_f32_e32 v161, v77, v161
	v_add_f32_e32 v161, v78, v161
	v_add_f32_e32 v161, v79, v161
	v_add_f32_e32 v144, v144, v161
	v_cvt_pk_bf16_f32 v64, v64, v65
	v_cvt_pk_bf16_f32 v65, v66, v67
	v_cvt_pk_bf16_f32 v66, v68, v69
	v_cvt_pk_bf16_f32 v67, v70, v71
	v_cvt_pk_bf16_f32 v68, v72, v73
	v_cvt_pk_bf16_f32 v69, v74, v75
	v_cvt_pk_bf16_f32 v70, v76, v77
	v_cvt_pk_bf16_f32 v71, v78, v79
	s_nop 0
	v_permlane32_swap_b32_e32 v64, v66
	v_permlane32_swap_b32_e32 v65, v67
	v_permlane32_swap_b32_e32 v68, v70
	v_permlane32_swap_b32_e32 v69, v71
	s_waitcnt lgkmcnt(0)
	ds_read_b128 v[214:217], v167 offset:61440
	ds_read_b128 v[218:221], v168 offset:61440
	ds_read_b128 v[166:169], v169 offset:61440
	ds_read_b128 v[222:225], v170 offset:61440
	ds_read_b128 v[226:229], v171 offset:61440
	ds_read_b128 v[170:173], v172 offset:61440
	s_setprio 1
	v_mfma_f32_32x32x16_bf16 v[48:63], v[64:67], v[182:185], v[48:63]
	v_mfma_f32_32x32x16_bf16 v[32:47], v[64:67], v[190:193], v[32:47]
	v_mfma_f32_32x32x16_bf16 v[16:31], v[64:67], v[198:201], v[16:31]
	v_mfma_f32_32x32x16_bf16 v[0:15], v[64:67], v[206:209], v[0:15]
	v_mfma_f32_32x32x16_bf16 v[48:63], v[68:71], v[186:189], v[48:63]
	v_mfma_f32_32x32x16_bf16 v[32:47], v[68:71], v[194:197], v[32:47]
	v_mfma_f32_32x32x16_bf16 v[16:31], v[68:71], v[202:205], v[16:31]
	v_mfma_f32_32x32x16_bf16 v[0:15], v[68:71], v[210:213], v[0:15]
	s_waitcnt lgkmcnt(0)
	v_mfma_f32_32x32x16_bf16 v[64:79], v[132:135], v[80:83], 0
	v_mfma_f32_32x32x16_bf16 v[64:79], v[136:139], v[84:87], v[64:79]
	v_mfma_f32_32x32x16_bf16 v[64:79], v[140:143], v[88:91], v[64:79]
	v_mfma_f32_32x32x16_bf16 v[64:79], v[174:177], v[92:95], v[64:79]
	v_mfma_f32_32x32x16_bf16 v[64:79], v[162:165], v[96:99], v[64:79]
	v_mfma_f32_32x32x16_bf16 v[64:79], v[178:181], v[100:103], v[64:79]
	s_waitcnt lgkmcnt(0)
	v_mfma_f32_32x32x16_bf16 v[64:79], v[214:217], v[104:107], v[64:79]
	v_mfma_f32_32x32x16_bf16 v[64:79], v[218:221], v[108:111], v[64:79]
	v_mfma_f32_32x32x16_bf16 v[64:79], v[166:169], v[112:115], v[64:79]
	v_mfma_f32_32x32x16_bf16 v[64:79], v[222:225], v[116:119], v[64:79]
	v_mfma_f32_32x32x16_bf16 v[64:79], v[226:229], v[120:123], v[64:79]
	v_mfma_f32_32x32x16_bf16 v[64:79], v[170:173], v[124:127], v[64:79]
	s_setprio 0
	v_add_u32_e32 v158, 0x12000, v158
	v_add_u32_e32 v132, v158, v151
	v_add_u32_e32 v136, v158, v149
	v_add_u32_e32 v140, v158, v148
	v_add_u32_e32 v161, v158, v147
	ds_read_b128 v[132:135], v132
	ds_read_b128 v[136:139], v136
	ds_read_b128 v[140:143], v140
	ds_read_b128 v[162:165], v161
	v_add_u32_e32 v161, v158, v146
	v_add_u32_e32 v170, v158, v150
	ds_read_b128 v[166:169], v161
	ds_read_b128 v[170:173], v170
	ds_read_b64_tr_b16 v[174:175], v145 offset:0x2000
	ds_read_b64_tr_b16 v[176:177], v145 offset:0x2800
	ds_read_b64_tr_b16 v[178:179], v145 offset:0x3000
	ds_read_b64_tr_b16 v[180:181], v145 offset:0x3800
	ds_read_b64_tr_b16 v[182:183], v145 offset:0x2200
	ds_read_b64_tr_b16 v[184:185], v145 offset:0x2a00
	ds_read_b64_tr_b16 v[186:187], v145 offset:0x3200
	ds_read_b64_tr_b16 v[188:189], v145 offset:0x3a00
	s_setprio 2
	ds_read_b64_tr_b16 v[190:191], v145 offset:0x2400
	ds_read_b64_tr_b16 v[192:193], v145 offset:0x2c00
	ds_read_b64_tr_b16 v[194:195], v145 offset:0x3400
	ds_read_b64_tr_b16 v[196:197], v145 offset:0x3c00
	ds_read_b64_tr_b16 v[198:199], v145 offset:0x2600
	ds_read_b64_tr_b16 v[200:201], v145 offset:0x2e00
	ds_read_b64_tr_b16 v[202:203], v145 offset:0x3600
	ds_read_b64_tr_b16 v[204:205], v145 offset:0x3e00
	v_exp_f32_e32 v64, v64
	v_exp_f32_e32 v65, v65
	v_exp_f32_e32 v66, v66
	v_exp_f32_e32 v67, v67
	v_exp_f32_e32 v68, v68
	v_exp_f32_e32 v69, v69
	v_add_f32_e32 v145, v65, v64
	v_exp_f32_e32 v70, v70
	v_add_f32_e32 v145, v66, v145
	v_exp_f32_e32 v71, v71
	v_add_f32_e32 v145, v67, v145
	v_exp_f32_e32 v72, v72
	v_add_f32_e32 v145, v68, v145
	v_exp_f32_e32 v73, v73
	v_add_f32_e32 v145, v69, v145
	v_exp_f32_e32 v74, v74
	v_add_f32_e32 v145, v70, v145
	v_exp_f32_e32 v75, v75
	v_add_f32_e32 v145, v71, v145
	v_exp_f32_e32 v76, v76
	v_add_f32_e32 v145, v72, v145
	v_exp_f32_e32 v77, v77
	v_add_f32_e32 v145, v73, v145
	v_exp_f32_e32 v78, v78
	v_add_f32_e32 v145, v74, v145
	v_exp_f32_e32 v79, v79
	v_add_f32_e32 v145, v75, v145
	v_add_f32_e32 v145, v76, v145
	v_add_f32_e32 v145, v77, v145
	v_add_f32_e32 v145, v78, v145
	v_add_f32_e32 v145, v79, v145
	v_add_f32_e32 v161, v144, v145
	v_cvt_pk_bf16_f32 v64, v64, v65
	v_cvt_pk_bf16_f32 v65, v66, v67
	v_cvt_pk_bf16_f32 v66, v68, v69
	v_cvt_pk_bf16_f32 v67, v70, v71
	v_cvt_pk_bf16_f32 v68, v72, v73
	v_cvt_pk_bf16_f32 v69, v74, v75
	v_cvt_pk_bf16_f32 v70, v76, v77
	v_cvt_pk_bf16_f32 v71, v78, v79
	s_nop 0
	v_permlane32_swap_b32_e32 v64, v66
	v_permlane32_swap_b32_e32 v65, v67
	v_permlane32_swap_b32_e32 v68, v70
	v_permlane32_swap_b32_e32 v69, v71
	s_waitcnt lgkmcnt(0)
	v_add_u32_e32 v72, v158, v152
	v_add_u32_e32 v73, v158, v153
	ds_read_b128 v[206:209], v72
	ds_read_b128 v[210:213], v73
	v_add_u32_e32 v72, v158, v154
	v_add_u32_e32 v73, v158, v155
	ds_read_b128 v[214:217], v72
	ds_read_b128 v[218:221], v73
	v_add_u32_e32 v72, v158, v156
	v_add_u32_e32 v73, v158, v157
	ds_read_b128 v[222:225], v72
	ds_read_b128 v[226:229], v73
	s_setprio 1
	s_cmp_lt_u32 s33, 0x100
	s_cbranch_scc1 .Lstg_mla_m62_7
	s_waitcnt vmcnt(0)
	s_barrier

.Lstg_mla_t63_8:
	s_setprio 0
	v_add_u32_e32 v158, s82, v159
	v_add_u32_e32 v132, v158, v151
	v_add_u32_e32 v136, v158, v149
	v_add_u32_e32 v140, v158, v148
	v_add_u32_e32 v144, v158, v147
	ds_read_b128 v[132:135], v132
	ds_read_b128 v[136:139], v136
	ds_read_b128 v[140:143], v140
	ds_read_b128 v[162:165], v144
	v_add_u32_e32 v144, v158, v146
	v_add_u32_e32 v148, v158, v150
	ds_read_b128 v[144:147], v144
	ds_read_b128 v[148:151], v148
	ds_read_b64_tr_b16 v[166:167], v130 offset:0
	ds_read_b64_tr_b16 v[168:169], v130 offset:0x800
	ds_read_b64_tr_b16 v[170:171], v130 offset:0x1000
	ds_read_b64_tr_b16 v[172:173], v130 offset:0x1800
	ds_read_b64_tr_b16 v[174:175], v130 offset:0x200
	ds_read_b64_tr_b16 v[176:177], v130 offset:0xa00
	ds_read_b64_tr_b16 v[178:179], v130 offset:0x1200
	ds_read_b64_tr_b16 v[180:181], v130 offset:0x1a00
	s_setprio 2
	ds_read_b64_tr_b16 v[182:183], v130 offset:0x400
	ds_read_b64_tr_b16 v[184:185], v130 offset:0xc00
	ds_read_b64_tr_b16 v[186:187], v130 offset:0x1400
	ds_read_b64_tr_b16 v[188:189], v130 offset:0x1c00
	ds_read_b64_tr_b16 v[190:191], v130 offset:0x600
	ds_read_b64_tr_b16 v[192:193], v130 offset:0xe00
	ds_read_b64_tr_b16 v[194:195], v130 offset:0x1600
	ds_read_b64_tr_b16 v[196:197], v130 offset:0x1e00
	v_exp_f32_e32 v64, v64
	v_exp_f32_e32 v65, v65
	v_exp_f32_e32 v66, v66
	v_exp_f32_e32 v67, v67
	v_exp_f32_e32 v68, v68
	v_exp_f32_e32 v69, v69
	v_add_f32_e32 v159, v65, v64
	v_exp_f32_e32 v70, v70
	v_add_f32_e32 v159, v66, v159
	v_exp_f32_e32 v71, v71
	v_add_f32_e32 v159, v67, v159
	v_exp_f32_e32 v72, v72
	v_add_f32_e32 v159, v68, v159
	v_exp_f32_e32 v73, v73
	v_add_f32_e32 v159, v69, v159
	v_exp_f32_e32 v74, v74
	v_add_f32_e32 v159, v70, v159
	v_exp_f32_e32 v75, v75
	v_add_f32_e32 v159, v71, v159
	v_exp_f32_e32 v76, v76
	v_add_f32_e32 v159, v72, v159
	v_exp_f32_e32 v77, v77
	v_add_f32_e32 v159, v73, v159
	v_exp_f32_e32 v78, v78
	v_add_f32_e32 v159, v74, v159
	v_exp_f32_e32 v79, v79
	v_add_f32_e32 v159, v75, v159
	v_add_f32_e32 v159, v76, v159
	v_add_f32_e32 v159, v77, v159
	v_add_f32_e32 v159, v78, v159
	v_add_f32_e32 v159, v79, v159
	v_add_f32_e32 v161, v161, v159
	v_cvt_pk_bf16_f32 v64, v64, v65
	v_cvt_pk_bf16_f32 v65, v66, v67
	v_cvt_pk_bf16_f32 v66, v68, v69
	v_cvt_pk_bf16_f32 v67, v70, v71
	v_cvt_pk_bf16_f32 v68, v72, v73
	v_cvt_pk_bf16_f32 v69, v74, v75
	v_cvt_pk_bf16_f32 v70, v76, v77
	v_cvt_pk_bf16_f32 v71, v78, v79
	s_nop 0
	v_permlane32_swap_b32_e32 v64, v66
	v_permlane32_swap_b32_e32 v65, v67
	v_permlane32_swap_b32_e32 v68, v70
	v_permlane32_swap_b32_e32 v69, v71
	s_waitcnt lgkmcnt(0)
	v_add_u32_e32 v72, v158, v152
	v_add_u32_e32 v73, v158, v153
	ds_read_b128 v[198:201], v72
	ds_read_b128 v[202:205], v73
	v_add_u32_e32 v72, v158, v154
	v_add_u32_e32 v73, v158, v155
	ds_read_b128 v[152:155], v72
	ds_read_b128 v[206:209], v73
	v_add_u32_e32 v72, v158, v156
	v_add_u32_e32 v73, v158, v157
	ds_read_b128 v[156:159], v72
	ds_read_b128 v[210:213], v73
	s_setprio 1
	v_mfma_f32_32x32x16_bf16 v[48:63], v[64:67], v[166:169], v[48:63]
	v_mfma_f32_32x32x16_bf16 v[32:47], v[64:67], v[174:177], v[32:47]
	v_mfma_f32_32x32x16_bf16 v[16:31], v[64:67], v[182:185], v[16:31]
	v_mfma_f32_32x32x16_bf16 v[0:15], v[64:67], v[190:193], v[0:15]
	v_mfma_f32_32x32x16_bf16 v[48:63], v[68:71], v[170:173], v[48:63]
	v_mfma_f32_32x32x16_bf16 v[32:47], v[68:71], v[178:181], v[32:47]
	v_mfma_f32_32x32x16_bf16 v[16:31], v[68:71], v[186:189], v[16:31]
	v_mfma_f32_32x32x16_bf16 v[0:15], v[68:71], v[194:197], v[0:15]
	s_waitcnt lgkmcnt(0)
; template <int TAG = 0> DI int fresh_tid(int wv) { int l; asm volatile("v_mbcnt_lo_u32_b32 %0, -1, 0\n\tv_mbcnt_hi_u32_b32 %0, -1, %0 ; site %1" : "=v"(l) : "n"(TAG)); return wv * 64 + l; }
; DI float swap_sum(float v) { auto rr = __builtin_amdgcn_permlane32_swap(__float_as_uint(v), __float_as_uint(v), false, false); return __uint_as_float(rr[0]) + __uint_as_float(rr[1]); }
; template <int DQK, int MODE, int LDQ, int LDK, int LDV> ...
;     ...
;     l_reg = swap_sum(l_reg);
;     { const int lane2 = fresh_tid<110 + MODE>(wv) & 63, r32 = lane2 & 31, hi = lane2 >> 5;
;     if (hi == 0) li_l[r32] = l_reg;
	v_mfma_f32_32x32x16_bf16 v[64:79], v[132:135], v[80:83], 0
	v_mfma_f32_32x32x16_bf16 v[64:79], v[136:139], v[84:87], v[64:79]
	v_mfma_f32_32x32x16_bf16 v[64:79], v[140:143], v[88:91], v[64:79]
	v_mfma_f32_32x32x16_bf16 v[64:79], v[162:165], v[92:95], v[64:79]
	v_mfma_f32_32x32x16_bf16 v[64:79], v[144:147], v[96:99], v[64:79]
	v_mfma_f32_32x32x16_bf16 v[64:79], v[148:151], v[100:103], v[64:79]
	s_waitcnt lgkmcnt(0)
	v_mfma_f32_32x32x16_bf16 v[64:79], v[198:201], v[104:107], v[64:79]
	v_mfma_f32_32x32x16_bf16 v[64:79], v[202:205], v[108:111], v[64:79]
	v_mfma_f32_32x32x16_bf16 v[64:79], v[152:155], v[112:115], v[64:79]
	v_mfma_f32_32x32x16_bf16 v[64:79], v[206:209], v[116:119], v[64:79]
	v_mfma_f32_32x32x16_bf16 v[64:79], v[156:159], v[120:123], v[64:79]
	v_mfma_f32_32x32x16_bf16 v[64:79], v[210:213], v[124:127], v[64:79]
	s_setprio 0
	ds_read_b64_tr_b16 v[80:81], v130 offset:0x2000
	ds_read_b64_tr_b16 v[82:83], v130 offset:0x2800
	ds_read_b64_tr_b16 v[84:85], v130 offset:0x3000
	ds_read_b64_tr_b16 v[86:87], v130 offset:0x3800
	ds_read_b64_tr_b16 v[88:89], v130 offset:0x2200
	ds_read_b64_tr_b16 v[90:91], v130 offset:0x2a00
	ds_read_b64_tr_b16 v[92:93], v130 offset:0x3200
	ds_read_b64_tr_b16 v[94:95], v130 offset:0x3a00
	s_setprio 2
	ds_read_b64_tr_b16 v[96:97], v130 offset:0x2400
	ds_read_b64_tr_b16 v[98:99], v130 offset:0x2c00
	ds_read_b64_tr_b16 v[100:101], v130 offset:0x3400
	ds_read_b64_tr_b16 v[102:103], v130 offset:0x3c00
	ds_read_b64_tr_b16 v[104:105], v130 offset:0x2600
	ds_read_b64_tr_b16 v[106:107], v130 offset:0x2e00
	ds_read_b64_tr_b16 v[108:109], v130 offset:0x3600
	ds_read_b64_tr_b16 v[110:111], v130 offset:0x3e00
	s_nop 11
	v_exp_f32_e32 v112, v64
	v_exp_f32_e32 v65, v65
	v_exp_f32_e32 v113, v66
	v_exp_f32_e32 v67, v67
	v_exp_f32_e32 v68, v68
	v_exp_f32_e32 v69, v69
	v_add_f32_e32 v64, v65, v112
	v_exp_f32_e32 v70, v70
	v_add_f32_e32 v64, v113, v64
	v_exp_f32_e32 v71, v71
	v_add_f32_e32 v64, v67, v64
	v_exp_f32_e32 v72, v72
	v_add_f32_e32 v64, v68, v64
	v_exp_f32_e32 v73, v73
	v_add_f32_e32 v64, v69, v64
	v_exp_f32_e32 v74, v74
	v_add_f32_e32 v64, v70, v64
	v_exp_f32_e32 v75, v75
	v_add_f32_e32 v64, v71, v64
	v_exp_f32_e32 v76, v76
	v_add_f32_e32 v64, v72, v64
	v_exp_f32_e32 v77, v77
	v_add_f32_e32 v64, v73, v64
	v_exp_f32_e32 v78, v78
	v_add_f32_e32 v64, v74, v64
	v_exp_f32_e32 v79, v79
	v_add_f32_e32 v64, v75, v64
	v_add_f32_e32 v64, v76, v64
	v_add_f32_e32 v64, v77, v64
	v_add_f32_e32 v64, v78, v64
	v_add_f32_e32 v64, v79, v64
	v_add_f32_e32 v64, v161, v64
	v_cvt_pk_bf16_f32 v66, v112, v65
	v_cvt_pk_bf16_f32 v67, v113, v67
	v_cvt_pk_bf16_f32 v68, v68, v69
	v_cvt_pk_bf16_f32 v69, v70, v71
	v_cvt_pk_bf16_f32 v70, v72, v73
	v_cvt_pk_bf16_f32 v71, v74, v75
	v_cvt_pk_bf16_f32 v72, v76, v77
	v_cvt_pk_bf16_f32 v73, v78, v79
	s_nop 0
	v_permlane32_swap_b32_e32 v66, v68
	v_permlane32_swap_b32_e32 v67, v69
	v_permlane32_swap_b32_e32 v70, v72
	v_permlane32_swap_b32_e32 v71, v73
	s_waitcnt lgkmcnt(0)
	s_setprio 1
	v_mfma_f32_32x32x16_bf16 v[48:63], v[66:69], v[80:83], v[48:63]
	v_mfma_f32_32x32x16_bf16 v[32:47], v[66:69], v[88:91], v[32:47]
	v_mfma_f32_32x32x16_bf16 v[16:31], v[66:69], v[96:99], v[16:31]
	v_mfma_f32_32x32x16_bf16 v[0:15], v[66:69], v[104:107], v[0:15]
	v_mfma_f32_32x32x16_bf16 v[48:63], v[70:73], v[84:87], v[48:63]
	v_mfma_f32_32x32x16_bf16 v[32:47], v[70:73], v[92:95], v[32:47]
	v_mfma_f32_32x32x16_bf16 v[16:31], v[70:73], v[100:103], v[16:31]
	v_mfma_f32_32x32x16_bf16 v[0:15], v[70:73], v[108:111], v[0:15]
	s_setprio 0
	v_mbcnt_lo_u32_b32 v66, -1, 0
	v_mbcnt_hi_u32_b32 v66, -1, v66
	v_mov_b32_e32 v67, v64
	v_and_b32_e32 v65, 31, v66
	v_bfe_u32 v66, v66, 5, 1
	v_permlane32_swap_b32_e32 v64, v67
	v_cmp_eq_u32_e32 vcc, 0, v66
	s_and_saveexec_b64 s[2:3], vcc
	s_cbranch_execz .LBB0_1910
	v_lshl_add_u32 v68, v65, 2, s4
	v_add_f32_e32 v64, v64, v67
	ds_write_b32 v68, v64
	s_branch .LBB0_1910
